# rlgk: 28 redundant s_waitcnt lgkmcnt(0) right after K-loop segment barriers deleted (the same wait sits right before the barrier, no LDS op in between)
# speedup vs baseline: 1.0067x; 1.0067x over previous
; #define PG8_STAGE(bufoff, gbase, voff) do { _Pragma("unroll") for (int _i = 0; _i < 2; ++_i) \
;         __builtin_amdgcn_global_load_lds((const unsigned*)((const char*)(gbase) + (voff)[_i]), (PG8_LAS unsigned*)(lds + (bufoff) + ldsw + _i * 8192), 16, 0, 0); } while (0)
; #define PG8_STAGEA(bufoff, gbase, voff) do { _Pragma("unroll") for (int _i = 0; _i < 2; ++_i) \
;         __builtin_amdgcn_global_load_lds((const unsigned*)((const char*)(gbase) + (voff)[_i]), (PG8_LAS unsigned*)(lds + (bufoff) + ldsw + _i * 8192), 16, 0, AUXA); } while (0)
; #define PG8_LDA(dst, b, h) do { _Pragma("unroll") for (int m = 0; m < 4; ++m) _Pragma("unroll") for (int k = 0; k < 2; ++k) dst[m][k] = *(const PG8_LAS bf16x8*)(lds + PG8_SA(b, h) + aoff + m * 2048 + k * 1024); } while (0)
; #define PG8_LDB(dst, b, h) do { _Pragma("unroll") for (int n = 0; n < 2; ++n) _Pragma("unroll") for (int k = 0; k < 2; ++k) dst[n][k] = *(const PG8_LAS bf16x8*)(lds + PG8_SB(b, h) + boff + n * 2048 + k * 1024); } while (0)
; #define PG8_MMA(ai, bj, At, Bt) do { __builtin_amdgcn_s_setprio(1); _Pragma("unroll") for (int m = 0; m < 4; ++m) _Pragma("unroll") for (int n = 0; n < 2; ++n) _Pragma("unroll") for (int k = 0; k < 2; ++k) \
;         acc[ai][bj][m][n] = __builtin_amdgcn_mfma_f32_16x16x32_bf16(Bt[n][k], At[m][k], acc[ai][bj][m][n], 0, 0, 0); __builtin_amdgcn_s_setprio(0); } while (0)
; #define PG8_WAIT_V(n) asm volatile("s_waitcnt vmcnt(" #n ")" ::: "memory")
; #define PG8_WAIT_L(n) asm volatile("s_waitcnt lgkmcnt(" #n ")" ::: "memory")
; #define PG8_BAR __builtin_amdgcn_s_barrier()
; #define PG8_SCHED __builtin_amdgcn_sched_barrier(0)
;     ...
;             PG8_LDB(B0, 0, 0); PG8_LDB(B1, 0, 1); PG8_SCHED; PG8_LDA(At, 0, 0); PG8_STAGEA(PG8_SA(1, 1), a1 + hstep, voffA);
;             PG8_WAIT_V(8); PG8_WAIT_L(0); PG8_BAR; PG8_MMA(0, 0, At, B0); PG8_MMA(0, 1, At, B1); PG8_BAR; PG8_SCHED;
;             PG8_LDA(At, 0, 1); PG8_STAGE(PG8_SB(0, 0), b2, voffB); PG8_STAGE(PG8_SB(0, 1), b2 + hstepB, voffB); PG8_STAGEA(PG8_SA(0, 0), a2, voffA);
;             PG8_WAIT_V(8); PG8_WAIT_L(0); PG8_BAR; PG8_MMA(1, 0, At, B0); PG8_MMA(1, 1, At, B1); PG8_BAR; PG8_SCHED;
.Lsprio_0:
.LBB0_119:
	ds_read_b128 v[128:131], v229
	ds_read_b128 v[132:135], v229 offset:1024
	ds_read_b128 v[136:139], v229 offset:2048
	ds_read_b128 v[140:143], v229 offset:3072
	ds_read_b128 v[176:179], v230
	ds_read_b128 v[180:183], v230 offset:1024
	ds_read_b128 v[184:187], v230 offset:2048
	ds_read_b128 v[188:191], v230 offset:3072
	s_add_u32 s36, s8, 0xfffc0080
	s_addc_u32 s37, s9, -1
	s_cmp_eq_u32 s78, 12
	s_cselect_b32 s39, s5, s37
	s_cselect_b32 s38, s7, s36
	s_cselect_b32 s37, s27, s59
	s_cselect_b32 s36, s29, s58
	v_lshl_add_u64 v[172:173], s[8:9], 0, v[164:165]
	s_add_i32 m0, s85, 0xc000
	ds_read_b128 v[192:195], v231
	ds_read_b128 v[196:199], v231 offset:1024
	ds_read_b128 v[238:241], v231 offset:2048
	ds_read_b128 v[242:245], v231 offset:3072
	ds_read_b128 v[246:249], v231 offset:4096
	ds_read_b128 v[250:253], v231 offset:5120
	ds_read_b128 v[210:213], v231 offset:6144
	ds_read_b128 v[214:217], v231 offset:7168
	global_load_lds_dwordx4 v[172:173], off
	v_lshl_add_u64 v[172:173], s[8:9], 0, v[166:167]
	s_add_i32 m0, s85, 0xe000
	s_nop 0
	global_load_lds_dwordx4 v[172:173], off
	s_waitcnt vmcnt(8)
	s_waitcnt lgkmcnt(0)
	s_barrier
	v_mfma_f32_16x16x32_bf16 v[76:79], v[128:131], v[192:195], v[76:79]
	v_mfma_f32_16x16x32_bf16 v[72:75], v[136:139], v[192:195], v[72:75]
	v_mfma_f32_16x16x32_bf16 v[124:127], v[128:131], v[238:241], v[124:127]
	v_mfma_f32_16x16x32_bf16 v[120:123], v[136:139], v[238:241], v[120:123]
	v_mfma_f32_16x16x32_bf16 v[108:111], v[128:131], v[246:249], v[108:111]
	v_mfma_f32_16x16x32_bf16 v[104:107], v[136:139], v[246:249], v[104:107]
	v_mfma_f32_16x16x32_bf16 v[92:95], v[128:131], v[210:213], v[92:95]
	v_mfma_f32_16x16x32_bf16 v[88:91], v[136:139], v[210:213], v[88:91]
	v_mfma_f32_16x16x32_bf16 v[76:79], v[132:135], v[196:199], v[76:79]
	v_mfma_f32_16x16x32_bf16 v[72:75], v[140:143], v[196:199], v[72:75]
	v_mfma_f32_16x16x32_bf16 v[124:127], v[132:135], v[242:245], v[124:127]
	v_mfma_f32_16x16x32_bf16 v[120:123], v[140:143], v[242:245], v[120:123]
	v_mfma_f32_16x16x32_bf16 v[108:111], v[132:135], v[250:253], v[108:111]
	v_mfma_f32_16x16x32_bf16 v[104:107], v[140:143], v[250:253], v[104:107]
	v_mfma_f32_16x16x32_bf16 v[92:95], v[132:135], v[214:217], v[92:95]
	v_mfma_f32_16x16x32_bf16 v[88:91], v[140:143], v[214:217], v[88:91]
	v_mfma_f32_16x16x32_bf16 v[52:55], v[176:179], v[192:195], v[52:55]
	v_mfma_f32_16x16x32_bf16 v[48:51], v[184:187], v[192:195], v[48:51]
	v_mfma_f32_16x16x32_bf16 v[116:119], v[176:179], v[238:241], v[116:119]
	v_mfma_f32_16x16x32_bf16 v[112:115], v[184:187], v[238:241], v[112:115]
	v_mfma_f32_16x16x32_bf16 v[100:103], v[176:179], v[246:249], v[100:103]
	v_mfma_f32_16x16x32_bf16 v[96:99], v[184:187], v[246:249], v[96:99]
	v_mfma_f32_16x16x32_bf16 v[84:87], v[176:179], v[210:213], v[84:87]
	v_mfma_f32_16x16x32_bf16 v[80:83], v[184:187], v[210:213], v[80:83]
	v_mfma_f32_16x16x32_bf16 v[52:55], v[180:183], v[196:199], v[52:55]
	v_mfma_f32_16x16x32_bf16 v[48:51], v[188:191], v[196:199], v[48:51]
	v_mfma_f32_16x16x32_bf16 v[116:119], v[180:183], v[242:245], v[116:119]
	v_mfma_f32_16x16x32_bf16 v[112:115], v[188:191], v[242:245], v[112:115]
	v_mfma_f32_16x16x32_bf16 v[100:103], v[180:183], v[250:253], v[100:103]
	v_mfma_f32_16x16x32_bf16 v[96:99], v[188:191], v[250:253], v[96:99]
	v_mfma_f32_16x16x32_bf16 v[84:87], v[180:183], v[214:217], v[84:87]
	v_mfma_f32_16x16x32_bf16 v[80:83], v[188:191], v[214:217], v[80:83]
	s_barrier
	s_add_i32 s79, s73, s67
	v_lshl_add_u64 v[172:173], s[36:37], 0, v[146:147]
	s_mov_b32 m0, s79
	ds_read_b128 v[192:195], v231 offset:16384
	ds_read_b128 v[196:199], v231 offset:17408
	ds_read_b128 v[210:213], v231 offset:18432
	ds_read_b128 v[214:217], v231 offset:19456
	ds_read_b128 v[238:241], v231 offset:20480
	ds_read_b128 v[242:245], v231 offset:21504
	ds_read_b128 v[246:249], v231 offset:22528
	ds_read_b128 v[250:253], v231 offset:23552
	global_load_lds_dwordx4 v[172:173], off
	s_add_i32 m0, s79, 0x2000
	s_add_u32 s80, s36, 0x10000
	v_lshl_add_u64 v[202:203], s[36:37], 0, v[150:151]
	s_addc_u32 s81, s37, 0
	s_add_i32 s79, s46, s67
	global_load_lds_dwordx4 v[202:203], off
	v_lshl_add_u64 v[204:205], s[80:81], 0, v[146:147]
	s_mov_b32 m0, s79
	v_lshl_add_u64 v[206:207], s[38:39], 0, v[148:149]
	global_load_lds_dwordx4 v[204:205], off
	v_lshl_add_u64 v[204:205], s[80:81], 0, v[150:151]
	s_add_i32 m0, s79, 0x2000
	s_nop 0
	global_load_lds_dwordx4 v[204:205], off
	v_lshl_add_u64 v[204:205], s[38:39], 0, v[144:145]
	s_mov_b32 m0, s85
	s_nop 0
	global_load_lds_dwordx4 v[204:205], off
	s_mov_b32 m0, s86
	s_nop 0
	global_load_lds_dwordx4 v[206:207], off
	s_waitcnt vmcnt(8)
	s_waitcnt lgkmcnt(0)
	s_barrier
; #define PG8_STAGEA(bufoff, gbase, voff) do { _Pragma("unroll") for (int _i = 0; _i < 2; ++_i) \
;         __builtin_amdgcn_global_load_lds((const unsigned*)((const char*)(gbase) + (voff)[_i]), (PG8_LAS unsigned*)(lds + (bufoff) + ldsw + _i * 8192), 16, 0, AUXA); } while (0)
; #define PG8_LDA(dst, b, h) do { _Pragma("unroll") for (int m = 0; m < 4; ++m) _Pragma("unroll") for (int k = 0; k < 2; ++k) dst[m][k] = *(const PG8_LAS bf16x8*)(lds + PG8_SA(b, h) + aoff + m * 2048 + k * 1024); } while (0)
; #define PG8_LDB(dst, b, h) do { _Pragma("unroll") for (int n = 0; n < 2; ++n) _Pragma("unroll") for (int k = 0; k < 2; ++k) dst[n][k] = *(const PG8_LAS bf16x8*)(lds + PG8_SB(b, h) + boff + n * 2048 + k * 1024); } while (0)
; #define PG8_MMA(ai, bj, At, Bt) do { __builtin_amdgcn_s_setprio(1); _Pragma("unroll") for (int m = 0; m < 4; ++m) _Pragma("unroll") for (int n = 0; n < 2; ++n) _Pragma("unroll") for (int k = 0; k < 2; ++k) \
;         acc[ai][bj][m][n] = __builtin_amdgcn_mfma_f32_16x16x32_bf16(Bt[n][k], At[m][k], acc[ai][bj][m][n], 0, 0, 0); __builtin_amdgcn_s_setprio(0); } while (0)
; #define PG8_WAIT_V(n) asm volatile("s_waitcnt vmcnt(" #n ")" ::: "memory")
; #define PG8_WAIT_L(n) asm volatile("s_waitcnt lgkmcnt(" #n ")" ::: "memory")
; #define PG8_BAR __builtin_amdgcn_s_barrier()
; #define PG8_SCHED __builtin_amdgcn_sched_barrier(0)
;     ...
;             PG8_WAIT_V(8); PG8_WAIT_L(0); PG8_BAR; PG8_MMA(1, 0, At, B0); PG8_MMA(1, 1, At, B1); PG8_BAR; PG8_SCHED;
;             PG8_LDB(B0, 1, 0); PG8_LDB(B1, 1, 1); PG8_SCHED; PG8_LDA(At, 1, 0); PG8_STAGEA(PG8_SA(0, 1), a2 + hstep, voffA);
;             PG8_WAIT_V(8); PG8_WAIT_L(0); PG8_BAR; PG8_MMA(0, 0, At, B0); PG8_MMA(0, 1, At, B1); PG8_BAR; PG8_SCHED;
	v_mfma_f32_16x16x32_bf16 v[68:71], v[128:131], v[192:195], v[68:71]
	v_mfma_f32_16x16x32_bf16 v[64:67], v[136:139], v[192:195], v[64:67]
	v_mfma_f32_16x16x32_bf16 v[44:47], v[128:131], v[210:213], v[44:47]
	v_mfma_f32_16x16x32_bf16 v[40:43], v[136:139], v[210:213], v[40:43]
	v_mfma_f32_16x16x32_bf16 v[28:31], v[128:131], v[238:241], v[28:31]
	v_mfma_f32_16x16x32_bf16 v[24:27], v[136:139], v[238:241], v[24:27]
	v_mfma_f32_16x16x32_bf16 v[12:15], v[128:131], v[246:249], v[12:15]
	v_mfma_f32_16x16x32_bf16 v[8:11], v[136:139], v[246:249], v[8:11]
	v_mfma_f32_16x16x32_bf16 v[68:71], v[132:135], v[196:199], v[68:71]
	v_mfma_f32_16x16x32_bf16 v[64:67], v[140:143], v[196:199], v[64:67]
	v_mfma_f32_16x16x32_bf16 v[44:47], v[132:135], v[214:217], v[44:47]
	v_mfma_f32_16x16x32_bf16 v[40:43], v[140:143], v[214:217], v[40:43]
	v_mfma_f32_16x16x32_bf16 v[28:31], v[132:135], v[242:245], v[28:31]
	v_mfma_f32_16x16x32_bf16 v[24:27], v[140:143], v[242:245], v[24:27]
	v_mfma_f32_16x16x32_bf16 v[12:15], v[132:135], v[250:253], v[12:15]
	v_mfma_f32_16x16x32_bf16 v[8:11], v[140:143], v[250:253], v[8:11]
	v_mfma_f32_16x16x32_bf16 v[60:63], v[176:179], v[192:195], v[60:63]
	v_mfma_f32_16x16x32_bf16 v[56:59], v[184:187], v[192:195], v[56:59]
	v_mfma_f32_16x16x32_bf16 v[36:39], v[176:179], v[210:213], v[36:39]
	v_mfma_f32_16x16x32_bf16 v[32:35], v[184:187], v[210:213], v[32:35]
	v_mfma_f32_16x16x32_bf16 v[20:23], v[176:179], v[238:241], v[20:23]
	v_mfma_f32_16x16x32_bf16 v[16:19], v[184:187], v[238:241], v[16:19]
	v_mfma_f32_16x16x32_bf16 v[4:7], v[176:179], v[246:249], v[4:7]
	v_mfma_f32_16x16x32_bf16 v[0:3], v[184:187], v[246:249], v[0:3]
	v_mfma_f32_16x16x32_bf16 v[60:63], v[180:183], v[196:199], v[60:63]
	v_mfma_f32_16x16x32_bf16 v[56:59], v[188:191], v[196:199], v[56:59]
	v_mfma_f32_16x16x32_bf16 v[36:39], v[180:183], v[214:217], v[36:39]
	v_mfma_f32_16x16x32_bf16 v[32:35], v[188:191], v[214:217], v[32:35]
	v_mfma_f32_16x16x32_bf16 v[20:23], v[180:183], v[242:245], v[20:23]
	v_mfma_f32_16x16x32_bf16 v[16:19], v[188:191], v[242:245], v[16:19]
	v_mfma_f32_16x16x32_bf16 v[4:7], v[180:183], v[250:253], v[4:7]
	v_mfma_f32_16x16x32_bf16 v[0:3], v[188:191], v[250:253], v[0:3]
	s_barrier
	s_add_i32 s79, 0, 0x18000
	s_add_i32 s80, 0, 0x1c000
	v_add_u32_e32 v140, s79, v226
	v_add_u32_e32 v152, s80, v226
	ds_read_b128 v[128:131], v140
	ds_read_b128 v[132:135], v140 offset:1024
	ds_read_b128 v[136:139], v140 offset:2048
	ds_read_b128 v[140:143], v140 offset:3072
	ds_read_b128 v[176:179], v152
	ds_read_b128 v[180:183], v152 offset:1024
	ds_read_b128 v[184:187], v152 offset:2048
	ds_read_b128 v[188:191], v152 offset:3072
	s_add_u32 s38, s38, 0x40000
	s_addc_u32 s39, s39, 0
	s_mov_b32 m0, s87
	v_lshl_add_u64 v[218:219], s[38:39], 0, v[144:145]
	ds_read_b128 v[192:195], v231 offset:32768
	ds_read_b128 v[196:199], v231 offset:33792
	ds_read_b128 v[210:213], v231 offset:34816
	ds_read_b128 v[214:217], v231 offset:35840
	ds_read_b128 v[238:241], v231 offset:36864
	ds_read_b128 v[242:245], v231 offset:37888
	ds_read_b128 v[246:249], v231 offset:38912
	ds_read_b128 v[250:253], v231 offset:39936
	global_load_lds_dwordx4 v[218:219], off
	v_lshl_add_u64 v[218:219], s[38:39], 0, v[148:149]
	s_mov_b32 m0, s88
	s_nop 0
	global_load_lds_dwordx4 v[218:219], off
	s_waitcnt vmcnt(8)
	s_waitcnt lgkmcnt(0)
	s_barrier
	v_mfma_f32_16x16x32_bf16 v[76:79], v[128:131], v[192:195], v[76:79]
	v_mfma_f32_16x16x32_bf16 v[72:75], v[136:139], v[192:195], v[72:75]
	v_mfma_f32_16x16x32_bf16 v[124:127], v[128:131], v[210:213], v[124:127]
	v_mfma_f32_16x16x32_bf16 v[120:123], v[136:139], v[210:213], v[120:123]
	v_mfma_f32_16x16x32_bf16 v[108:111], v[128:131], v[238:241], v[108:111]
	v_mfma_f32_16x16x32_bf16 v[104:107], v[136:139], v[238:241], v[104:107]
	v_mfma_f32_16x16x32_bf16 v[92:95], v[128:131], v[246:249], v[92:95]
	v_mfma_f32_16x16x32_bf16 v[88:91], v[136:139], v[246:249], v[88:91]
	v_mfma_f32_16x16x32_bf16 v[76:79], v[132:135], v[196:199], v[76:79]
	v_mfma_f32_16x16x32_bf16 v[72:75], v[140:143], v[196:199], v[72:75]
	v_mfma_f32_16x16x32_bf16 v[124:127], v[132:135], v[214:217], v[124:127]
	v_mfma_f32_16x16x32_bf16 v[120:123], v[140:143], v[214:217], v[120:123]
	v_mfma_f32_16x16x32_bf16 v[108:111], v[132:135], v[242:245], v[108:111]
	v_mfma_f32_16x16x32_bf16 v[104:107], v[140:143], v[242:245], v[104:107]
	v_mfma_f32_16x16x32_bf16 v[92:95], v[132:135], v[250:253], v[92:95]
	v_mfma_f32_16x16x32_bf16 v[88:91], v[140:143], v[250:253], v[88:91]
	v_mfma_f32_16x16x32_bf16 v[52:55], v[176:179], v[192:195], v[52:55]
	v_mfma_f32_16x16x32_bf16 v[48:51], v[184:187], v[192:195], v[48:51]
	v_mfma_f32_16x16x32_bf16 v[116:119], v[176:179], v[210:213], v[116:119]
	v_mfma_f32_16x16x32_bf16 v[112:115], v[184:187], v[210:213], v[112:115]
	v_mfma_f32_16x16x32_bf16 v[100:103], v[176:179], v[238:241], v[100:103]
	v_mfma_f32_16x16x32_bf16 v[96:99], v[184:187], v[238:241], v[96:99]
	v_mfma_f32_16x16x32_bf16 v[84:87], v[176:179], v[246:249], v[84:87]
	v_mfma_f32_16x16x32_bf16 v[80:83], v[184:187], v[246:249], v[80:83]
	v_mfma_f32_16x16x32_bf16 v[52:55], v[180:183], v[196:199], v[52:55]
	v_mfma_f32_16x16x32_bf16 v[48:51], v[188:191], v[196:199], v[48:51]
	v_mfma_f32_16x16x32_bf16 v[116:119], v[180:183], v[214:217], v[116:119]
	v_mfma_f32_16x16x32_bf16 v[112:115], v[188:191], v[214:217], v[112:115]
	v_mfma_f32_16x16x32_bf16 v[100:103], v[180:183], v[242:245], v[100:103]
	v_mfma_f32_16x16x32_bf16 v[96:99], v[188:191], v[242:245], v[96:99]
	v_mfma_f32_16x16x32_bf16 v[84:87], v[180:183], v[250:253], v[84:87]
	v_mfma_f32_16x16x32_bf16 v[80:83], v[188:191], v[250:253], v[80:83]
	s_barrier
; #define PG8_STAGE(bufoff, gbase, voff) do { _Pragma("unroll") for (int _i = 0; _i < 2; ++_i) \
;         __builtin_amdgcn_global_load_lds((const unsigned*)((const char*)(gbase) + (voff)[_i]), (PG8_LAS unsigned*)(lds + (bufoff) + ldsw + _i * 8192), 16, 0, 0); } while (0)
; #define PG8_STAGEA(bufoff, gbase, voff) do { _Pragma("unroll") for (int _i = 0; _i < 2; ++_i) \
;         __builtin_amdgcn_global_load_lds((const unsigned*)((const char*)(gbase) + (voff)[_i]), (PG8_LAS unsigned*)(lds + (bufoff) + ldsw + _i * 8192), 16, 0, AUXA); } while (0)
; #define PG8_LDA(dst, b, h) do { _Pragma("unroll") for (int m = 0; m < 4; ++m) _Pragma("unroll") for (int k = 0; k < 2; ++k) dst[m][k] = *(const PG8_LAS bf16x8*)(lds + PG8_SA(b, h) + aoff + m * 2048 + k * 1024); } while (0)
; #define PG8_MMA(ai, bj, At, Bt) do { __builtin_amdgcn_s_setprio(1); _Pragma("unroll") for (int m = 0; m < 4; ++m) _Pragma("unroll") for (int n = 0; n < 2; ++n) _Pragma("unroll") for (int k = 0; k < 2; ++k) \
;         acc[ai][bj][m][n] = __builtin_amdgcn_mfma_f32_16x16x32_bf16(Bt[n][k], At[m][k], acc[ai][bj][m][n], 0, 0, 0); __builtin_amdgcn_s_setprio(0); } while (0)
; #define PG8_WAIT_V(n) asm volatile("s_waitcnt vmcnt(" #n ")" ::: "memory")
; #define PG8_WAIT_L(n) asm volatile("s_waitcnt lgkmcnt(" #n ")" ::: "memory")
; #define PG8_BAR __builtin_amdgcn_s_barrier()
; #define PG8_SCHED __builtin_amdgcn_sched_barrier(0)
;     ...
;             PG8_WAIT_V(8); PG8_WAIT_L(0); PG8_BAR; PG8_MMA(0, 0, At, B0); PG8_MMA(0, 1, At, B1); PG8_BAR; PG8_SCHED;
;             PG8_LDA(At, 1, 1); PG8_STAGE(PG8_SB(1, 0), b3, voffB); PG8_STAGE(PG8_SB(1, 1), b3 + hstepB, voffB); PG8_STAGEA(PG8_SA(1, 0), a3, voffA);
;             PG8_WAIT_V(8); PG8_WAIT_L(0); PG8_BAR; PG8_MMA(1, 0, At, B0); PG8_MMA(1, 1, At, B1); PG8_BAR; PG8_SCHED;
	s_add_i32 s38, s79, s67
	v_lshl_add_u64 v[172:173], v[172:173], 0, s[16:17]
	s_mov_b32 m0, s38
	ds_read_b128 v[192:195], v231 offset:49152
	ds_read_b128 v[196:199], v231 offset:50176
	ds_read_b128 v[210:213], v231 offset:51200
	ds_read_b128 v[214:217], v231 offset:52224
	ds_read_b128 v[238:241], v231 offset:53248
	ds_read_b128 v[242:245], v231 offset:54272
	ds_read_b128 v[246:249], v231 offset:55296
	ds_read_b128 v[250:253], v231 offset:56320
	global_load_lds_dwordx4 v[172:173], off
	s_add_i32 m0, s38, 0x2000
	s_add_u32 s36, s36, 0x10080
	v_lshl_add_u64 v[172:173], v[202:203], 0, s[16:17]
	s_addc_u32 s37, s37, 0
	s_add_i32 s38, s80, s67
	global_load_lds_dwordx4 v[172:173], off
	v_lshl_add_u64 v[172:173], s[36:37], 0, v[146:147]
	s_mov_b32 m0, s38
	s_nop 0
	global_load_lds_dwordx4 v[172:173], off
	v_lshl_add_u64 v[172:173], s[36:37], 0, v[150:151]
	s_add_i32 m0, s38, 0x2000
	s_nop 0
	global_load_lds_dwordx4 v[172:173], off
	v_lshl_add_u64 v[172:173], v[204:205], 0, s[16:17]
	s_mov_b32 m0, s89
	s_nop 0
	global_load_lds_dwordx4 v[172:173], off
	v_lshl_add_u64 v[172:173], v[206:207], 0, s[16:17]
	s_mov_b32 m0, s90
	s_nop 0
	global_load_lds_dwordx4 v[172:173], off
	s_waitcnt vmcnt(8)
	s_waitcnt lgkmcnt(0)
	s_barrier
	v_mfma_f32_16x16x32_bf16 v[68:71], v[128:131], v[192:195], v[68:71]
	v_mfma_f32_16x16x32_bf16 v[64:67], v[136:139], v[192:195], v[64:67]
	v_mfma_f32_16x16x32_bf16 v[44:47], v[128:131], v[210:213], v[44:47]
	v_mfma_f32_16x16x32_bf16 v[40:43], v[136:139], v[210:213], v[40:43]
	v_mfma_f32_16x16x32_bf16 v[28:31], v[128:131], v[238:241], v[28:31]
	v_mfma_f32_16x16x32_bf16 v[24:27], v[136:139], v[238:241], v[24:27]
	v_mfma_f32_16x16x32_bf16 v[12:15], v[128:131], v[246:249], v[12:15]
	v_mfma_f32_16x16x32_bf16 v[8:11], v[136:139], v[246:249], v[8:11]
	v_mfma_f32_16x16x32_bf16 v[68:71], v[132:135], v[196:199], v[68:71]
	v_mfma_f32_16x16x32_bf16 v[64:67], v[140:143], v[196:199], v[64:67]
	v_mfma_f32_16x16x32_bf16 v[44:47], v[132:135], v[214:217], v[44:47]
	v_mfma_f32_16x16x32_bf16 v[40:43], v[140:143], v[214:217], v[40:43]
	v_mfma_f32_16x16x32_bf16 v[28:31], v[132:135], v[242:245], v[28:31]
	v_mfma_f32_16x16x32_bf16 v[24:27], v[140:143], v[242:245], v[24:27]
	v_mfma_f32_16x16x32_bf16 v[12:15], v[132:135], v[250:253], v[12:15]
	v_mfma_f32_16x16x32_bf16 v[8:11], v[140:143], v[250:253], v[8:11]
	v_mfma_f32_16x16x32_bf16 v[60:63], v[176:179], v[192:195], v[60:63]
	v_mfma_f32_16x16x32_bf16 v[56:59], v[184:187], v[192:195], v[56:59]
	v_mfma_f32_16x16x32_bf16 v[36:39], v[176:179], v[210:213], v[36:39]
	v_mfma_f32_16x16x32_bf16 v[32:35], v[184:187], v[210:213], v[32:35]
	v_mfma_f32_16x16x32_bf16 v[20:23], v[176:179], v[238:241], v[20:23]
	v_mfma_f32_16x16x32_bf16 v[16:19], v[184:187], v[238:241], v[16:19]
	v_mfma_f32_16x16x32_bf16 v[4:7], v[176:179], v[246:249], v[4:7]
	v_mfma_f32_16x16x32_bf16 v[0:3], v[184:187], v[246:249], v[0:3]
	v_mfma_f32_16x16x32_bf16 v[60:63], v[180:183], v[196:199], v[60:63]
	v_mfma_f32_16x16x32_bf16 v[56:59], v[188:191], v[196:199], v[56:59]
	v_mfma_f32_16x16x32_bf16 v[36:39], v[180:183], v[214:217], v[36:39]
	v_mfma_f32_16x16x32_bf16 v[32:35], v[188:191], v[214:217], v[32:35]
	v_mfma_f32_16x16x32_bf16 v[20:23], v[180:183], v[242:245], v[20:23]
	v_mfma_f32_16x16x32_bf16 v[16:19], v[188:191], v[242:245], v[16:19]
	v_mfma_f32_16x16x32_bf16 v[4:7], v[180:183], v[250:253], v[4:7]
	v_mfma_f32_16x16x32_bf16 v[0:3], v[188:191], v[250:253], v[0:3]
	s_barrier
	s_add_i32 s78, s78, 2
	s_add_u32 s8, s8, 0x100
	s_addc_u32 s9, s9, 0
	s_add_u32 s58, s58, 0x100
	s_addc_u32 s59, s59, 0
	s_cmp_gt_u32 s78, 13
	s_cbranch_scc0 .LBB0_119
	s_setprio 0
	s_and_b64 vcc, exec, s[18:19]
	s_cbranch_vccz .LBB0_122
	s_barrier

; #define PG8_STAGE(bufoff, gbase, voff) do { _Pragma("unroll") for (int _i = 0; _i < 2; ++_i) \
;         __builtin_amdgcn_global_load_lds((const unsigned*)((const char*)(gbase) + (voff)[_i]), (PG8_LAS unsigned*)(lds + (bufoff) + ldsw + _i * 8192), 16, 0, 0); } while (0)
; #define PG8_STAGEA(bufoff, gbase, voff) do { _Pragma("unroll") for (int _i = 0; _i < 2; ++_i) \
;         __builtin_amdgcn_global_load_lds((const unsigned*)((const char*)(gbase) + (voff)[_i]), (PG8_LAS unsigned*)(lds + (bufoff) + ldsw + _i * 8192), 16, 0, AUXA); } while (0)
; #define PG8_LDA(dst, b, h) do { _Pragma("unroll") for (int m = 0; m < 4; ++m) _Pragma("unroll") for (int k = 0; k < 2; ++k) dst[m][k] = *(const PG8_LAS bf16x8*)(lds + PG8_SA(b, h) + aoff + m * 2048 + k * 1024); } while (0)
; #define PG8_LDB(dst, b, h) do { _Pragma("unroll") for (int n = 0; n < 2; ++n) _Pragma("unroll") for (int k = 0; k < 2; ++k) dst[n][k] = *(const PG8_LAS bf16x8*)(lds + PG8_SB(b, h) + boff + n * 2048 + k * 1024); } while (0)
; #define PG8_MMA(ai, bj, At, Bt) do { __builtin_amdgcn_s_setprio(1); _Pragma("unroll") for (int m = 0; m < 4; ++m) _Pragma("unroll") for (int n = 0; n < 2; ++n) _Pragma("unroll") for (int k = 0; k < 2; ++k) \
;         acc[ai][bj][m][n] = __builtin_amdgcn_mfma_f32_16x16x32_bf16(Bt[n][k], At[m][k], acc[ai][bj][m][n], 0, 0, 0); __builtin_amdgcn_s_setprio(0); } while (0)
; #define PG8_WAIT_V(n) asm volatile("s_waitcnt vmcnt(" #n ")" ::: "memory")
; #define PG8_WAIT_L(n) asm volatile("s_waitcnt lgkmcnt(" #n ")" ::: "memory")
; #define PG8_BAR __builtin_amdgcn_s_barrier()
; #define PG8_SCHED __builtin_amdgcn_sched_barrier(0)
;     ...
;             PG8_LDB(B0, 0, 0); PG8_LDB(B1, 0, 1); PG8_SCHED; PG8_LDA(At, 0, 0); PG8_STAGEA(PG8_SA(1, 1), a1 + hstep, voffA);
;             PG8_WAIT_V(8); PG8_WAIT_L(0); PG8_BAR; PG8_MMA(0, 0, At, B0); PG8_MMA(0, 1, At, B1); PG8_BAR; PG8_SCHED;
;             PG8_LDA(At, 0, 1); PG8_STAGE(PG8_SB(0, 0), b2, voffB); PG8_STAGE(PG8_SB(0, 1), b2 + hstepB, voffB); PG8_STAGEA(PG8_SA(0, 0), a2, voffA);
;             PG8_WAIT_V(8); PG8_WAIT_L(0); PG8_BAR; PG8_MMA(1, 0, At, B0); PG8_MMA(1, 1, At, B1); PG8_BAR; PG8_SCHED;
.Lsprio_1:
.LBB0_444:
	ds_read_b128 v[148:151], v142
	ds_read_b128 v[152:155], v142 offset:1024
	ds_read_b128 v[156:159], v142 offset:2048
	ds_read_b128 v[160:163], v142 offset:3072
	ds_read_b128 v[164:167], v143
	ds_read_b128 v[168:171], v143 offset:1024
	ds_read_b128 v[176:179], v143 offset:2048
	ds_read_b128 v[180:183], v143 offset:3072
	s_add_u32 s14, s12, 0xf25c0080
	s_addc_u32 s15, s13, -1
	s_cmp_lg_u32 s22, 12
	s_cselect_b32 s14, s14, 0
	s_cselect_b32 s15, s15, 0
	s_add_u32 s16, s8, s14
	s_addc_u32 s17, s9, s15
	s_add_u32 s14, s6, s14
	s_addc_u32 s15, s7, s15
	s_mov_b32 m0, s23
	v_lshl_add_u64 v[172:173], v[136:137], 0, s[12:13]
	ds_read_b128 v[184:187], v144
	ds_read_b128 v[188:191], v144 offset:1024
	ds_read_b128 v[192:195], v144 offset:2048
	ds_read_b128 v[196:199], v144 offset:3072
	ds_read_b128 v[202:205], v144 offset:4096
	ds_read_b128 v[210:213], v144 offset:5120
	ds_read_b128 v[214:217], v144 offset:6144
	ds_read_b128 v[218:221], v144 offset:7168
	global_load_lds_dwordx4 v[172:173], off
	v_lshl_add_u64 v[172:173], v[138:139], 0, s[12:13]
	s_mov_b32 m0, s24
	s_nop 0
	global_load_lds_dwordx4 v[172:173], off
	s_waitcnt vmcnt(8)
	s_waitcnt lgkmcnt(0)
	s_barrier
	v_mfma_f32_16x16x32_bf16 v[124:127], v[148:151], v[184:187], v[124:127]
	v_mfma_f32_16x16x32_bf16 v[120:123], v[156:159], v[184:187], v[120:123]
	v_mfma_f32_16x16x32_bf16 v[108:111], v[148:151], v[192:195], v[108:111]
	v_mfma_f32_16x16x32_bf16 v[104:107], v[156:159], v[192:195], v[104:107]
	v_mfma_f32_16x16x32_bf16 v[92:95], v[148:151], v[202:205], v[92:95]
	v_mfma_f32_16x16x32_bf16 v[88:91], v[156:159], v[202:205], v[88:91]
	v_mfma_f32_16x16x32_bf16 v[76:79], v[148:151], v[214:217], v[76:79]
	v_mfma_f32_16x16x32_bf16 v[72:75], v[156:159], v[214:217], v[72:75]
	v_mfma_f32_16x16x32_bf16 v[124:127], v[152:155], v[188:191], v[124:127]
	v_mfma_f32_16x16x32_bf16 v[120:123], v[160:163], v[188:191], v[120:123]
	v_mfma_f32_16x16x32_bf16 v[108:111], v[152:155], v[196:199], v[108:111]
	v_mfma_f32_16x16x32_bf16 v[104:107], v[160:163], v[196:199], v[104:107]
	v_mfma_f32_16x16x32_bf16 v[92:95], v[152:155], v[210:213], v[92:95]
	v_mfma_f32_16x16x32_bf16 v[88:91], v[160:163], v[210:213], v[88:91]
	v_mfma_f32_16x16x32_bf16 v[76:79], v[152:155], v[218:221], v[76:79]
	v_mfma_f32_16x16x32_bf16 v[72:75], v[160:163], v[218:221], v[72:75]
	v_mfma_f32_16x16x32_bf16 v[116:119], v[164:167], v[184:187], v[116:119]
	v_mfma_f32_16x16x32_bf16 v[112:115], v[176:179], v[184:187], v[112:115]
	v_mfma_f32_16x16x32_bf16 v[100:103], v[164:167], v[192:195], v[100:103]
	v_mfma_f32_16x16x32_bf16 v[96:99], v[176:179], v[192:195], v[96:99]
	v_mfma_f32_16x16x32_bf16 v[84:87], v[164:167], v[202:205], v[84:87]
	v_mfma_f32_16x16x32_bf16 v[80:83], v[176:179], v[202:205], v[80:83]
	v_mfma_f32_16x16x32_bf16 v[68:71], v[164:167], v[214:217], v[68:71]
	v_mfma_f32_16x16x32_bf16 v[64:67], v[176:179], v[214:217], v[64:67]
	v_mfma_f32_16x16x32_bf16 v[116:119], v[168:171], v[188:191], v[116:119]
	v_mfma_f32_16x16x32_bf16 v[112:115], v[180:183], v[188:191], v[112:115]
	v_mfma_f32_16x16x32_bf16 v[100:103], v[168:171], v[196:199], v[100:103]
	v_mfma_f32_16x16x32_bf16 v[96:99], v[180:183], v[196:199], v[96:99]
	v_mfma_f32_16x16x32_bf16 v[84:87], v[168:171], v[210:213], v[84:87]
	v_mfma_f32_16x16x32_bf16 v[80:83], v[180:183], v[210:213], v[80:83]
	v_mfma_f32_16x16x32_bf16 v[68:71], v[168:171], v[218:221], v[68:71]
	v_mfma_f32_16x16x32_bf16 v[64:67], v[180:183], v[218:221], v[64:67]
	s_barrier
	s_mov_b32 m0, s25
	v_lshl_add_u64 v[172:173], s[14:15], 0, v[132:133]
	s_add_u32 s36, s14, 0x10000
	ds_read_b128 v[184:187], v144 offset:16384
	ds_read_b128 v[188:191], v144 offset:17408
	ds_read_b128 v[192:195], v144 offset:18432
	ds_read_b128 v[196:199], v144 offset:19456
	ds_read_b128 v[202:205], v144 offset:20480
	ds_read_b128 v[210:213], v144 offset:21504
	ds_read_b128 v[214:217], v144 offset:22528
	ds_read_b128 v[218:221], v144 offset:23552
	global_load_lds_dwordx4 v[172:173], off
	v_lshl_add_u64 v[206:207], s[14:15], 0, v[128:129]
	s_mov_b32 m0, s26
	s_addc_u32 s37, s15, 0
	global_load_lds_dwordx4 v[206:207], off
	v_lshl_add_u64 v[222:223], s[36:37], 0, v[132:133]
	s_mov_b32 m0, s27
	v_lshl_add_u64 v[224:225], s[16:17], 0, v[130:131]
	global_load_lds_dwordx4 v[222:223], off
	v_lshl_add_u64 v[222:223], s[36:37], 0, v[128:129]
	s_mov_b32 m0, s28
	s_nop 0
	global_load_lds_dwordx4 v[222:223], off
	v_lshl_add_u64 v[222:223], s[16:17], 0, v[134:135]
	s_mov_b32 m0, s1
	s_nop 0
	global_load_lds_dwordx4 v[222:223], off
	s_mov_b32 m0, s3
	s_nop 0
	global_load_lds_dwordx4 v[224:225], off
	s_waitcnt vmcnt(8)
	s_waitcnt lgkmcnt(0)
	s_barrier
; #define PG8_STAGEA(bufoff, gbase, voff) do { _Pragma("unroll") for (int _i = 0; _i < 2; ++_i) \
;         __builtin_amdgcn_global_load_lds((const unsigned*)((const char*)(gbase) + (voff)[_i]), (PG8_LAS unsigned*)(lds + (bufoff) + ldsw + _i * 8192), 16, 0, AUXA); } while (0)
; #define PG8_LDA(dst, b, h) do { _Pragma("unroll") for (int m = 0; m < 4; ++m) _Pragma("unroll") for (int k = 0; k < 2; ++k) dst[m][k] = *(const PG8_LAS bf16x8*)(lds + PG8_SA(b, h) + aoff + m * 2048 + k * 1024); } while (0)
; #define PG8_LDB(dst, b, h) do { _Pragma("unroll") for (int n = 0; n < 2; ++n) _Pragma("unroll") for (int k = 0; k < 2; ++k) dst[n][k] = *(const PG8_LAS bf16x8*)(lds + PG8_SB(b, h) + boff + n * 2048 + k * 1024); } while (0)
; #define PG8_MMA(ai, bj, At, Bt) do { __builtin_amdgcn_s_setprio(1); _Pragma("unroll") for (int m = 0; m < 4; ++m) _Pragma("unroll") for (int n = 0; n < 2; ++n) _Pragma("unroll") for (int k = 0; k < 2; ++k) \
;         acc[ai][bj][m][n] = __builtin_amdgcn_mfma_f32_16x16x32_bf16(Bt[n][k], At[m][k], acc[ai][bj][m][n], 0, 0, 0); __builtin_amdgcn_s_setprio(0); } while (0)
; #define PG8_WAIT_V(n) asm volatile("s_waitcnt vmcnt(" #n ")" ::: "memory")
; #define PG8_WAIT_L(n) asm volatile("s_waitcnt lgkmcnt(" #n ")" ::: "memory")
; #define PG8_BAR __builtin_amdgcn_s_barrier()
; #define PG8_SCHED __builtin_amdgcn_sched_barrier(0)
;     ...
;             PG8_WAIT_V(8); PG8_WAIT_L(0); PG8_BAR; PG8_MMA(1, 0, At, B0); PG8_MMA(1, 1, At, B1); PG8_BAR; PG8_SCHED;
;             PG8_LDB(B0, 1, 0); PG8_LDB(B1, 1, 1); PG8_SCHED; PG8_LDA(At, 1, 0); PG8_STAGEA(PG8_SA(0, 1), a2 + hstep, voffA);
;             PG8_WAIT_V(8); PG8_WAIT_L(0); PG8_BAR; PG8_MMA(0, 0, At, B0); PG8_MMA(0, 1, At, B1); PG8_BAR; PG8_SCHED;
	v_mfma_f32_16x16x32_bf16 v[60:63], v[148:151], v[184:187], v[60:63]
	v_mfma_f32_16x16x32_bf16 v[56:59], v[156:159], v[184:187], v[56:59]
	v_mfma_f32_16x16x32_bf16 v[44:47], v[148:151], v[192:195], v[44:47]
	v_mfma_f32_16x16x32_bf16 v[40:43], v[156:159], v[192:195], v[40:43]
	v_mfma_f32_16x16x32_bf16 v[28:31], v[148:151], v[202:205], v[28:31]
	v_mfma_f32_16x16x32_bf16 v[24:27], v[156:159], v[202:205], v[24:27]
	v_mfma_f32_16x16x32_bf16 v[12:15], v[148:151], v[214:217], v[12:15]
	v_mfma_f32_16x16x32_bf16 v[8:11], v[156:159], v[214:217], v[8:11]
	v_mfma_f32_16x16x32_bf16 v[60:63], v[152:155], v[188:191], v[60:63]
	v_mfma_f32_16x16x32_bf16 v[56:59], v[160:163], v[188:191], v[56:59]
	v_mfma_f32_16x16x32_bf16 v[44:47], v[152:155], v[196:199], v[44:47]
	v_mfma_f32_16x16x32_bf16 v[40:43], v[160:163], v[196:199], v[40:43]
	v_mfma_f32_16x16x32_bf16 v[28:31], v[152:155], v[210:213], v[28:31]
	v_mfma_f32_16x16x32_bf16 v[24:27], v[160:163], v[210:213], v[24:27]
	v_mfma_f32_16x16x32_bf16 v[12:15], v[152:155], v[218:221], v[12:15]
	v_mfma_f32_16x16x32_bf16 v[8:11], v[160:163], v[218:221], v[8:11]
	v_mfma_f32_16x16x32_bf16 v[52:55], v[164:167], v[184:187], v[52:55]
	v_mfma_f32_16x16x32_bf16 v[48:51], v[176:179], v[184:187], v[48:51]
	v_mfma_f32_16x16x32_bf16 v[36:39], v[164:167], v[192:195], v[36:39]
	v_mfma_f32_16x16x32_bf16 v[32:35], v[176:179], v[192:195], v[32:35]
	v_mfma_f32_16x16x32_bf16 v[20:23], v[164:167], v[202:205], v[20:23]
	v_mfma_f32_16x16x32_bf16 v[16:19], v[176:179], v[202:205], v[16:19]
	v_mfma_f32_16x16x32_bf16 v[4:7], v[164:167], v[214:217], v[4:7]
	v_mfma_f32_16x16x32_bf16 v[0:3], v[176:179], v[214:217], v[0:3]
	v_mfma_f32_16x16x32_bf16 v[52:55], v[168:171], v[188:191], v[52:55]
	v_mfma_f32_16x16x32_bf16 v[48:51], v[180:183], v[188:191], v[48:51]
	v_mfma_f32_16x16x32_bf16 v[36:39], v[168:171], v[196:199], v[36:39]
	v_mfma_f32_16x16x32_bf16 v[32:35], v[180:183], v[196:199], v[32:35]
	v_mfma_f32_16x16x32_bf16 v[20:23], v[168:171], v[210:213], v[20:23]
	v_mfma_f32_16x16x32_bf16 v[16:19], v[180:183], v[210:213], v[16:19]
	v_mfma_f32_16x16x32_bf16 v[4:7], v[168:171], v[218:221], v[4:7]
	v_mfma_f32_16x16x32_bf16 v[0:3], v[180:183], v[218:221], v[0:3]
	s_barrier
	ds_read_b128 v[148:151], v145
	ds_read_b128 v[152:155], v145 offset:1024
	ds_read_b128 v[156:159], v145 offset:2048
	ds_read_b128 v[160:163], v145 offset:3072
	ds_read_b128 v[164:167], v146
	ds_read_b128 v[168:171], v146 offset:1024
	ds_read_b128 v[176:179], v146 offset:2048
	ds_read_b128 v[180:183], v146 offset:3072
	s_add_u32 s16, s16, 0x40000
	s_addc_u32 s17, s17, 0
	s_mov_b32 m0, s18
	v_lshl_add_u64 v[226:227], s[16:17], 0, v[134:135]
	ds_read_b128 v[184:187], v144 offset:32768
	ds_read_b128 v[188:191], v144 offset:33792
	ds_read_b128 v[192:195], v144 offset:34816
	ds_read_b128 v[196:199], v144 offset:35840
	ds_read_b128 v[202:205], v144 offset:36864
	ds_read_b128 v[210:213], v144 offset:37888
	ds_read_b128 v[214:217], v144 offset:38912
	ds_read_b128 v[218:221], v144 offset:39936
	global_load_lds_dwordx4 v[226:227], off
	v_lshl_add_u64 v[226:227], s[16:17], 0, v[130:131]
	s_mov_b32 m0, s19
	s_nop 0
	global_load_lds_dwordx4 v[226:227], off
	s_waitcnt vmcnt(8)
	s_waitcnt lgkmcnt(0)
	s_barrier
	v_mfma_f32_16x16x32_bf16 v[124:127], v[148:151], v[184:187], v[124:127]
	v_mfma_f32_16x16x32_bf16 v[120:123], v[156:159], v[184:187], v[120:123]
	v_mfma_f32_16x16x32_bf16 v[108:111], v[148:151], v[192:195], v[108:111]
	v_mfma_f32_16x16x32_bf16 v[104:107], v[156:159], v[192:195], v[104:107]
	v_mfma_f32_16x16x32_bf16 v[92:95], v[148:151], v[202:205], v[92:95]
	v_mfma_f32_16x16x32_bf16 v[88:91], v[156:159], v[202:205], v[88:91]
	v_mfma_f32_16x16x32_bf16 v[76:79], v[148:151], v[214:217], v[76:79]
	v_mfma_f32_16x16x32_bf16 v[72:75], v[156:159], v[214:217], v[72:75]
	v_mfma_f32_16x16x32_bf16 v[124:127], v[152:155], v[188:191], v[124:127]
	v_mfma_f32_16x16x32_bf16 v[120:123], v[160:163], v[188:191], v[120:123]
	v_mfma_f32_16x16x32_bf16 v[108:111], v[152:155], v[196:199], v[108:111]
	v_mfma_f32_16x16x32_bf16 v[104:107], v[160:163], v[196:199], v[104:107]
	v_mfma_f32_16x16x32_bf16 v[92:95], v[152:155], v[210:213], v[92:95]
	v_mfma_f32_16x16x32_bf16 v[88:91], v[160:163], v[210:213], v[88:91]
	v_mfma_f32_16x16x32_bf16 v[76:79], v[152:155], v[218:221], v[76:79]
	v_mfma_f32_16x16x32_bf16 v[72:75], v[160:163], v[218:221], v[72:75]
	v_mfma_f32_16x16x32_bf16 v[116:119], v[164:167], v[184:187], v[116:119]
	v_mfma_f32_16x16x32_bf16 v[112:115], v[176:179], v[184:187], v[112:115]
	v_mfma_f32_16x16x32_bf16 v[100:103], v[164:167], v[192:195], v[100:103]
	v_mfma_f32_16x16x32_bf16 v[96:99], v[176:179], v[192:195], v[96:99]
	v_mfma_f32_16x16x32_bf16 v[84:87], v[164:167], v[202:205], v[84:87]
	v_mfma_f32_16x16x32_bf16 v[80:83], v[176:179], v[202:205], v[80:83]
	v_mfma_f32_16x16x32_bf16 v[68:71], v[164:167], v[214:217], v[68:71]
	v_mfma_f32_16x16x32_bf16 v[64:67], v[176:179], v[214:217], v[64:67]
	v_mfma_f32_16x16x32_bf16 v[116:119], v[168:171], v[188:191], v[116:119]
	v_mfma_f32_16x16x32_bf16 v[112:115], v[180:183], v[188:191], v[112:115]
	v_mfma_f32_16x16x32_bf16 v[100:103], v[168:171], v[196:199], v[100:103]
	v_mfma_f32_16x16x32_bf16 v[96:99], v[180:183], v[196:199], v[96:99]
	v_mfma_f32_16x16x32_bf16 v[84:87], v[168:171], v[210:213], v[84:87]
	v_mfma_f32_16x16x32_bf16 v[80:83], v[180:183], v[210:213], v[80:83]
	v_mfma_f32_16x16x32_bf16 v[68:71], v[168:171], v[218:221], v[68:71]
	v_mfma_f32_16x16x32_bf16 v[64:67], v[180:183], v[218:221], v[64:67]
	s_barrier
; #define PG8_STAGE(bufoff, gbase, voff) do { _Pragma("unroll") for (int _i = 0; _i < 2; ++_i) \
;         __builtin_amdgcn_global_load_lds((const unsigned*)((const char*)(gbase) + (voff)[_i]), (PG8_LAS unsigned*)(lds + (bufoff) + ldsw + _i * 8192), 16, 0, 0); } while (0)
; #define PG8_STAGEA(bufoff, gbase, voff) do { _Pragma("unroll") for (int _i = 0; _i < 2; ++_i) \
;         __builtin_amdgcn_global_load_lds((const unsigned*)((const char*)(gbase) + (voff)[_i]), (PG8_LAS unsigned*)(lds + (bufoff) + ldsw + _i * 8192), 16, 0, AUXA); } while (0)
; #define PG8_LDA(dst, b, h) do { _Pragma("unroll") for (int m = 0; m < 4; ++m) _Pragma("unroll") for (int k = 0; k < 2; ++k) dst[m][k] = *(const PG8_LAS bf16x8*)(lds + PG8_SA(b, h) + aoff + m * 2048 + k * 1024); } while (0)
; #define PG8_MMA(ai, bj, At, Bt) do { __builtin_amdgcn_s_setprio(1); _Pragma("unroll") for (int m = 0; m < 4; ++m) _Pragma("unroll") for (int n = 0; n < 2; ++n) _Pragma("unroll") for (int k = 0; k < 2; ++k) \
;         acc[ai][bj][m][n] = __builtin_amdgcn_mfma_f32_16x16x32_bf16(Bt[n][k], At[m][k], acc[ai][bj][m][n], 0, 0, 0); __builtin_amdgcn_s_setprio(0); } while (0)
; #define PG8_WAIT_V(n) asm volatile("s_waitcnt vmcnt(" #n ")" ::: "memory")
; #define PG8_WAIT_L(n) asm volatile("s_waitcnt lgkmcnt(" #n ")" ::: "memory")
; #define PG8_BAR __builtin_amdgcn_s_barrier()
; #define PG8_SCHED __builtin_amdgcn_sched_barrier(0)
;     ...
;             PG8_WAIT_V(8); PG8_WAIT_L(0); PG8_BAR; PG8_MMA(0, 0, At, B0); PG8_MMA(0, 1, At, B1); PG8_BAR; PG8_SCHED;
;             PG8_LDA(At, 1, 1); PG8_STAGE(PG8_SB(1, 0), b3, voffB); PG8_STAGE(PG8_SB(1, 1), b3 + hstepB, voffB); PG8_STAGEA(PG8_SA(1, 0), a3, voffA);
;             PG8_WAIT_V(8); PG8_WAIT_L(0); PG8_BAR; PG8_MMA(1, 0, At, B0); PG8_MMA(1, 1, At, B1); PG8_BAR; PG8_SCHED;
	s_mov_b32 m0, s29
	v_lshl_add_u64 v[172:173], v[172:173], 0, s[10:11]
	s_add_u32 s14, s14, 0x10080
	ds_read_b128 v[184:187], v144 offset:49152
	ds_read_b128 v[188:191], v144 offset:50176
	ds_read_b128 v[192:195], v144 offset:51200
	ds_read_b128 v[196:199], v144 offset:52224
	ds_read_b128 v[202:205], v144 offset:53248
	ds_read_b128 v[210:213], v144 offset:54272
	ds_read_b128 v[214:217], v144 offset:55296
	ds_read_b128 v[218:221], v144 offset:56320
	global_load_lds_dwordx4 v[172:173], off
	v_lshl_add_u64 v[172:173], v[206:207], 0, s[10:11]
	s_mov_b32 m0, s30
	s_addc_u32 s15, s15, 0
	global_load_lds_dwordx4 v[172:173], off
	v_lshl_add_u64 v[172:173], s[14:15], 0, v[132:133]
	s_mov_b32 m0, s31
	s_nop 0
	global_load_lds_dwordx4 v[172:173], off
	v_lshl_add_u64 v[172:173], s[14:15], 0, v[128:129]
	s_mov_b32 m0, s34
	s_nop 0
	global_load_lds_dwordx4 v[172:173], off
	v_lshl_add_u64 v[172:173], v[222:223], 0, s[10:11]
	s_mov_b32 m0, s20
	s_nop 0
	global_load_lds_dwordx4 v[172:173], off
	v_lshl_add_u64 v[172:173], v[224:225], 0, s[10:11]
	s_mov_b32 m0, s21
	s_nop 0
	global_load_lds_dwordx4 v[172:173], off
	s_waitcnt vmcnt(8)
	s_waitcnt lgkmcnt(0)
	s_barrier
	v_mfma_f32_16x16x32_bf16 v[60:63], v[148:151], v[184:187], v[60:63]
	v_mfma_f32_16x16x32_bf16 v[56:59], v[156:159], v[184:187], v[56:59]
	v_mfma_f32_16x16x32_bf16 v[44:47], v[148:151], v[192:195], v[44:47]
	v_mfma_f32_16x16x32_bf16 v[40:43], v[156:159], v[192:195], v[40:43]
	v_mfma_f32_16x16x32_bf16 v[28:31], v[148:151], v[202:205], v[28:31]
	v_mfma_f32_16x16x32_bf16 v[24:27], v[156:159], v[202:205], v[24:27]
	v_mfma_f32_16x16x32_bf16 v[12:15], v[148:151], v[214:217], v[12:15]
	v_mfma_f32_16x16x32_bf16 v[8:11], v[156:159], v[214:217], v[8:11]
	v_mfma_f32_16x16x32_bf16 v[60:63], v[152:155], v[188:191], v[60:63]
	v_mfma_f32_16x16x32_bf16 v[56:59], v[160:163], v[188:191], v[56:59]
	v_mfma_f32_16x16x32_bf16 v[44:47], v[152:155], v[196:199], v[44:47]
	v_mfma_f32_16x16x32_bf16 v[40:43], v[160:163], v[196:199], v[40:43]
	v_mfma_f32_16x16x32_bf16 v[28:31], v[152:155], v[210:213], v[28:31]
	v_mfma_f32_16x16x32_bf16 v[24:27], v[160:163], v[210:213], v[24:27]
	v_mfma_f32_16x16x32_bf16 v[12:15], v[152:155], v[218:221], v[12:15]
	v_mfma_f32_16x16x32_bf16 v[8:11], v[160:163], v[218:221], v[8:11]
	v_mfma_f32_16x16x32_bf16 v[52:55], v[164:167], v[184:187], v[52:55]
	v_mfma_f32_16x16x32_bf16 v[48:51], v[176:179], v[184:187], v[48:51]
	v_mfma_f32_16x16x32_bf16 v[36:39], v[164:167], v[192:195], v[36:39]
	v_mfma_f32_16x16x32_bf16 v[32:35], v[176:179], v[192:195], v[32:35]
	v_mfma_f32_16x16x32_bf16 v[20:23], v[164:167], v[202:205], v[20:23]
	v_mfma_f32_16x16x32_bf16 v[16:19], v[176:179], v[202:205], v[16:19]
	v_mfma_f32_16x16x32_bf16 v[4:7], v[164:167], v[214:217], v[4:7]
	v_mfma_f32_16x16x32_bf16 v[0:3], v[176:179], v[214:217], v[0:3]
	v_mfma_f32_16x16x32_bf16 v[52:55], v[168:171], v[188:191], v[52:55]
	v_mfma_f32_16x16x32_bf16 v[48:51], v[180:183], v[188:191], v[48:51]
	v_mfma_f32_16x16x32_bf16 v[36:39], v[168:171], v[196:199], v[36:39]
	v_mfma_f32_16x16x32_bf16 v[32:35], v[180:183], v[196:199], v[32:35]
	v_mfma_f32_16x16x32_bf16 v[20:23], v[168:171], v[210:213], v[20:23]
	v_mfma_f32_16x16x32_bf16 v[16:19], v[180:183], v[210:213], v[16:19]
	v_mfma_f32_16x16x32_bf16 v[4:7], v[168:171], v[218:221], v[4:7]
	v_mfma_f32_16x16x32_bf16 v[0:3], v[180:183], v[218:221], v[0:3]
	s_barrier
	s_add_i32 s22, s22, 2
	s_add_u32 s12, s12, 0x100
	s_addc_u32 s13, s13, 0
	s_cmp_gt_u32 s22, 13
	s_cbranch_scc0 .LBB0_444
	s_setprio 0
	v_readlane_b32 s1, v255, 10
	s_cmpk_lt_u32 s1, 0x100
	s_cbranch_scc0 .LBB0_447
	s_barrier

; #define PG8_STAGE(bufoff, gbase, voff) do { _Pragma("unroll") for (int _i = 0; _i < 2; ++_i) \
;         __builtin_amdgcn_global_load_lds((const unsigned*)((const char*)(gbase) + (voff)[_i]), (PG8_LAS unsigned*)(lds + (bufoff) + ldsw + _i * 8192), 16, 0, 0); } while (0)
; #define PG8_STAGEA(bufoff, gbase, voff) do { _Pragma("unroll") for (int _i = 0; _i < 2; ++_i) \
;         __builtin_amdgcn_global_load_lds((const unsigned*)((const char*)(gbase) + (voff)[_i]), (PG8_LAS unsigned*)(lds + (bufoff) + ldsw + _i * 8192), 16, 0, AUXA); } while (0)
; #define PG8_LDA(dst, b, h) do { _Pragma("unroll") for (int m = 0; m < 4; ++m) _Pragma("unroll") for (int k = 0; k < 2; ++k) dst[m][k] = *(const PG8_LAS bf16x8*)(lds + PG8_SA(b, h) + aoff + m * 2048 + k * 1024); } while (0)
; #define PG8_LDB(dst, b, h) do { _Pragma("unroll") for (int n = 0; n < 2; ++n) _Pragma("unroll") for (int k = 0; k < 2; ++k) dst[n][k] = *(const PG8_LAS bf16x8*)(lds + PG8_SB(b, h) + boff + n * 2048 + k * 1024); } while (0)
; #define PG8_MMA(ai, bj, At, Bt) do { __builtin_amdgcn_s_setprio(1); _Pragma("unroll") for (int m = 0; m < 4; ++m) _Pragma("unroll") for (int n = 0; n < 2; ++n) _Pragma("unroll") for (int k = 0; k < 2; ++k) \
;         acc[ai][bj][m][n] = __builtin_amdgcn_mfma_f32_16x16x32_bf16(Bt[n][k], At[m][k], acc[ai][bj][m][n], 0, 0, 0); __builtin_amdgcn_s_setprio(0); } while (0)
; #define PG8_WAIT_V(n) asm volatile("s_waitcnt vmcnt(" #n ")" ::: "memory")
; #define PG8_WAIT_L(n) asm volatile("s_waitcnt lgkmcnt(" #n ")" ::: "memory")
; #define PG8_BAR __builtin_amdgcn_s_barrier()
; #define PG8_SCHED __builtin_amdgcn_sched_barrier(0)
;     ...
;             PG8_LDB(B0, 0, 0); PG8_LDB(B1, 0, 1); PG8_SCHED; PG8_LDA(At, 0, 0); PG8_STAGEA(PG8_SA(1, 1), a1 + hstep, voffA);
;             PG8_WAIT_V(8); PG8_WAIT_L(0); PG8_BAR; PG8_MMA(0, 0, At, B0); PG8_MMA(0, 1, At, B1); PG8_BAR; PG8_SCHED;
;             PG8_LDA(At, 0, 1); PG8_STAGE(PG8_SB(0, 0), b2, voffB); PG8_STAGE(PG8_SB(0, 1), b2 + hstepB, voffB); PG8_STAGEA(PG8_SA(0, 0), a2, voffA);
;             PG8_WAIT_V(8); PG8_WAIT_L(0); PG8_BAR; PG8_MMA(1, 0, At, B0); PG8_MMA(1, 1, At, B1); PG8_BAR; PG8_SCHED;
.Lsprio_2:
.LBB0_758:
	ds_read_b128 v[148:151], v142
	ds_read_b128 v[152:155], v142 offset:1024
	ds_read_b128 v[156:159], v142 offset:2048
	ds_read_b128 v[160:163], v142 offset:3072
	ds_read_b128 v[164:167], v143
	ds_read_b128 v[168:171], v143 offset:1024
	ds_read_b128 v[176:179], v143 offset:2048
	ds_read_b128 v[180:183], v143 offset:3072
	s_add_u32 s14, s12, 0xf03c0080
	s_addc_u32 s15, s13, -1
	s_cmp_lg_u32 s22, 12
	s_cselect_b32 s14, s14, 0
	s_cselect_b32 s15, s15, 0
	s_add_u32 s16, s8, s14
	s_addc_u32 s17, s9, s15
	s_add_u32 s14, s6, s14
	s_addc_u32 s15, s7, s15
	s_mov_b32 m0, s23
	v_lshl_add_u64 v[172:173], v[138:139], 0, s[12:13]
	ds_read_b128 v[184:187], v144
	ds_read_b128 v[188:191], v144 offset:1024
	ds_read_b128 v[192:195], v144 offset:2048
	ds_read_b128 v[196:199], v144 offset:3072
	ds_read_b128 v[202:205], v144 offset:4096
	ds_read_b128 v[210:213], v144 offset:5120
	ds_read_b128 v[214:217], v144 offset:6144
	ds_read_b128 v[218:221], v144 offset:7168
	global_load_lds_dwordx4 v[172:173], off
	v_lshl_add_u64 v[172:173], v[140:141], 0, s[12:13]
	s_mov_b32 m0, s24
	s_nop 0
	global_load_lds_dwordx4 v[172:173], off
	s_waitcnt vmcnt(8)
	s_waitcnt lgkmcnt(0)
	s_barrier
	v_mfma_f32_16x16x32_bf16 v[124:127], v[148:151], v[184:187], v[124:127]
	v_mfma_f32_16x16x32_bf16 v[120:123], v[156:159], v[184:187], v[120:123]
	v_mfma_f32_16x16x32_bf16 v[108:111], v[148:151], v[192:195], v[108:111]
	v_mfma_f32_16x16x32_bf16 v[104:107], v[156:159], v[192:195], v[104:107]
	v_mfma_f32_16x16x32_bf16 v[92:95], v[148:151], v[202:205], v[92:95]
	v_mfma_f32_16x16x32_bf16 v[88:91], v[156:159], v[202:205], v[88:91]
	v_mfma_f32_16x16x32_bf16 v[76:79], v[148:151], v[214:217], v[76:79]
	v_mfma_f32_16x16x32_bf16 v[72:75], v[156:159], v[214:217], v[72:75]
	v_mfma_f32_16x16x32_bf16 v[124:127], v[152:155], v[188:191], v[124:127]
	v_mfma_f32_16x16x32_bf16 v[120:123], v[160:163], v[188:191], v[120:123]
	v_mfma_f32_16x16x32_bf16 v[108:111], v[152:155], v[196:199], v[108:111]
	v_mfma_f32_16x16x32_bf16 v[104:107], v[160:163], v[196:199], v[104:107]
	v_mfma_f32_16x16x32_bf16 v[92:95], v[152:155], v[210:213], v[92:95]
	v_mfma_f32_16x16x32_bf16 v[88:91], v[160:163], v[210:213], v[88:91]
	v_mfma_f32_16x16x32_bf16 v[76:79], v[152:155], v[218:221], v[76:79]
	v_mfma_f32_16x16x32_bf16 v[72:75], v[160:163], v[218:221], v[72:75]
	v_mfma_f32_16x16x32_bf16 v[116:119], v[164:167], v[184:187], v[116:119]
	v_mfma_f32_16x16x32_bf16 v[112:115], v[176:179], v[184:187], v[112:115]
	v_mfma_f32_16x16x32_bf16 v[100:103], v[164:167], v[192:195], v[100:103]
	v_mfma_f32_16x16x32_bf16 v[96:99], v[176:179], v[192:195], v[96:99]
	v_mfma_f32_16x16x32_bf16 v[84:87], v[164:167], v[202:205], v[84:87]
	v_mfma_f32_16x16x32_bf16 v[80:83], v[176:179], v[202:205], v[80:83]
	v_mfma_f32_16x16x32_bf16 v[68:71], v[164:167], v[214:217], v[68:71]
	v_mfma_f32_16x16x32_bf16 v[64:67], v[176:179], v[214:217], v[64:67]
	v_mfma_f32_16x16x32_bf16 v[116:119], v[168:171], v[188:191], v[116:119]
	v_mfma_f32_16x16x32_bf16 v[112:115], v[180:183], v[188:191], v[112:115]
	v_mfma_f32_16x16x32_bf16 v[100:103], v[168:171], v[196:199], v[100:103]
	v_mfma_f32_16x16x32_bf16 v[96:99], v[180:183], v[196:199], v[96:99]
	v_mfma_f32_16x16x32_bf16 v[84:87], v[168:171], v[210:213], v[84:87]
	v_mfma_f32_16x16x32_bf16 v[80:83], v[180:183], v[210:213], v[80:83]
	v_mfma_f32_16x16x32_bf16 v[68:71], v[168:171], v[218:221], v[68:71]
	v_mfma_f32_16x16x32_bf16 v[64:67], v[180:183], v[218:221], v[64:67]
	s_barrier
	s_mov_b32 m0, s25
	v_lshl_add_u64 v[172:173], s[14:15], 0, v[134:135]
	s_add_u32 s36, s14, 0x10000
	ds_read_b128 v[184:187], v144 offset:16384
	ds_read_b128 v[188:191], v144 offset:17408
	ds_read_b128 v[192:195], v144 offset:18432
	ds_read_b128 v[196:199], v144 offset:19456
	ds_read_b128 v[202:205], v144 offset:20480
	ds_read_b128 v[210:213], v144 offset:21504
	ds_read_b128 v[214:217], v144 offset:22528
	ds_read_b128 v[218:221], v144 offset:23552
	global_load_lds_dwordx4 v[172:173], off
	v_lshl_add_u64 v[206:207], s[14:15], 0, v[130:131]
	s_mov_b32 m0, s26
	s_addc_u32 s37, s15, 0
	global_load_lds_dwordx4 v[206:207], off
	v_lshl_add_u64 v[222:223], s[36:37], 0, v[134:135]
	s_mov_b32 m0, s27
	v_lshl_add_u64 v[224:225], s[16:17], 0, v[132:133]
	global_load_lds_dwordx4 v[222:223], off
	v_lshl_add_u64 v[222:223], s[36:37], 0, v[130:131]
	s_mov_b32 m0, s28
	s_nop 0
	global_load_lds_dwordx4 v[222:223], off
	v_lshl_add_u64 v[222:223], s[16:17], 0, v[136:137]
	s_mov_b32 m0, s1
	s_nop 0
	global_load_lds_dwordx4 v[222:223], off
	s_mov_b32 m0, s5
	s_nop 0
	global_load_lds_dwordx4 v[224:225], off
	s_waitcnt vmcnt(8)
	s_waitcnt lgkmcnt(0)
	s_barrier
; #define PG8_STAGE(bufoff, gbase, voff) do { _Pragma("unroll") for (int _i = 0; _i < 2; ++_i) \
;         __builtin_amdgcn_global_load_lds((const unsigned*)((const char*)(gbase) + (voff)[_i]), (PG8_LAS unsigned*)(lds + (bufoff) + ldsw + _i * 8192), 16, 0, 0); } while (0)
; #define PG8_STAGEA(bufoff, gbase, voff) do { _Pragma("unroll") for (int _i = 0; _i < 2; ++_i) \
;         __builtin_amdgcn_global_load_lds((const unsigned*)((const char*)(gbase) + (voff)[_i]), (PG8_LAS unsigned*)(lds + (bufoff) + ldsw + _i * 8192), 16, 0, AUXA); } while (0)
; #define PG8_LDA(dst, b, h) do { _Pragma("unroll") for (int m = 0; m < 4; ++m) _Pragma("unroll") for (int k = 0; k < 2; ++k) dst[m][k] = *(const PG8_LAS bf16x8*)(lds + PG8_SA(b, h) + aoff + m * 2048 + k * 1024); } while (0)
; #define PG8_LDB(dst, b, h) do { _Pragma("unroll") for (int n = 0; n < 2; ++n) _Pragma("unroll") for (int k = 0; k < 2; ++k) dst[n][k] = *(const PG8_LAS bf16x8*)(lds + PG8_SB(b, h) + boff + n * 2048 + k * 1024); } while (0)
; #define PG8_WAIT_V(n) asm volatile("s_waitcnt vmcnt(" #n ")" ::: "memory")
; #define PG8_WAIT_L(n) asm volatile("s_waitcnt lgkmcnt(" #n ")" ::: "memory")
; #define PG8_BAR __builtin_amdgcn_s_barrier()
; #define PG8_SCHED __builtin_amdgcn_sched_barrier(0)
;     ...
;             if constexpr (SP2) {
;             PG8_LDB(B0, 0, 0); PG8_LDB(B1, 0, 1); PG8_SCHED; PG8_LDA(At, 0, 0); PG8_STAGEA(PG8_SA(1, 1), a1 + hstep, voffA);
;             PG8_WAIT_V(8); PG8_WAIT_L(0); PG8_BAR; PG8_MMA(0, 0, At, B0); PG8_MMA(0, 1, At, B1); PG8_BAR; PG8_SCHED;
;             PG8_LDA(At, 0, 1); PG8_STAGE(PG8_SB(0, 0), b2, voffB); PG8_STAGE(PG8_SB(0, 1), b2 + hstepB, voffB); PG8_STAGEA(PG8_SA(0, 0), a2, voffA);
;             PG8_WAIT_V(8); PG8_WAIT_L(0); PG8_BAR; PG8_MMA(1, 0, At, B0); PG8_MMA(1, 1, At, B1); PG8_BAR; PG8_SCHED;
;             PG8_LDB(B0, 1, 0); PG8_LDB(B1, 1, 1); PG8_SCHED; PG8_LDA(At, 1, 0); PG8_STAGEA(PG8_SA(0, 1), a2 + hstep, voffA);
;             PG8_WAIT_V(8); PG8_WAIT_L(0); PG8_BAR; PG8_MMA(0, 0, At, B0); PG8_MMA(0, 1, At, B1); PG8_BAR; PG8_SCHED;
;             PG8_LDA(At, 1, 1); PG8_STAGE(PG8_SB(1, 0), b3, voffB); PG8_STAGE(PG8_SB(1, 1), b3 + hstepB, voffB); PG8_STAGEA(PG8_SA(1, 0), a3, voffA);
;             PG8_WAIT_V(8); PG8_WAIT_L(0); PG8_BAR; PG8_MMA(1, 0, At, B0); PG8_MMA(1, 1, At, B1); PG8_BAR; PG8_SCHED;
	v_mfma_f32_16x16x32_bf16 v[60:63], v[148:151], v[184:187], v[60:63]
	v_mfma_f32_16x16x32_bf16 v[56:59], v[156:159], v[184:187], v[56:59]
	v_mfma_f32_16x16x32_bf16 v[44:47], v[148:151], v[192:195], v[44:47]
	v_mfma_f32_16x16x32_bf16 v[40:43], v[156:159], v[192:195], v[40:43]
	v_mfma_f32_16x16x32_bf16 v[28:31], v[148:151], v[202:205], v[28:31]
	v_mfma_f32_16x16x32_bf16 v[24:27], v[156:159], v[202:205], v[24:27]
	v_mfma_f32_16x16x32_bf16 v[12:15], v[148:151], v[214:217], v[12:15]
	v_mfma_f32_16x16x32_bf16 v[8:11], v[156:159], v[214:217], v[8:11]
	v_mfma_f32_16x16x32_bf16 v[60:63], v[152:155], v[188:191], v[60:63]
	v_mfma_f32_16x16x32_bf16 v[56:59], v[160:163], v[188:191], v[56:59]
	v_mfma_f32_16x16x32_bf16 v[44:47], v[152:155], v[196:199], v[44:47]
	v_mfma_f32_16x16x32_bf16 v[40:43], v[160:163], v[196:199], v[40:43]
	v_mfma_f32_16x16x32_bf16 v[28:31], v[152:155], v[210:213], v[28:31]
	v_mfma_f32_16x16x32_bf16 v[24:27], v[160:163], v[210:213], v[24:27]
	v_mfma_f32_16x16x32_bf16 v[12:15], v[152:155], v[218:221], v[12:15]
	v_mfma_f32_16x16x32_bf16 v[8:11], v[160:163], v[218:221], v[8:11]
	v_mfma_f32_16x16x32_bf16 v[52:55], v[164:167], v[184:187], v[52:55]
	v_mfma_f32_16x16x32_bf16 v[48:51], v[176:179], v[184:187], v[48:51]
	v_mfma_f32_16x16x32_bf16 v[36:39], v[164:167], v[192:195], v[36:39]
	v_mfma_f32_16x16x32_bf16 v[32:35], v[176:179], v[192:195], v[32:35]
	v_mfma_f32_16x16x32_bf16 v[20:23], v[164:167], v[202:205], v[20:23]
	v_mfma_f32_16x16x32_bf16 v[16:19], v[176:179], v[202:205], v[16:19]
	v_mfma_f32_16x16x32_bf16 v[4:7], v[164:167], v[214:217], v[4:7]
	v_mfma_f32_16x16x32_bf16 v[0:3], v[176:179], v[214:217], v[0:3]
	v_mfma_f32_16x16x32_bf16 v[52:55], v[168:171], v[188:191], v[52:55]
	v_mfma_f32_16x16x32_bf16 v[48:51], v[180:183], v[188:191], v[48:51]
	v_mfma_f32_16x16x32_bf16 v[36:39], v[168:171], v[196:199], v[36:39]
	v_mfma_f32_16x16x32_bf16 v[32:35], v[180:183], v[196:199], v[32:35]
	v_mfma_f32_16x16x32_bf16 v[20:23], v[168:171], v[210:213], v[20:23]
	v_mfma_f32_16x16x32_bf16 v[16:19], v[180:183], v[210:213], v[16:19]
	v_mfma_f32_16x16x32_bf16 v[4:7], v[168:171], v[218:221], v[4:7]
	v_mfma_f32_16x16x32_bf16 v[0:3], v[180:183], v[218:221], v[0:3]
	s_barrier
	ds_read_b128 v[148:151], v145
	ds_read_b128 v[152:155], v145 offset:1024
	ds_read_b128 v[156:159], v145 offset:2048
	ds_read_b128 v[160:163], v145 offset:3072
	ds_read_b128 v[164:167], v146
	ds_read_b128 v[168:171], v146 offset:1024
	ds_read_b128 v[176:179], v146 offset:2048
	ds_read_b128 v[180:183], v146 offset:3072
	s_add_u32 s16, s16, 0x40000
	s_addc_u32 s17, s17, 0
	s_mov_b32 m0, s18
	v_lshl_add_u64 v[226:227], s[16:17], 0, v[136:137]
	ds_read_b128 v[184:187], v144 offset:32768
	ds_read_b128 v[188:191], v144 offset:33792
	ds_read_b128 v[192:195], v144 offset:34816
	ds_read_b128 v[196:199], v144 offset:35840
	ds_read_b128 v[202:205], v144 offset:36864
	ds_read_b128 v[210:213], v144 offset:37888
	ds_read_b128 v[214:217], v144 offset:38912
	ds_read_b128 v[218:221], v144 offset:39936
	global_load_lds_dwordx4 v[226:227], off
	v_lshl_add_u64 v[226:227], s[16:17], 0, v[132:133]
	s_mov_b32 m0, s19
	s_nop 0
	global_load_lds_dwordx4 v[226:227], off
	s_waitcnt vmcnt(8)
	s_waitcnt lgkmcnt(0)
	s_barrier
	v_mfma_f32_16x16x32_bf16 v[124:127], v[148:151], v[184:187], v[124:127]
	v_mfma_f32_16x16x32_bf16 v[120:123], v[156:159], v[184:187], v[120:123]
	v_mfma_f32_16x16x32_bf16 v[108:111], v[148:151], v[192:195], v[108:111]
	v_mfma_f32_16x16x32_bf16 v[104:107], v[156:159], v[192:195], v[104:107]
	v_mfma_f32_16x16x32_bf16 v[92:95], v[148:151], v[202:205], v[92:95]
	v_mfma_f32_16x16x32_bf16 v[88:91], v[156:159], v[202:205], v[88:91]
	v_mfma_f32_16x16x32_bf16 v[76:79], v[148:151], v[214:217], v[76:79]
	v_mfma_f32_16x16x32_bf16 v[72:75], v[156:159], v[214:217], v[72:75]
	v_mfma_f32_16x16x32_bf16 v[124:127], v[152:155], v[188:191], v[124:127]
	v_mfma_f32_16x16x32_bf16 v[120:123], v[160:163], v[188:191], v[120:123]
	v_mfma_f32_16x16x32_bf16 v[108:111], v[152:155], v[196:199], v[108:111]
	v_mfma_f32_16x16x32_bf16 v[104:107], v[160:163], v[196:199], v[104:107]
	v_mfma_f32_16x16x32_bf16 v[92:95], v[152:155], v[210:213], v[92:95]
	v_mfma_f32_16x16x32_bf16 v[88:91], v[160:163], v[210:213], v[88:91]
	v_mfma_f32_16x16x32_bf16 v[76:79], v[152:155], v[218:221], v[76:79]
	v_mfma_f32_16x16x32_bf16 v[72:75], v[160:163], v[218:221], v[72:75]
	v_mfma_f32_16x16x32_bf16 v[116:119], v[164:167], v[184:187], v[116:119]
	v_mfma_f32_16x16x32_bf16 v[112:115], v[176:179], v[184:187], v[112:115]
	v_mfma_f32_16x16x32_bf16 v[100:103], v[164:167], v[192:195], v[100:103]
	v_mfma_f32_16x16x32_bf16 v[96:99], v[176:179], v[192:195], v[96:99]
	v_mfma_f32_16x16x32_bf16 v[84:87], v[164:167], v[202:205], v[84:87]
	v_mfma_f32_16x16x32_bf16 v[80:83], v[176:179], v[202:205], v[80:83]
	v_mfma_f32_16x16x32_bf16 v[68:71], v[164:167], v[214:217], v[68:71]
	v_mfma_f32_16x16x32_bf16 v[64:67], v[176:179], v[214:217], v[64:67]
	v_mfma_f32_16x16x32_bf16 v[116:119], v[168:171], v[188:191], v[116:119]
	v_mfma_f32_16x16x32_bf16 v[112:115], v[180:183], v[188:191], v[112:115]
	v_mfma_f32_16x16x32_bf16 v[100:103], v[168:171], v[196:199], v[100:103]
	v_mfma_f32_16x16x32_bf16 v[96:99], v[180:183], v[196:199], v[96:99]
	v_mfma_f32_16x16x32_bf16 v[84:87], v[168:171], v[210:213], v[84:87]
	v_mfma_f32_16x16x32_bf16 v[80:83], v[180:183], v[210:213], v[80:83]
	v_mfma_f32_16x16x32_bf16 v[68:71], v[168:171], v[218:221], v[68:71]
	v_mfma_f32_16x16x32_bf16 v[64:67], v[180:183], v[218:221], v[64:67]
	s_barrier
; #define PG8_STAGE(bufoff, gbase, voff) do { _Pragma("unroll") for (int _i = 0; _i < 2; ++_i) \
;         __builtin_amdgcn_global_load_lds((const unsigned*)((const char*)(gbase) + (voff)[_i]), (PG8_LAS unsigned*)(lds + (bufoff) + ldsw + _i * 8192), 16, 0, 0); } while (0)
; #define PG8_STAGEA(bufoff, gbase, voff) do { _Pragma("unroll") for (int _i = 0; _i < 2; ++_i) \
;         __builtin_amdgcn_global_load_lds((const unsigned*)((const char*)(gbase) + (voff)[_i]), (PG8_LAS unsigned*)(lds + (bufoff) + ldsw + _i * 8192), 16, 0, AUXA); } while (0)
; #define PG8_LDA(dst, b, h) do { _Pragma("unroll") for (int m = 0; m < 4; ++m) _Pragma("unroll") for (int k = 0; k < 2; ++k) dst[m][k] = *(const PG8_LAS bf16x8*)(lds + PG8_SA(b, h) + aoff + m * 2048 + k * 1024); } while (0)
; #define PG8_LDB(dst, b, h) do { _Pragma("unroll") for (int n = 0; n < 2; ++n) _Pragma("unroll") for (int k = 0; k < 2; ++k) dst[n][k] = *(const PG8_LAS bf16x8*)(lds + PG8_SB(b, h) + boff + n * 2048 + k * 1024); } while (0)
; #define PG8_WAIT_V(n) asm volatile("s_waitcnt vmcnt(" #n ")" ::: "memory")
; #define PG8_WAIT_L(n) asm volatile("s_waitcnt lgkmcnt(" #n ")" ::: "memory")
; #define PG8_BAR __builtin_amdgcn_s_barrier()
; #define PG8_SCHED __builtin_amdgcn_sched_barrier(0)
;     ...
;             if constexpr (SP2) {
;             PG8_LDB(B0, 0, 0); PG8_LDB(B1, 0, 1); PG8_SCHED; PG8_LDA(At, 0, 0); PG8_STAGEA(PG8_SA(1, 1), a1 + hstep, voffA);
;             PG8_WAIT_V(8); PG8_WAIT_L(0); PG8_BAR; PG8_MMA(0, 0, At, B0); PG8_MMA(0, 1, At, B1); PG8_BAR; PG8_SCHED;
;             PG8_LDA(At, 0, 1); PG8_STAGE(PG8_SB(0, 0), b2, voffB); PG8_STAGE(PG8_SB(0, 1), b2 + hstepB, voffB); PG8_STAGEA(PG8_SA(0, 0), a2, voffA);
;             PG8_WAIT_V(8); PG8_WAIT_L(0); PG8_BAR; PG8_MMA(1, 0, At, B0); PG8_MMA(1, 1, At, B1); PG8_BAR; PG8_SCHED;
;             PG8_LDB(B0, 1, 0); PG8_LDB(B1, 1, 1); PG8_SCHED; PG8_LDA(At, 1, 0); PG8_STAGEA(PG8_SA(0, 1), a2 + hstep, voffA);
;             PG8_WAIT_V(8); PG8_WAIT_L(0); PG8_BAR; PG8_MMA(0, 0, At, B0); PG8_MMA(0, 1, At, B1); PG8_BAR; PG8_SCHED;
;             PG8_LDA(At, 1, 1); PG8_STAGE(PG8_SB(1, 0), b3, voffB); PG8_STAGE(PG8_SB(1, 1), b3 + hstepB, voffB); PG8_STAGEA(PG8_SA(1, 0), a3, voffA);
;             PG8_WAIT_V(8); PG8_WAIT_L(0); PG8_BAR; PG8_MMA(1, 0, At, B0); PG8_MMA(1, 1, At, B1); PG8_BAR; PG8_SCHED;
;     ...
;         if constexpr (ALIGN_EPI) { if (wr == 0) PG8_BAR; }
	s_mov_b32 m0, s29
	v_lshl_add_u64 v[172:173], v[172:173], 0, s[10:11]
	s_add_u32 s14, s14, 0x10080
	ds_read_b128 v[184:187], v144 offset:49152
	ds_read_b128 v[188:191], v144 offset:50176
	ds_read_b128 v[192:195], v144 offset:51200
	ds_read_b128 v[196:199], v144 offset:52224
	ds_read_b128 v[202:205], v144 offset:53248
	ds_read_b128 v[210:213], v144 offset:54272
	ds_read_b128 v[214:217], v144 offset:55296
	ds_read_b128 v[218:221], v144 offset:56320
	global_load_lds_dwordx4 v[172:173], off
	v_lshl_add_u64 v[172:173], v[206:207], 0, s[10:11]
	s_mov_b32 m0, s30
	s_addc_u32 s15, s15, 0
	global_load_lds_dwordx4 v[172:173], off
	v_lshl_add_u64 v[172:173], s[14:15], 0, v[134:135]
	s_mov_b32 m0, s31
	s_nop 0
	global_load_lds_dwordx4 v[172:173], off
	v_lshl_add_u64 v[172:173], s[14:15], 0, v[130:131]
	s_mov_b32 m0, s34
	s_nop 0
	global_load_lds_dwordx4 v[172:173], off
	v_lshl_add_u64 v[172:173], v[222:223], 0, s[10:11]
	s_mov_b32 m0, s20
	s_nop 0
	global_load_lds_dwordx4 v[172:173], off
	v_lshl_add_u64 v[172:173], v[224:225], 0, s[10:11]
	s_mov_b32 m0, s21
	s_nop 0
	global_load_lds_dwordx4 v[172:173], off
	s_waitcnt vmcnt(8)
	s_waitcnt lgkmcnt(0)
	s_barrier
	v_mfma_f32_16x16x32_bf16 v[60:63], v[148:151], v[184:187], v[60:63]
	v_mfma_f32_16x16x32_bf16 v[56:59], v[156:159], v[184:187], v[56:59]
	v_mfma_f32_16x16x32_bf16 v[44:47], v[148:151], v[192:195], v[44:47]
	v_mfma_f32_16x16x32_bf16 v[40:43], v[156:159], v[192:195], v[40:43]
	v_mfma_f32_16x16x32_bf16 v[28:31], v[148:151], v[202:205], v[28:31]
	v_mfma_f32_16x16x32_bf16 v[24:27], v[156:159], v[202:205], v[24:27]
	v_mfma_f32_16x16x32_bf16 v[12:15], v[148:151], v[214:217], v[12:15]
	v_mfma_f32_16x16x32_bf16 v[8:11], v[156:159], v[214:217], v[8:11]
	v_mfma_f32_16x16x32_bf16 v[60:63], v[152:155], v[188:191], v[60:63]
	v_mfma_f32_16x16x32_bf16 v[56:59], v[160:163], v[188:191], v[56:59]
	v_mfma_f32_16x16x32_bf16 v[44:47], v[152:155], v[196:199], v[44:47]
	v_mfma_f32_16x16x32_bf16 v[40:43], v[160:163], v[196:199], v[40:43]
	v_mfma_f32_16x16x32_bf16 v[28:31], v[152:155], v[210:213], v[28:31]
	v_mfma_f32_16x16x32_bf16 v[24:27], v[160:163], v[210:213], v[24:27]
	v_mfma_f32_16x16x32_bf16 v[12:15], v[152:155], v[218:221], v[12:15]
	v_mfma_f32_16x16x32_bf16 v[8:11], v[160:163], v[218:221], v[8:11]
	v_mfma_f32_16x16x32_bf16 v[52:55], v[164:167], v[184:187], v[52:55]
	v_mfma_f32_16x16x32_bf16 v[48:51], v[176:179], v[184:187], v[48:51]
	v_mfma_f32_16x16x32_bf16 v[36:39], v[164:167], v[192:195], v[36:39]
	v_mfma_f32_16x16x32_bf16 v[32:35], v[176:179], v[192:195], v[32:35]
	v_mfma_f32_16x16x32_bf16 v[20:23], v[164:167], v[202:205], v[20:23]
	v_mfma_f32_16x16x32_bf16 v[16:19], v[176:179], v[202:205], v[16:19]
	v_mfma_f32_16x16x32_bf16 v[4:7], v[164:167], v[214:217], v[4:7]
	v_mfma_f32_16x16x32_bf16 v[0:3], v[176:179], v[214:217], v[0:3]
	v_mfma_f32_16x16x32_bf16 v[52:55], v[168:171], v[188:191], v[52:55]
	v_mfma_f32_16x16x32_bf16 v[48:51], v[180:183], v[188:191], v[48:51]
	v_mfma_f32_16x16x32_bf16 v[36:39], v[168:171], v[196:199], v[36:39]
	v_mfma_f32_16x16x32_bf16 v[32:35], v[180:183], v[196:199], v[32:35]
	v_mfma_f32_16x16x32_bf16 v[20:23], v[168:171], v[210:213], v[20:23]
	v_mfma_f32_16x16x32_bf16 v[16:19], v[180:183], v[210:213], v[16:19]
	v_mfma_f32_16x16x32_bf16 v[4:7], v[168:171], v[218:221], v[4:7]
	v_mfma_f32_16x16x32_bf16 v[0:3], v[180:183], v[218:221], v[0:3]
	s_barrier
	s_add_i32 s22, s22, 2
	s_add_u32 s12, s12, 0x100
	s_addc_u32 s13, s13, 0
	s_cmp_gt_u32 s22, 13
	s_cbranch_scc0 .LBB0_758
	s_setprio 0
	v_readlane_b32 s1, v255, 10
	s_cmpk_lt_u32 s1, 0x100
	s_cbranch_scc0 .LBB0_761
	s_barrier

;     __host__ __device__ bool next(int i, Unit& u) const { return at((long)i * G + c, u); }
;     __host__ __device__ bool next(int i, Unit& u) const { if (i != 0 || c >= cnt) return false; u.pm = pm0 + c / nN; u.pn = c % nN; u.k0 = 0; u.nt = ntk; return true; }
; #define PG8_STAGE(bufoff, gbase, voff) do { _Pragma("unroll") for (int _i = 0; _i < 2; ++_i) \
;         __builtin_amdgcn_global_load_lds((const unsigned*)((const char*)(gbase) + (voff)[_i]), (PG8_LAS unsigned*)(lds + (bufoff) + ldsw + _i * 8192), 16, 0, 0); } while (0)
; #define PG8_BAR __builtin_amdgcn_s_barrier()
;     ...
;     for (;;) {
;         const bool has_next = S.next(ui + 1, nxt);
;         const char* nA = has_next ? (const char*)g.A + (size_t)nxt.pm * tstep + (size_t)nxt.k0 * (BK * 2) : cA; const char* nB = has_next ? (const char*)g.Bt + (size_t)nxt.pn * tstep + (size_t)nxt.k0 * (BK * 2) : cB;
;         const int nt = cur.nt;
;         for (int t = 0; t < nt; t += 2) {
;             const bool last = (t == nt - 2);
;             const char* a1 = cA + (size_t)(t + 1) * kstep;
;             const char* a2 = last ? nA : cA + (size_t)(t + 2) * kstep; const char* b2 = last ? nB : cB + (size_t)(t + 2) * kstep;
;             const char* a3 = a2 + kstep; const char* b3 = b2 + kstep;
;             if (last && has_next) S.a_ready(nxt);
;             if constexpr (SP2) {
;             PG8_LDB(B0, 0, 0); PG8_LDB(B1, 0, 1); PG8_SCHED; PG8_LDA(At, 0, 0); PG8_STAGEA(PG8_SA(1, 1), a1 + hstep, voffA);
;             PG8_WAIT_V(8); PG8_WAIT_L(0); PG8_BAR; PG8_MMA(0, 0, At, B0); PG8_MMA(0, 1, At, B1); PG8_BAR; PG8_SCHED;
;             PG8_LDA(At, 0, 1); PG8_STAGE(PG8_SB(0, 0), b2, voffB); PG8_STAGE(PG8_SB(0, 1), b2 + hstepB, voffB); PG8_STAGEA(PG8_SA(0, 0), a2, voffA);
;             PG8_WAIT_V(8); PG8_WAIT_L(0); PG8_BAR; PG8_MMA(1, 0, At, B0); PG8_MMA(1, 1, At, B1); PG8_BAR; PG8_SCHED;
;             PG8_LDB(B0, 1, 0); PG8_LDB(B1, 1, 1); PG8_SCHED; PG8_LDA(At, 1, 0); PG8_STAGEA(PG8_SA(0, 1), a2 + hstep, voffA);
;             PG8_WAIT_V(8); PG8_WAIT_L(0); PG8_BAR; PG8_MMA(0, 0, At, B0); PG8_MMA(0, 1, At, B1); PG8_BAR; PG8_SCHED;
;             PG8_LDA(At, 1, 1); PG8_STAGE(PG8_SB(1, 0), b3, voffB); PG8_STAGE(PG8_SB(1, 1), b3 + hstepB, voffB); PG8_STAGEA(PG8_SA(1, 0), a3, voffA);
;             PG8_WAIT_V(8); PG8_WAIT_L(0); PG8_BAR; PG8_MMA(1, 0, At, B0); PG8_MMA(1, 1, At, B1); PG8_BAR; PG8_SCHED;
.Lsprio_3:
.LBB0_854:
	ds_read_b128 v[142:145], v151
	ds_read_b128 v[154:157], v151 offset:1024
	ds_read_b128 v[158:161], v151 offset:2048
	ds_read_b128 v[162:165], v151 offset:3072
	ds_read_b128 v[166:169], v152
	ds_read_b128 v[170:173], v152 offset:1024
	ds_read_b128 v[176:179], v152 offset:2048
	ds_read_b128 v[180:183], v152 offset:3072
	s_add_u32 s36, s34, 0xfffc0080
	s_addc_u32 s37, s35, -1
	s_cmp_eq_u32 s58, 12
	s_cselect_b32 s39, s15, s37
	s_cselect_b32 s38, s25, s36
	s_cselect_b32 s37, s23, s57
	s_cselect_b32 s36, s31, s56
	v_lshl_add_u64 v[206:207], s[34:35], 0, v[136:137]
	s_add_i32 m0, s40, 0xc000
	ds_read_b128 v[184:187], v153
	ds_read_b128 v[188:191], v153 offset:1024
	ds_read_b128 v[192:195], v153 offset:2048
	ds_read_b128 v[196:199], v153 offset:3072
	ds_read_b128 v[202:205], v153 offset:4096
	ds_read_b128 v[210:213], v153 offset:5120
	ds_read_b128 v[214:217], v153 offset:6144
	ds_read_b128 v[218:221], v153 offset:7168
	global_load_lds_dwordx4 v[206:207], off
	v_lshl_add_u64 v[206:207], s[34:35], 0, v[138:139]
	s_add_i32 m0, s40, 0xe000
	s_nop 0
	global_load_lds_dwordx4 v[206:207], off
	s_waitcnt vmcnt(8)
	s_waitcnt lgkmcnt(0)
	s_barrier
	v_mfma_f32_16x16x32_bf16 v[124:127], v[142:145], v[184:187], v[124:127]
	v_mfma_f32_16x16x32_bf16 v[120:123], v[158:161], v[184:187], v[120:123]
	v_mfma_f32_16x16x32_bf16 v[108:111], v[142:145], v[192:195], v[108:111]
	v_mfma_f32_16x16x32_bf16 v[104:107], v[158:161], v[192:195], v[104:107]
	v_mfma_f32_16x16x32_bf16 v[92:95], v[142:145], v[202:205], v[92:95]
	v_mfma_f32_16x16x32_bf16 v[88:91], v[158:161], v[202:205], v[88:91]
	v_mfma_f32_16x16x32_bf16 v[76:79], v[142:145], v[214:217], v[76:79]
	v_mfma_f32_16x16x32_bf16 v[72:75], v[158:161], v[214:217], v[72:75]
	v_mfma_f32_16x16x32_bf16 v[124:127], v[154:157], v[188:191], v[124:127]
	v_mfma_f32_16x16x32_bf16 v[120:123], v[162:165], v[188:191], v[120:123]
	v_mfma_f32_16x16x32_bf16 v[108:111], v[154:157], v[196:199], v[108:111]
	v_mfma_f32_16x16x32_bf16 v[104:107], v[162:165], v[196:199], v[104:107]
	v_mfma_f32_16x16x32_bf16 v[92:95], v[154:157], v[210:213], v[92:95]
	v_mfma_f32_16x16x32_bf16 v[88:91], v[162:165], v[210:213], v[88:91]
	v_mfma_f32_16x16x32_bf16 v[76:79], v[154:157], v[218:221], v[76:79]
	v_mfma_f32_16x16x32_bf16 v[72:75], v[162:165], v[218:221], v[72:75]
	v_mfma_f32_16x16x32_bf16 v[116:119], v[166:169], v[184:187], v[116:119]
	v_mfma_f32_16x16x32_bf16 v[112:115], v[176:179], v[184:187], v[112:115]
	v_mfma_f32_16x16x32_bf16 v[100:103], v[166:169], v[192:195], v[100:103]
	v_mfma_f32_16x16x32_bf16 v[96:99], v[176:179], v[192:195], v[96:99]
	v_mfma_f32_16x16x32_bf16 v[84:87], v[166:169], v[202:205], v[84:87]
	v_mfma_f32_16x16x32_bf16 v[80:83], v[176:179], v[202:205], v[80:83]
	v_mfma_f32_16x16x32_bf16 v[68:71], v[166:169], v[214:217], v[68:71]
	v_mfma_f32_16x16x32_bf16 v[64:67], v[176:179], v[214:217], v[64:67]
	v_mfma_f32_16x16x32_bf16 v[116:119], v[170:173], v[188:191], v[116:119]
	v_mfma_f32_16x16x32_bf16 v[112:115], v[180:183], v[188:191], v[112:115]
	v_mfma_f32_16x16x32_bf16 v[100:103], v[170:173], v[196:199], v[100:103]
	v_mfma_f32_16x16x32_bf16 v[96:99], v[180:183], v[196:199], v[96:99]
	v_mfma_f32_16x16x32_bf16 v[84:87], v[170:173], v[210:213], v[84:87]
	v_mfma_f32_16x16x32_bf16 v[80:83], v[180:183], v[210:213], v[80:83]
	v_mfma_f32_16x16x32_bf16 v[68:71], v[170:173], v[218:221], v[68:71]
	v_mfma_f32_16x16x32_bf16 v[64:67], v[180:183], v[218:221], v[64:67]
	s_barrier
	s_add_i32 s59, s54, s67
	v_lshl_add_u64 v[206:207], s[36:37], 0, v[130:131]
	s_mov_b32 m0, s59
	ds_read_b128 v[184:187], v153 offset:16384
	ds_read_b128 v[188:191], v153 offset:17408
	ds_read_b128 v[192:195], v153 offset:18432
	ds_read_b128 v[196:199], v153 offset:19456
	ds_read_b128 v[202:205], v153 offset:20480
	ds_read_b128 v[210:213], v153 offset:21504
	ds_read_b128 v[214:217], v153 offset:22528
	ds_read_b128 v[218:221], v153 offset:23552
	global_load_lds_dwordx4 v[206:207], off
	s_add_i32 m0, s59, 0x2000
	s_add_u32 s70, s36, 0x10000
	v_lshl_add_u64 v[222:223], s[36:37], 0, v[134:135]
	s_addc_u32 s71, s37, 0
	s_add_i32 s59, s55, s67
	global_load_lds_dwordx4 v[222:223], off
	v_lshl_add_u64 v[224:225], s[70:71], 0, v[130:131]
	s_mov_b32 m0, s59
	v_lshl_add_u64 v[226:227], s[38:39], 0, v[132:133]
	global_load_lds_dwordx4 v[224:225], off
	v_lshl_add_u64 v[224:225], s[70:71], 0, v[134:135]
	s_add_i32 m0, s59, 0x2000
	s_nop 0
	global_load_lds_dwordx4 v[224:225], off
	v_lshl_add_u64 v[224:225], s[38:39], 0, v[128:129]
	s_mov_b32 m0, s40
	s_nop 0
	global_load_lds_dwordx4 v[224:225], off
	s_mov_b32 m0, s41
	s_nop 0
	global_load_lds_dwordx4 v[226:227], off
	s_waitcnt vmcnt(8)
	s_waitcnt lgkmcnt(0)
	s_barrier
; #define PG8_STAGE(bufoff, gbase, voff) do { _Pragma("unroll") for (int _i = 0; _i < 2; ++_i) \
;         __builtin_amdgcn_global_load_lds((const unsigned*)((const char*)(gbase) + (voff)[_i]), (PG8_LAS unsigned*)(lds + (bufoff) + ldsw + _i * 8192), 16, 0, 0); } while (0)
; #define PG8_STAGEA(bufoff, gbase, voff) do { _Pragma("unroll") for (int _i = 0; _i < 2; ++_i) \
;         __builtin_amdgcn_global_load_lds((const unsigned*)((const char*)(gbase) + (voff)[_i]), (PG8_LAS unsigned*)(lds + (bufoff) + ldsw + _i * 8192), 16, 0, AUXA); } while (0)
; #define PG8_LDA(dst, b, h) do { _Pragma("unroll") for (int m = 0; m < 4; ++m) _Pragma("unroll") for (int k = 0; k < 2; ++k) dst[m][k] = *(const PG8_LAS bf16x8*)(lds + PG8_SA(b, h) + aoff + m * 2048 + k * 1024); } while (0)
; #define PG8_LDB(dst, b, h) do { _Pragma("unroll") for (int n = 0; n < 2; ++n) _Pragma("unroll") for (int k = 0; k < 2; ++k) dst[n][k] = *(const PG8_LAS bf16x8*)(lds + PG8_SB(b, h) + boff + n * 2048 + k * 1024); } while (0)
; #define PG8_WAIT_V(n) asm volatile("s_waitcnt vmcnt(" #n ")" ::: "memory")
; #define PG8_WAIT_L(n) asm volatile("s_waitcnt lgkmcnt(" #n ")" ::: "memory")
; #define PG8_BAR __builtin_amdgcn_s_barrier()
; #define PG8_SCHED __builtin_amdgcn_sched_barrier(0)
;     ...
;             if constexpr (SP2) {
;             PG8_LDB(B0, 0, 0); PG8_LDB(B1, 0, 1); PG8_SCHED; PG8_LDA(At, 0, 0); PG8_STAGEA(PG8_SA(1, 1), a1 + hstep, voffA);
;             PG8_WAIT_V(8); PG8_WAIT_L(0); PG8_BAR; PG8_MMA(0, 0, At, B0); PG8_MMA(0, 1, At, B1); PG8_BAR; PG8_SCHED;
;             PG8_LDA(At, 0, 1); PG8_STAGE(PG8_SB(0, 0), b2, voffB); PG8_STAGE(PG8_SB(0, 1), b2 + hstepB, voffB); PG8_STAGEA(PG8_SA(0, 0), a2, voffA);
;             PG8_WAIT_V(8); PG8_WAIT_L(0); PG8_BAR; PG8_MMA(1, 0, At, B0); PG8_MMA(1, 1, At, B1); PG8_BAR; PG8_SCHED;
;             PG8_LDB(B0, 1, 0); PG8_LDB(B1, 1, 1); PG8_SCHED; PG8_LDA(At, 1, 0); PG8_STAGEA(PG8_SA(0, 1), a2 + hstep, voffA);
;             PG8_WAIT_V(8); PG8_WAIT_L(0); PG8_BAR; PG8_MMA(0, 0, At, B0); PG8_MMA(0, 1, At, B1); PG8_BAR; PG8_SCHED;
;             PG8_LDA(At, 1, 1); PG8_STAGE(PG8_SB(1, 0), b3, voffB); PG8_STAGE(PG8_SB(1, 1), b3 + hstepB, voffB); PG8_STAGEA(PG8_SA(1, 0), a3, voffA);
;             PG8_WAIT_V(8); PG8_WAIT_L(0); PG8_BAR; PG8_MMA(1, 0, At, B0); PG8_MMA(1, 1, At, B1); PG8_BAR; PG8_SCHED;
	v_mfma_f32_16x16x32_bf16 v[60:63], v[142:145], v[184:187], v[60:63]
	v_mfma_f32_16x16x32_bf16 v[56:59], v[158:161], v[184:187], v[56:59]
	v_mfma_f32_16x16x32_bf16 v[44:47], v[142:145], v[192:195], v[44:47]
	v_mfma_f32_16x16x32_bf16 v[40:43], v[158:161], v[192:195], v[40:43]
	v_mfma_f32_16x16x32_bf16 v[28:31], v[142:145], v[202:205], v[28:31]
	v_mfma_f32_16x16x32_bf16 v[24:27], v[158:161], v[202:205], v[24:27]
	v_mfma_f32_16x16x32_bf16 v[12:15], v[142:145], v[214:217], v[12:15]
	v_mfma_f32_16x16x32_bf16 v[8:11], v[158:161], v[214:217], v[8:11]
	v_mfma_f32_16x16x32_bf16 v[60:63], v[154:157], v[188:191], v[60:63]
	v_mfma_f32_16x16x32_bf16 v[56:59], v[162:165], v[188:191], v[56:59]
	v_mfma_f32_16x16x32_bf16 v[44:47], v[154:157], v[196:199], v[44:47]
	v_mfma_f32_16x16x32_bf16 v[40:43], v[162:165], v[196:199], v[40:43]
	v_mfma_f32_16x16x32_bf16 v[28:31], v[154:157], v[210:213], v[28:31]
	v_mfma_f32_16x16x32_bf16 v[24:27], v[162:165], v[210:213], v[24:27]
	v_mfma_f32_16x16x32_bf16 v[12:15], v[154:157], v[218:221], v[12:15]
	v_mfma_f32_16x16x32_bf16 v[8:11], v[162:165], v[218:221], v[8:11]
	v_mfma_f32_16x16x32_bf16 v[52:55], v[166:169], v[184:187], v[52:55]
	v_mfma_f32_16x16x32_bf16 v[48:51], v[176:179], v[184:187], v[48:51]
	v_mfma_f32_16x16x32_bf16 v[36:39], v[166:169], v[192:195], v[36:39]
	v_mfma_f32_16x16x32_bf16 v[32:35], v[176:179], v[192:195], v[32:35]
	v_mfma_f32_16x16x32_bf16 v[20:23], v[166:169], v[202:205], v[20:23]
	v_mfma_f32_16x16x32_bf16 v[16:19], v[176:179], v[202:205], v[16:19]
	v_mfma_f32_16x16x32_bf16 v[4:7], v[166:169], v[214:217], v[4:7]
	v_mfma_f32_16x16x32_bf16 v[0:3], v[176:179], v[214:217], v[0:3]
	v_mfma_f32_16x16x32_bf16 v[52:55], v[170:173], v[188:191], v[52:55]
	v_mfma_f32_16x16x32_bf16 v[48:51], v[180:183], v[188:191], v[48:51]
	v_mfma_f32_16x16x32_bf16 v[36:39], v[170:173], v[196:199], v[36:39]
	v_mfma_f32_16x16x32_bf16 v[32:35], v[180:183], v[196:199], v[32:35]
	v_mfma_f32_16x16x32_bf16 v[20:23], v[170:173], v[210:213], v[20:23]
	v_mfma_f32_16x16x32_bf16 v[16:19], v[180:183], v[210:213], v[16:19]
	v_mfma_f32_16x16x32_bf16 v[4:7], v[170:173], v[218:221], v[4:7]
	v_mfma_f32_16x16x32_bf16 v[0:3], v[180:183], v[218:221], v[0:3]
	s_barrier
	s_add_i32 s59, 0, 0x18000
	s_add_i32 s70, 0, 0x1c000
	v_add_u32_e32 v162, s59, v147
	v_add_u32_e32 v174, s70, v147
	ds_read_b128 v[142:145], v162
	ds_read_b128 v[154:157], v162 offset:1024
	ds_read_b128 v[158:161], v162 offset:2048
	ds_read_b128 v[162:165], v162 offset:3072
	ds_read_b128 v[166:169], v174
	ds_read_b128 v[170:173], v174 offset:1024
	ds_read_b128 v[176:179], v174 offset:2048
	ds_read_b128 v[180:183], v174 offset:3072
	s_add_u32 s38, s38, 0x40000
	s_addc_u32 s39, s39, 0
	s_mov_b32 m0, s43
	v_lshl_add_u64 v[228:229], s[38:39], 0, v[128:129]
	ds_read_b128 v[184:187], v153 offset:32768
	ds_read_b128 v[188:191], v153 offset:33792
	ds_read_b128 v[192:195], v153 offset:34816
	ds_read_b128 v[196:199], v153 offset:35840
	ds_read_b128 v[202:205], v153 offset:36864
	ds_read_b128 v[210:213], v153 offset:37888
	ds_read_b128 v[214:217], v153 offset:38912
	ds_read_b128 v[218:221], v153 offset:39936
	global_load_lds_dwordx4 v[228:229], off
	v_lshl_add_u64 v[228:229], s[38:39], 0, v[132:133]
	s_mov_b32 m0, s44
	s_nop 0
	global_load_lds_dwordx4 v[228:229], off
	s_waitcnt vmcnt(8)
	s_waitcnt lgkmcnt(0)
	s_barrier
	v_mfma_f32_16x16x32_bf16 v[124:127], v[142:145], v[184:187], v[124:127]
	v_mfma_f32_16x16x32_bf16 v[120:123], v[158:161], v[184:187], v[120:123]
	v_mfma_f32_16x16x32_bf16 v[108:111], v[142:145], v[192:195], v[108:111]
	v_mfma_f32_16x16x32_bf16 v[104:107], v[158:161], v[192:195], v[104:107]
	v_mfma_f32_16x16x32_bf16 v[92:95], v[142:145], v[202:205], v[92:95]
	v_mfma_f32_16x16x32_bf16 v[88:91], v[158:161], v[202:205], v[88:91]
	v_mfma_f32_16x16x32_bf16 v[76:79], v[142:145], v[214:217], v[76:79]
	v_mfma_f32_16x16x32_bf16 v[72:75], v[158:161], v[214:217], v[72:75]
	v_mfma_f32_16x16x32_bf16 v[124:127], v[154:157], v[188:191], v[124:127]
	v_mfma_f32_16x16x32_bf16 v[120:123], v[162:165], v[188:191], v[120:123]
	v_mfma_f32_16x16x32_bf16 v[108:111], v[154:157], v[196:199], v[108:111]
	v_mfma_f32_16x16x32_bf16 v[104:107], v[162:165], v[196:199], v[104:107]
	v_mfma_f32_16x16x32_bf16 v[92:95], v[154:157], v[210:213], v[92:95]
	v_mfma_f32_16x16x32_bf16 v[88:91], v[162:165], v[210:213], v[88:91]
	v_mfma_f32_16x16x32_bf16 v[76:79], v[154:157], v[218:221], v[76:79]
	v_mfma_f32_16x16x32_bf16 v[72:75], v[162:165], v[218:221], v[72:75]
	v_mfma_f32_16x16x32_bf16 v[116:119], v[166:169], v[184:187], v[116:119]
	v_mfma_f32_16x16x32_bf16 v[112:115], v[176:179], v[184:187], v[112:115]
	v_mfma_f32_16x16x32_bf16 v[100:103], v[166:169], v[192:195], v[100:103]
	v_mfma_f32_16x16x32_bf16 v[96:99], v[176:179], v[192:195], v[96:99]
	v_mfma_f32_16x16x32_bf16 v[84:87], v[166:169], v[202:205], v[84:87]
	v_mfma_f32_16x16x32_bf16 v[80:83], v[176:179], v[202:205], v[80:83]
	v_mfma_f32_16x16x32_bf16 v[68:71], v[166:169], v[214:217], v[68:71]
	v_mfma_f32_16x16x32_bf16 v[64:67], v[176:179], v[214:217], v[64:67]
	v_mfma_f32_16x16x32_bf16 v[116:119], v[170:173], v[188:191], v[116:119]
	v_mfma_f32_16x16x32_bf16 v[112:115], v[180:183], v[188:191], v[112:115]
	v_mfma_f32_16x16x32_bf16 v[100:103], v[170:173], v[196:199], v[100:103]
	v_mfma_f32_16x16x32_bf16 v[96:99], v[180:183], v[196:199], v[96:99]
	v_mfma_f32_16x16x32_bf16 v[84:87], v[170:173], v[210:213], v[84:87]
	v_mfma_f32_16x16x32_bf16 v[80:83], v[180:183], v[210:213], v[80:83]
	v_mfma_f32_16x16x32_bf16 v[68:71], v[170:173], v[218:221], v[68:71]
	v_mfma_f32_16x16x32_bf16 v[64:67], v[180:183], v[218:221], v[64:67]
	s_barrier
; #define PG8_STAGE(bufoff, gbase, voff) do { _Pragma("unroll") for (int _i = 0; _i < 2; ++_i) \
;         __builtin_amdgcn_global_load_lds((const unsigned*)((const char*)(gbase) + (voff)[_i]), (PG8_LAS unsigned*)(lds + (bufoff) + ldsw + _i * 8192), 16, 0, 0); } while (0)
; #define PG8_STAGEA(bufoff, gbase, voff) do { _Pragma("unroll") for (int _i = 0; _i < 2; ++_i) \
;         __builtin_amdgcn_global_load_lds((const unsigned*)((const char*)(gbase) + (voff)[_i]), (PG8_LAS unsigned*)(lds + (bufoff) + ldsw + _i * 8192), 16, 0, AUXA); } while (0)
; #define PG8_LDA(dst, b, h) do { _Pragma("unroll") for (int m = 0; m < 4; ++m) _Pragma("unroll") for (int k = 0; k < 2; ++k) dst[m][k] = *(const PG8_LAS bf16x8*)(lds + PG8_SA(b, h) + aoff + m * 2048 + k * 1024); } while (0)
; #define PG8_LDB(dst, b, h) do { _Pragma("unroll") for (int n = 0; n < 2; ++n) _Pragma("unroll") for (int k = 0; k < 2; ++k) dst[n][k] = *(const PG8_LAS bf16x8*)(lds + PG8_SB(b, h) + boff + n * 2048 + k * 1024); } while (0)
; #define PG8_WAIT_V(n) asm volatile("s_waitcnt vmcnt(" #n ")" ::: "memory")
; #define PG8_WAIT_L(n) asm volatile("s_waitcnt lgkmcnt(" #n ")" ::: "memory")
; #define PG8_BAR __builtin_amdgcn_s_barrier()
; #define PG8_SCHED __builtin_amdgcn_sched_barrier(0)
;     ...
;             if constexpr (SP2) {
;             PG8_LDB(B0, 0, 0); PG8_LDB(B1, 0, 1); PG8_SCHED; PG8_LDA(At, 0, 0); PG8_STAGEA(PG8_SA(1, 1), a1 + hstep, voffA);
;             PG8_WAIT_V(8); PG8_WAIT_L(0); PG8_BAR; PG8_MMA(0, 0, At, B0); PG8_MMA(0, 1, At, B1); PG8_BAR; PG8_SCHED;
;             PG8_LDA(At, 0, 1); PG8_STAGE(PG8_SB(0, 0), b2, voffB); PG8_STAGE(PG8_SB(0, 1), b2 + hstepB, voffB); PG8_STAGEA(PG8_SA(0, 0), a2, voffA);
;             PG8_WAIT_V(8); PG8_WAIT_L(0); PG8_BAR; PG8_MMA(1, 0, At, B0); PG8_MMA(1, 1, At, B1); PG8_BAR; PG8_SCHED;
;             PG8_LDB(B0, 1, 0); PG8_LDB(B1, 1, 1); PG8_SCHED; PG8_LDA(At, 1, 0); PG8_STAGEA(PG8_SA(0, 1), a2 + hstep, voffA);
;             PG8_WAIT_V(8); PG8_WAIT_L(0); PG8_BAR; PG8_MMA(0, 0, At, B0); PG8_MMA(0, 1, At, B1); PG8_BAR; PG8_SCHED;
;             PG8_LDA(At, 1, 1); PG8_STAGE(PG8_SB(1, 0), b3, voffB); PG8_STAGE(PG8_SB(1, 1), b3 + hstepB, voffB); PG8_STAGEA(PG8_SA(1, 0), a3, voffA);
;             PG8_WAIT_V(8); PG8_WAIT_L(0); PG8_BAR; PG8_MMA(1, 0, At, B0); PG8_MMA(1, 1, At, B1); PG8_BAR; PG8_SCHED;
;     ...
;         if constexpr (ALIGN_EPI) { if (wr == 0) PG8_BAR; }
	s_add_i32 s38, s59, s67
	v_lshl_add_u64 v[206:207], v[206:207], 0, s[18:19]
	s_mov_b32 m0, s38
	ds_read_b128 v[184:187], v153 offset:49152
	ds_read_b128 v[188:191], v153 offset:50176
	ds_read_b128 v[192:195], v153 offset:51200
	ds_read_b128 v[196:199], v153 offset:52224
	ds_read_b128 v[202:205], v153 offset:53248
	ds_read_b128 v[210:213], v153 offset:54272
	ds_read_b128 v[214:217], v153 offset:55296
	ds_read_b128 v[218:221], v153 offset:56320
	global_load_lds_dwordx4 v[206:207], off
	s_add_i32 m0, s38, 0x2000
	s_add_u32 s36, s36, 0x10080
	v_lshl_add_u64 v[206:207], v[222:223], 0, s[18:19]
	s_addc_u32 s37, s37, 0
	s_add_i32 s38, s70, s67
	global_load_lds_dwordx4 v[206:207], off
	v_lshl_add_u64 v[206:207], s[36:37], 0, v[130:131]
	s_mov_b32 m0, s38
	s_nop 0
	global_load_lds_dwordx4 v[206:207], off
	v_lshl_add_u64 v[206:207], s[36:37], 0, v[134:135]
	s_add_i32 m0, s38, 0x2000
	s_nop 0
	global_load_lds_dwordx4 v[206:207], off
	v_lshl_add_u64 v[206:207], v[224:225], 0, s[18:19]
	s_mov_b32 m0, s45
	s_nop 0
	global_load_lds_dwordx4 v[206:207], off
	v_lshl_add_u64 v[206:207], v[226:227], 0, s[18:19]
	s_mov_b32 m0, s46
	s_nop 0
	global_load_lds_dwordx4 v[206:207], off
	s_waitcnt vmcnt(8)
	s_waitcnt lgkmcnt(0)
	s_barrier
	v_mfma_f32_16x16x32_bf16 v[60:63], v[142:145], v[184:187], v[60:63]
	v_mfma_f32_16x16x32_bf16 v[56:59], v[158:161], v[184:187], v[56:59]
	v_mfma_f32_16x16x32_bf16 v[44:47], v[142:145], v[192:195], v[44:47]
	v_mfma_f32_16x16x32_bf16 v[40:43], v[158:161], v[192:195], v[40:43]
	v_mfma_f32_16x16x32_bf16 v[28:31], v[142:145], v[202:205], v[28:31]
	v_mfma_f32_16x16x32_bf16 v[24:27], v[158:161], v[202:205], v[24:27]
	v_mfma_f32_16x16x32_bf16 v[12:15], v[142:145], v[214:217], v[12:15]
	v_mfma_f32_16x16x32_bf16 v[8:11], v[158:161], v[214:217], v[8:11]
	v_mfma_f32_16x16x32_bf16 v[60:63], v[154:157], v[188:191], v[60:63]
	v_mfma_f32_16x16x32_bf16 v[56:59], v[162:165], v[188:191], v[56:59]
	v_mfma_f32_16x16x32_bf16 v[44:47], v[154:157], v[196:199], v[44:47]
	v_mfma_f32_16x16x32_bf16 v[40:43], v[162:165], v[196:199], v[40:43]
	v_mfma_f32_16x16x32_bf16 v[28:31], v[154:157], v[210:213], v[28:31]
	v_mfma_f32_16x16x32_bf16 v[24:27], v[162:165], v[210:213], v[24:27]
	v_mfma_f32_16x16x32_bf16 v[12:15], v[154:157], v[218:221], v[12:15]
	v_mfma_f32_16x16x32_bf16 v[8:11], v[162:165], v[218:221], v[8:11]
	v_mfma_f32_16x16x32_bf16 v[52:55], v[166:169], v[184:187], v[52:55]
	v_mfma_f32_16x16x32_bf16 v[48:51], v[176:179], v[184:187], v[48:51]
	v_mfma_f32_16x16x32_bf16 v[36:39], v[166:169], v[192:195], v[36:39]
	v_mfma_f32_16x16x32_bf16 v[32:35], v[176:179], v[192:195], v[32:35]
	v_mfma_f32_16x16x32_bf16 v[20:23], v[166:169], v[202:205], v[20:23]
	v_mfma_f32_16x16x32_bf16 v[16:19], v[176:179], v[202:205], v[16:19]
	v_mfma_f32_16x16x32_bf16 v[4:7], v[166:169], v[214:217], v[4:7]
	v_mfma_f32_16x16x32_bf16 v[0:3], v[176:179], v[214:217], v[0:3]
	v_mfma_f32_16x16x32_bf16 v[52:55], v[170:173], v[188:191], v[52:55]
	v_mfma_f32_16x16x32_bf16 v[48:51], v[180:183], v[188:191], v[48:51]
	v_mfma_f32_16x16x32_bf16 v[36:39], v[170:173], v[196:199], v[36:39]
	v_mfma_f32_16x16x32_bf16 v[32:35], v[180:183], v[196:199], v[32:35]
	v_mfma_f32_16x16x32_bf16 v[20:23], v[170:173], v[210:213], v[20:23]
	v_mfma_f32_16x16x32_bf16 v[16:19], v[180:183], v[210:213], v[16:19]
	v_mfma_f32_16x16x32_bf16 v[4:7], v[170:173], v[218:221], v[4:7]
	v_mfma_f32_16x16x32_bf16 v[0:3], v[180:183], v[218:221], v[0:3]
	s_barrier
	s_add_i32 s58, s58, 2
	s_add_u32 s34, s34, 0x100
	s_addc_u32 s35, s35, 0
	s_add_u32 s56, s56, 0x100
	s_addc_u32 s57, s57, 0
	s_cmp_gt_u32 s58, 13
	s_cbranch_scc0 .LBB0_854
	s_setprio 0
	s_and_b64 vcc, exec, s[20:21]
	s_cbranch_vccz .LBB0_857
	s_barrier

; #define PG8_STAGE(bufoff, gbase, voff) do { _Pragma("unroll") for (int _i = 0; _i < 2; ++_i) \
;         __builtin_amdgcn_global_load_lds((const unsigned*)((const char*)(gbase) + (voff)[_i]), (PG8_LAS unsigned*)(lds + (bufoff) + ldsw + _i * 8192), 16, 0, 0); } while (0)
; #define PG8_STAGEA(bufoff, gbase, voff) do { _Pragma("unroll") for (int _i = 0; _i < 2; ++_i) \
;         __builtin_amdgcn_global_load_lds((const unsigned*)((const char*)(gbase) + (voff)[_i]), (PG8_LAS unsigned*)(lds + (bufoff) + ldsw + _i * 8192), 16, 0, AUXA); } while (0)
; #define PG8_LDA(dst, b, h) do { _Pragma("unroll") for (int m = 0; m < 4; ++m) _Pragma("unroll") for (int k = 0; k < 2; ++k) dst[m][k] = *(const PG8_LAS bf16x8*)(lds + PG8_SA(b, h) + aoff + m * 2048 + k * 1024); } while (0)
; #define PG8_LDB(dst, b, h) do { _Pragma("unroll") for (int n = 0; n < 2; ++n) _Pragma("unroll") for (int k = 0; k < 2; ++k) dst[n][k] = *(const PG8_LAS bf16x8*)(lds + PG8_SB(b, h) + boff + n * 2048 + k * 1024); } while (0)
; #define PG8_WAIT_V(n) asm volatile("s_waitcnt vmcnt(" #n ")" ::: "memory")
; #define PG8_WAIT_L(n) asm volatile("s_waitcnt lgkmcnt(" #n ")" ::: "memory")
; #define PG8_BAR __builtin_amdgcn_s_barrier()
; #define PG8_SCHED __builtin_amdgcn_sched_barrier(0)
;     ...
;             if constexpr (SP2) {
;             PG8_LDB(B0, 0, 0); PG8_LDB(B1, 0, 1); PG8_SCHED; PG8_LDA(At, 0, 0); PG8_STAGEA(PG8_SA(1, 1), a1 + hstep, voffA);
;             PG8_WAIT_V(8); PG8_WAIT_L(0); PG8_BAR; PG8_MMA(0, 0, At, B0); PG8_MMA(0, 1, At, B1); PG8_BAR; PG8_SCHED;
;             PG8_LDA(At, 0, 1); PG8_STAGE(PG8_SB(0, 0), b2, voffB); PG8_STAGE(PG8_SB(0, 1), b2 + hstepB, voffB); PG8_STAGEA(PG8_SA(0, 0), a2, voffA);
;             PG8_WAIT_V(8); PG8_WAIT_L(0); PG8_BAR; PG8_MMA(1, 0, At, B0); PG8_MMA(1, 1, At, B1); PG8_BAR; PG8_SCHED;
;             PG8_LDB(B0, 1, 0); PG8_LDB(B1, 1, 1); PG8_SCHED; PG8_LDA(At, 1, 0); PG8_STAGEA(PG8_SA(0, 1), a2 + hstep, voffA);
;             PG8_WAIT_V(8); PG8_WAIT_L(0); PG8_BAR; PG8_MMA(0, 0, At, B0); PG8_MMA(0, 1, At, B1); PG8_BAR; PG8_SCHED;
;             PG8_LDA(At, 1, 1); PG8_STAGE(PG8_SB(1, 0), b3, voffB); PG8_STAGE(PG8_SB(1, 1), b3 + hstepB, voffB); PG8_STAGEA(PG8_SA(1, 0), a3, voffA);
;             PG8_WAIT_V(8); PG8_WAIT_L(0); PG8_BAR; PG8_MMA(1, 0, At, B0); PG8_MMA(1, 1, At, B1); PG8_BAR; PG8_SCHED;
.Lsp5_back:
	v_lshl_add_u64 v[206:207], v[142:143], 0, s[36:37]
	s_add_i32 m0, s17, 0xc000
	ds_read_b128 v[184:187], v149
	ds_read_b128 v[188:191], v149 offset:1024
	ds_read_b128 v[192:195], v149 offset:2048
	ds_read_b128 v[196:199], v149 offset:3072
	ds_read_b128 v[202:205], v149 offset:4096
	ds_read_b128 v[210:213], v149 offset:5120
	ds_read_b128 v[214:217], v149 offset:6144
	ds_read_b128 v[218:221], v149 offset:7168
	global_load_lds_dwordx4 v[206:207], off
	v_lshl_add_u64 v[206:207], v[144:145], 0, s[36:37]
	s_add_i32 m0, s17, 0xe000
	s_nop 0
	global_load_lds_dwordx4 v[206:207], off
	s_waitcnt vmcnt(8)
	s_waitcnt lgkmcnt(0)
	s_barrier
	v_mfma_f32_16x16x32_bf16 v[124:127], v[150:153], v[184:187], v[124:127]
	v_mfma_f32_16x16x32_bf16 v[120:123], v[158:161], v[184:187], v[120:123]
	v_mfma_f32_16x16x32_bf16 v[108:111], v[150:153], v[192:195], v[108:111]
	v_mfma_f32_16x16x32_bf16 v[104:107], v[158:161], v[192:195], v[104:107]
	v_mfma_f32_16x16x32_bf16 v[92:95], v[150:153], v[202:205], v[92:95]
	v_mfma_f32_16x16x32_bf16 v[88:91], v[158:161], v[202:205], v[88:91]
	v_mfma_f32_16x16x32_bf16 v[76:79], v[150:153], v[214:217], v[76:79]
	v_mfma_f32_16x16x32_bf16 v[72:75], v[158:161], v[214:217], v[72:75]
	v_mfma_f32_16x16x32_bf16 v[124:127], v[154:157], v[188:191], v[124:127]
	v_mfma_f32_16x16x32_bf16 v[120:123], v[162:165], v[188:191], v[120:123]
	v_mfma_f32_16x16x32_bf16 v[108:111], v[154:157], v[196:199], v[108:111]
	v_mfma_f32_16x16x32_bf16 v[104:107], v[162:165], v[196:199], v[104:107]
	v_mfma_f32_16x16x32_bf16 v[92:95], v[154:157], v[210:213], v[92:95]
	v_mfma_f32_16x16x32_bf16 v[88:91], v[162:165], v[210:213], v[88:91]
	v_mfma_f32_16x16x32_bf16 v[76:79], v[154:157], v[218:221], v[76:79]
	v_mfma_f32_16x16x32_bf16 v[72:75], v[162:165], v[218:221], v[72:75]
	v_mfma_f32_16x16x32_bf16 v[116:119], v[166:169], v[184:187], v[116:119]
	v_mfma_f32_16x16x32_bf16 v[112:115], v[176:179], v[184:187], v[112:115]
	v_mfma_f32_16x16x32_bf16 v[100:103], v[166:169], v[192:195], v[100:103]
	v_mfma_f32_16x16x32_bf16 v[96:99], v[176:179], v[192:195], v[96:99]
	v_mfma_f32_16x16x32_bf16 v[84:87], v[166:169], v[202:205], v[84:87]
	v_mfma_f32_16x16x32_bf16 v[80:83], v[176:179], v[202:205], v[80:83]
	v_mfma_f32_16x16x32_bf16 v[68:71], v[166:169], v[214:217], v[68:71]
	v_mfma_f32_16x16x32_bf16 v[64:67], v[176:179], v[214:217], v[64:67]
	v_mfma_f32_16x16x32_bf16 v[116:119], v[170:173], v[188:191], v[116:119]
	v_mfma_f32_16x16x32_bf16 v[112:115], v[180:183], v[188:191], v[112:115]
	v_mfma_f32_16x16x32_bf16 v[100:103], v[170:173], v[196:199], v[100:103]
	v_mfma_f32_16x16x32_bf16 v[96:99], v[180:183], v[196:199], v[96:99]
	v_mfma_f32_16x16x32_bf16 v[84:87], v[170:173], v[210:213], v[84:87]
	v_mfma_f32_16x16x32_bf16 v[80:83], v[180:183], v[210:213], v[80:83]
	v_mfma_f32_16x16x32_bf16 v[68:71], v[170:173], v[218:221], v[68:71]
	v_mfma_f32_16x16x32_bf16 v[64:67], v[180:183], v[218:221], v[64:67]
	s_barrier
	s_add_i32 s59, s12, s67
	v_lshl_add_u64 v[206:207], s[38:39], 0, v[132:133]
	s_mov_b32 m0, s59
	ds_read_b128 v[184:187], v149 offset:16384
	ds_read_b128 v[188:191], v149 offset:17408
	ds_read_b128 v[192:195], v149 offset:18432
	ds_read_b128 v[196:199], v149 offset:19456
	ds_read_b128 v[202:205], v149 offset:20480
	ds_read_b128 v[210:213], v149 offset:21504
	ds_read_b128 v[214:217], v149 offset:22528
	ds_read_b128 v[218:221], v149 offset:23552
	global_load_lds_dwordx4 v[206:207], off
	s_add_i32 m0, s59, 0x2000
	s_add_u32 s70, s38, 0x10000
	v_lshl_add_u64 v[222:223], s[38:39], 0, v[128:129]
	s_addc_u32 s71, s39, 0
	s_add_i32 s59, s50, s67
	global_load_lds_dwordx4 v[222:223], off
	v_lshl_add_u64 v[224:225], s[70:71], 0, v[132:133]
	s_mov_b32 m0, s59
	v_lshl_add_u64 v[226:227], s[40:41], 0, v[130:131]
	global_load_lds_dwordx4 v[224:225], off
	v_lshl_add_u64 v[224:225], s[70:71], 0, v[128:129]
	s_add_i32 m0, s59, 0x2000
	s_nop 0
	global_load_lds_dwordx4 v[224:225], off
	v_lshl_add_u64 v[224:225], s[40:41], 0, v[134:135]
	s_mov_b32 m0, s17
	s_nop 0
	global_load_lds_dwordx4 v[224:225], off
	s_mov_b32 m0, s43
	s_nop 0
	global_load_lds_dwordx4 v[226:227], off
	s_waitcnt vmcnt(8)
	s_waitcnt lgkmcnt(0)
	s_barrier
	v_mfma_f32_16x16x32_bf16 v[60:63], v[150:153], v[184:187], v[60:63]
	v_mfma_f32_16x16x32_bf16 v[56:59], v[158:161], v[184:187], v[56:59]
	v_mfma_f32_16x16x32_bf16 v[44:47], v[150:153], v[192:195], v[44:47]
	v_mfma_f32_16x16x32_bf16 v[40:43], v[158:161], v[192:195], v[40:43]
	v_mfma_f32_16x16x32_bf16 v[28:31], v[150:153], v[202:205], v[28:31]
	v_mfma_f32_16x16x32_bf16 v[24:27], v[158:161], v[202:205], v[24:27]
	v_mfma_f32_16x16x32_bf16 v[12:15], v[150:153], v[214:217], v[12:15]
	v_mfma_f32_16x16x32_bf16 v[8:11], v[158:161], v[214:217], v[8:11]
	v_mfma_f32_16x16x32_bf16 v[60:63], v[154:157], v[188:191], v[60:63]
	v_mfma_f32_16x16x32_bf16 v[56:59], v[162:165], v[188:191], v[56:59]
	v_mfma_f32_16x16x32_bf16 v[44:47], v[154:157], v[196:199], v[44:47]
	v_mfma_f32_16x16x32_bf16 v[40:43], v[162:165], v[196:199], v[40:43]
	v_mfma_f32_16x16x32_bf16 v[28:31], v[154:157], v[210:213], v[28:31]
	v_mfma_f32_16x16x32_bf16 v[24:27], v[162:165], v[210:213], v[24:27]
	v_mfma_f32_16x16x32_bf16 v[12:15], v[154:157], v[218:221], v[12:15]
	v_mfma_f32_16x16x32_bf16 v[8:11], v[162:165], v[218:221], v[8:11]
	v_mfma_f32_16x16x32_bf16 v[52:55], v[166:169], v[184:187], v[52:55]
	v_mfma_f32_16x16x32_bf16 v[48:51], v[176:179], v[184:187], v[48:51]
	v_mfma_f32_16x16x32_bf16 v[36:39], v[166:169], v[192:195], v[36:39]
	v_mfma_f32_16x16x32_bf16 v[32:35], v[176:179], v[192:195], v[32:35]
	v_mfma_f32_16x16x32_bf16 v[20:23], v[166:169], v[202:205], v[20:23]
	v_mfma_f32_16x16x32_bf16 v[16:19], v[176:179], v[202:205], v[16:19]
	v_mfma_f32_16x16x32_bf16 v[4:7], v[166:169], v[214:217], v[4:7]
	v_mfma_f32_16x16x32_bf16 v[0:3], v[176:179], v[214:217], v[0:3]
	v_mfma_f32_16x16x32_bf16 v[52:55], v[170:173], v[188:191], v[52:55]
	v_mfma_f32_16x16x32_bf16 v[48:51], v[180:183], v[188:191], v[48:51]
	v_mfma_f32_16x16x32_bf16 v[36:39], v[170:173], v[196:199], v[36:39]
	v_mfma_f32_16x16x32_bf16 v[32:35], v[180:183], v[196:199], v[32:35]
	v_mfma_f32_16x16x32_bf16 v[20:23], v[170:173], v[210:213], v[20:23]
	v_mfma_f32_16x16x32_bf16 v[16:19], v[180:183], v[210:213], v[16:19]
	v_mfma_f32_16x16x32_bf16 v[4:7], v[170:173], v[218:221], v[4:7]
	v_mfma_f32_16x16x32_bf16 v[0:3], v[180:183], v[218:221], v[0:3]
	s_barrier
; #define PG8_STAGE(bufoff, gbase, voff) do { _Pragma("unroll") for (int _i = 0; _i < 2; ++_i) \
;         __builtin_amdgcn_global_load_lds((const unsigned*)((const char*)(gbase) + (voff)[_i]), (PG8_LAS unsigned*)(lds + (bufoff) + ldsw + _i * 8192), 16, 0, 0); } while (0)
; #define PG8_STAGEA(bufoff, gbase, voff) do { _Pragma("unroll") for (int _i = 0; _i < 2; ++_i) \
;         __builtin_amdgcn_global_load_lds((const unsigned*)((const char*)(gbase) + (voff)[_i]), (PG8_LAS unsigned*)(lds + (bufoff) + ldsw + _i * 8192), 16, 0, AUXA); } while (0)
; #define PG8_LDA(dst, b, h) do { _Pragma("unroll") for (int m = 0; m < 4; ++m) _Pragma("unroll") for (int k = 0; k < 2; ++k) dst[m][k] = *(const PG8_LAS bf16x8*)(lds + PG8_SA(b, h) + aoff + m * 2048 + k * 1024); } while (0)
; #define PG8_LDB(dst, b, h) do { _Pragma("unroll") for (int n = 0; n < 2; ++n) _Pragma("unroll") for (int k = 0; k < 2; ++k) dst[n][k] = *(const PG8_LAS bf16x8*)(lds + PG8_SB(b, h) + boff + n * 2048 + k * 1024); } while (0)
; #define PG8_WAIT_V(n) asm volatile("s_waitcnt vmcnt(" #n ")" ::: "memory")
; #define PG8_WAIT_L(n) asm volatile("s_waitcnt lgkmcnt(" #n ")" ::: "memory")
; #define PG8_BAR __builtin_amdgcn_s_barrier()
; #define PG8_SCHED __builtin_amdgcn_sched_barrier(0)
;     ...
;             if constexpr (SP2) {
;             PG8_LDB(B0, 0, 0); PG8_LDB(B1, 0, 1); PG8_SCHED; PG8_LDA(At, 0, 0); PG8_STAGEA(PG8_SA(1, 1), a1 + hstep, voffA);
;             PG8_WAIT_V(8); PG8_WAIT_L(0); PG8_BAR; PG8_MMA(0, 0, At, B0); PG8_MMA(0, 1, At, B1); PG8_BAR; PG8_SCHED;
;             PG8_LDA(At, 0, 1); PG8_STAGE(PG8_SB(0, 0), b2, voffB); PG8_STAGE(PG8_SB(0, 1), b2 + hstepB, voffB); PG8_STAGEA(PG8_SA(0, 0), a2, voffA);
;             PG8_WAIT_V(8); PG8_WAIT_L(0); PG8_BAR; PG8_MMA(1, 0, At, B0); PG8_MMA(1, 1, At, B1); PG8_BAR; PG8_SCHED;
;             PG8_LDB(B0, 1, 0); PG8_LDB(B1, 1, 1); PG8_SCHED; PG8_LDA(At, 1, 0); PG8_STAGEA(PG8_SA(0, 1), a2 + hstep, voffA);
;             PG8_WAIT_V(8); PG8_WAIT_L(0); PG8_BAR; PG8_MMA(0, 0, At, B0); PG8_MMA(0, 1, At, B1); PG8_BAR; PG8_SCHED;
;             PG8_LDA(At, 1, 1); PG8_STAGE(PG8_SB(1, 0), b3, voffB); PG8_STAGE(PG8_SB(1, 1), b3 + hstepB, voffB); PG8_STAGEA(PG8_SA(1, 0), a3, voffA);
;             PG8_WAIT_V(8); PG8_WAIT_L(0); PG8_BAR; PG8_MMA(1, 0, At, B0); PG8_MMA(1, 1, At, B1); PG8_BAR; PG8_SCHED;
;     ...
;         if constexpr (ALIGN_EPI) { if (wr == 0) PG8_BAR; }
	s_add_i32 s59, 0, 0x18000
	s_add_i32 s70, 0, 0x1c000
	v_add_u32_e32 v162, s59, v148
	v_add_u32_e32 v174, s70, v148
	ds_read_b128 v[150:153], v162
	ds_read_b128 v[154:157], v162 offset:1024
	ds_read_b128 v[158:161], v162 offset:2048
	ds_read_b128 v[162:165], v162 offset:3072
	ds_read_b128 v[166:169], v174
	ds_read_b128 v[170:173], v174 offset:1024
	ds_read_b128 v[176:179], v174 offset:2048
	ds_read_b128 v[180:183], v174 offset:3072
	s_add_u32 s40, s40, 0x40000
	s_addc_u32 s41, s41, 0
	s_mov_b32 m0, s44
	v_lshl_add_u64 v[228:229], s[40:41], 0, v[134:135]
	ds_read_b128 v[184:187], v149 offset:32768
	ds_read_b128 v[188:191], v149 offset:33792
	ds_read_b128 v[192:195], v149 offset:34816
	ds_read_b128 v[196:199], v149 offset:35840
	ds_read_b128 v[202:205], v149 offset:36864
	ds_read_b128 v[210:213], v149 offset:37888
	ds_read_b128 v[214:217], v149 offset:38912
	ds_read_b128 v[218:221], v149 offset:39936
	global_load_lds_dwordx4 v[228:229], off
	v_lshl_add_u64 v[228:229], s[40:41], 0, v[130:131]
	s_mov_b32 m0, s45
	s_nop 0
	global_load_lds_dwordx4 v[228:229], off
	s_waitcnt vmcnt(8)
	s_waitcnt lgkmcnt(0)
	s_barrier
	v_mfma_f32_16x16x32_bf16 v[124:127], v[150:153], v[184:187], v[124:127]
	v_mfma_f32_16x16x32_bf16 v[120:123], v[158:161], v[184:187], v[120:123]
	v_mfma_f32_16x16x32_bf16 v[108:111], v[150:153], v[192:195], v[108:111]
	v_mfma_f32_16x16x32_bf16 v[104:107], v[158:161], v[192:195], v[104:107]
	v_mfma_f32_16x16x32_bf16 v[92:95], v[150:153], v[202:205], v[92:95]
	v_mfma_f32_16x16x32_bf16 v[88:91], v[158:161], v[202:205], v[88:91]
	v_mfma_f32_16x16x32_bf16 v[76:79], v[150:153], v[214:217], v[76:79]
	v_mfma_f32_16x16x32_bf16 v[72:75], v[158:161], v[214:217], v[72:75]
	v_mfma_f32_16x16x32_bf16 v[124:127], v[154:157], v[188:191], v[124:127]
	v_mfma_f32_16x16x32_bf16 v[120:123], v[162:165], v[188:191], v[120:123]
	v_mfma_f32_16x16x32_bf16 v[108:111], v[154:157], v[196:199], v[108:111]
	v_mfma_f32_16x16x32_bf16 v[104:107], v[162:165], v[196:199], v[104:107]
	v_mfma_f32_16x16x32_bf16 v[92:95], v[154:157], v[210:213], v[92:95]
	v_mfma_f32_16x16x32_bf16 v[88:91], v[162:165], v[210:213], v[88:91]
	v_mfma_f32_16x16x32_bf16 v[76:79], v[154:157], v[218:221], v[76:79]
	v_mfma_f32_16x16x32_bf16 v[72:75], v[162:165], v[218:221], v[72:75]
	v_mfma_f32_16x16x32_bf16 v[116:119], v[166:169], v[184:187], v[116:119]
	v_mfma_f32_16x16x32_bf16 v[112:115], v[176:179], v[184:187], v[112:115]
	v_mfma_f32_16x16x32_bf16 v[100:103], v[166:169], v[192:195], v[100:103]
	v_mfma_f32_16x16x32_bf16 v[96:99], v[176:179], v[192:195], v[96:99]
	v_mfma_f32_16x16x32_bf16 v[84:87], v[166:169], v[202:205], v[84:87]
	v_mfma_f32_16x16x32_bf16 v[80:83], v[176:179], v[202:205], v[80:83]
	v_mfma_f32_16x16x32_bf16 v[68:71], v[166:169], v[214:217], v[68:71]
	v_mfma_f32_16x16x32_bf16 v[64:67], v[176:179], v[214:217], v[64:67]
	v_mfma_f32_16x16x32_bf16 v[116:119], v[170:173], v[188:191], v[116:119]
	v_mfma_f32_16x16x32_bf16 v[112:115], v[180:183], v[188:191], v[112:115]
	v_mfma_f32_16x16x32_bf16 v[100:103], v[170:173], v[196:199], v[100:103]
	v_mfma_f32_16x16x32_bf16 v[96:99], v[180:183], v[196:199], v[96:99]
	v_mfma_f32_16x16x32_bf16 v[84:87], v[170:173], v[210:213], v[84:87]
	v_mfma_f32_16x16x32_bf16 v[80:83], v[180:183], v[210:213], v[80:83]
	v_mfma_f32_16x16x32_bf16 v[68:71], v[170:173], v[218:221], v[68:71]
	v_mfma_f32_16x16x32_bf16 v[64:67], v[180:183], v[218:221], v[64:67]
	s_barrier
	s_add_i32 s40, s59, s67
	v_lshl_add_u64 v[206:207], v[206:207], 0, s[20:21]
	s_mov_b32 m0, s40
	ds_read_b128 v[184:187], v149 offset:49152
	ds_read_b128 v[188:191], v149 offset:50176
	ds_read_b128 v[192:195], v149 offset:51200
	ds_read_b128 v[196:199], v149 offset:52224
	ds_read_b128 v[202:205], v149 offset:53248
	ds_read_b128 v[210:213], v149 offset:54272
	ds_read_b128 v[214:217], v149 offset:55296
	ds_read_b128 v[218:221], v149 offset:56320
	global_load_lds_dwordx4 v[206:207], off
	s_add_i32 m0, s40, 0x2000
	s_add_u32 s38, s38, 0x10080
	v_lshl_add_u64 v[206:207], v[222:223], 0, s[20:21]
	s_addc_u32 s39, s39, 0
	s_add_i32 s40, s70, s67
	global_load_lds_dwordx4 v[206:207], off
	v_lshl_add_u64 v[206:207], s[38:39], 0, v[132:133]
	s_mov_b32 m0, s40
	s_nop 0
	global_load_lds_dwordx4 v[206:207], off
	v_lshl_add_u64 v[206:207], s[38:39], 0, v[128:129]
	s_add_i32 m0, s40, 0x2000
	s_nop 0
	global_load_lds_dwordx4 v[206:207], off
	v_lshl_add_u64 v[206:207], v[224:225], 0, s[20:21]
	s_mov_b32 m0, s46
	s_nop 0
	global_load_lds_dwordx4 v[206:207], off
	v_lshl_add_u64 v[206:207], v[226:227], 0, s[20:21]
	s_mov_b32 m0, s47
	s_nop 0
	global_load_lds_dwordx4 v[206:207], off
	s_waitcnt vmcnt(8)
	s_waitcnt lgkmcnt(0)
	s_barrier
	v_mfma_f32_16x16x32_bf16 v[60:63], v[150:153], v[184:187], v[60:63]
	v_mfma_f32_16x16x32_bf16 v[56:59], v[158:161], v[184:187], v[56:59]
	v_mfma_f32_16x16x32_bf16 v[44:47], v[150:153], v[192:195], v[44:47]
	v_mfma_f32_16x16x32_bf16 v[40:43], v[158:161], v[192:195], v[40:43]
	v_mfma_f32_16x16x32_bf16 v[28:31], v[150:153], v[202:205], v[28:31]
	v_mfma_f32_16x16x32_bf16 v[24:27], v[158:161], v[202:205], v[24:27]
	v_mfma_f32_16x16x32_bf16 v[12:15], v[150:153], v[214:217], v[12:15]
	v_mfma_f32_16x16x32_bf16 v[8:11], v[158:161], v[214:217], v[8:11]
	v_mfma_f32_16x16x32_bf16 v[60:63], v[154:157], v[188:191], v[60:63]
	v_mfma_f32_16x16x32_bf16 v[56:59], v[162:165], v[188:191], v[56:59]
	v_mfma_f32_16x16x32_bf16 v[44:47], v[154:157], v[196:199], v[44:47]
	v_mfma_f32_16x16x32_bf16 v[40:43], v[162:165], v[196:199], v[40:43]
	v_mfma_f32_16x16x32_bf16 v[28:31], v[154:157], v[210:213], v[28:31]
	v_mfma_f32_16x16x32_bf16 v[24:27], v[162:165], v[210:213], v[24:27]
	v_mfma_f32_16x16x32_bf16 v[12:15], v[154:157], v[218:221], v[12:15]
	v_mfma_f32_16x16x32_bf16 v[8:11], v[162:165], v[218:221], v[8:11]
	v_mfma_f32_16x16x32_bf16 v[52:55], v[166:169], v[184:187], v[52:55]
	v_mfma_f32_16x16x32_bf16 v[48:51], v[176:179], v[184:187], v[48:51]
	v_mfma_f32_16x16x32_bf16 v[36:39], v[166:169], v[192:195], v[36:39]
	v_mfma_f32_16x16x32_bf16 v[32:35], v[176:179], v[192:195], v[32:35]
	v_mfma_f32_16x16x32_bf16 v[20:23], v[166:169], v[202:205], v[20:23]
	v_mfma_f32_16x16x32_bf16 v[16:19], v[176:179], v[202:205], v[16:19]
	v_mfma_f32_16x16x32_bf16 v[4:7], v[166:169], v[214:217], v[4:7]
	v_mfma_f32_16x16x32_bf16 v[0:3], v[176:179], v[214:217], v[0:3]
	v_mfma_f32_16x16x32_bf16 v[52:55], v[170:173], v[188:191], v[52:55]
	v_mfma_f32_16x16x32_bf16 v[48:51], v[180:183], v[188:191], v[48:51]
	v_mfma_f32_16x16x32_bf16 v[36:39], v[170:173], v[196:199], v[36:39]
	v_mfma_f32_16x16x32_bf16 v[32:35], v[180:183], v[196:199], v[32:35]
	v_mfma_f32_16x16x32_bf16 v[20:23], v[170:173], v[210:213], v[20:23]
	v_mfma_f32_16x16x32_bf16 v[16:19], v[180:183], v[210:213], v[16:19]
	v_mfma_f32_16x16x32_bf16 v[4:7], v[170:173], v[218:221], v[4:7]
	v_mfma_f32_16x16x32_bf16 v[0:3], v[180:183], v[218:221], v[0:3]
	s_barrier
	s_add_i32 s58, s58, 2
	s_add_u32 s36, s36, 0x100
	s_addc_u32 s37, s37, 0
	s_cmp_gt_u32 s58, 13
	s_cbranch_scc0 .LBB0_888
	s_setprio 0
	s_and_b64 vcc, exec, s[22:23]
	s_cbranch_vccz .LBB0_891
	s_barrier

; #define PG8_STAGE(bufoff, gbase, voff) do { _Pragma("unroll") for (int _i = 0; _i < 2; ++_i) \
;         __builtin_amdgcn_global_load_lds((const unsigned*)((const char*)(gbase) + (voff)[_i]), (PG8_LAS unsigned*)(lds + (bufoff) + ldsw + _i * 8192), 16, 0, 0); } while (0)
; #define PG8_STAGEA(bufoff, gbase, voff) do { _Pragma("unroll") for (int _i = 0; _i < 2; ++_i) \
;         __builtin_amdgcn_global_load_lds((const unsigned*)((const char*)(gbase) + (voff)[_i]), (PG8_LAS unsigned*)(lds + (bufoff) + ldsw + _i * 8192), 16, 0, AUXA); } while (0)
; #define PG8_LDA(dst, b, h) do { _Pragma("unroll") for (int m = 0; m < 4; ++m) _Pragma("unroll") for (int k = 0; k < 2; ++k) dst[m][k] = *(const PG8_LAS bf16x8*)(lds + PG8_SA(b, h) + aoff + m * 2048 + k * 1024); } while (0)
; #define PG8_LDB(dst, b, h) do { _Pragma("unroll") for (int n = 0; n < 2; ++n) _Pragma("unroll") for (int k = 0; k < 2; ++k) dst[n][k] = *(const PG8_LAS bf16x8*)(lds + PG8_SB(b, h) + boff + n * 2048 + k * 1024); } while (0)
; #define PG8_WAIT_V(n) asm volatile("s_waitcnt vmcnt(" #n ")" ::: "memory")
; #define PG8_WAIT_L(n) asm volatile("s_waitcnt lgkmcnt(" #n ")" ::: "memory")
; #define PG8_BAR __builtin_amdgcn_s_barrier()
; #define PG8_SCHED __builtin_amdgcn_sched_barrier(0)
;     ...
;             if constexpr (SP2) {
;             PG8_LDB(B0, 0, 0); PG8_LDB(B1, 0, 1); PG8_SCHED; PG8_LDA(At, 0, 0); PG8_STAGEA(PG8_SA(1, 1), a1 + hstep, voffA);
;             PG8_WAIT_V(8); PG8_WAIT_L(0); PG8_BAR; PG8_MMA(0, 0, At, B0); PG8_MMA(0, 1, At, B1); PG8_BAR; PG8_SCHED;
;             PG8_LDA(At, 0, 1); PG8_STAGE(PG8_SB(0, 0), b2, voffB); PG8_STAGE(PG8_SB(0, 1), b2 + hstepB, voffB); PG8_STAGEA(PG8_SA(0, 0), a2, voffA);
;             PG8_WAIT_V(8); PG8_WAIT_L(0); PG8_BAR; PG8_MMA(1, 0, At, B0); PG8_MMA(1, 1, At, B1); PG8_BAR; PG8_SCHED;
;             PG8_LDB(B0, 1, 0); PG8_LDB(B1, 1, 1); PG8_SCHED; PG8_LDA(At, 1, 0); PG8_STAGEA(PG8_SA(0, 1), a2 + hstep, voffA);
;             PG8_WAIT_V(8); PG8_WAIT_L(0); PG8_BAR; PG8_MMA(0, 0, At, B0); PG8_MMA(0, 1, At, B1); PG8_BAR; PG8_SCHED;
;             PG8_LDA(At, 1, 1); PG8_STAGE(PG8_SB(1, 0), b3, voffB); PG8_STAGE(PG8_SB(1, 1), b3 + hstepB, voffB); PG8_STAGEA(PG8_SA(1, 0), a3, voffA);
;             PG8_WAIT_V(8); PG8_WAIT_L(0); PG8_BAR; PG8_MMA(1, 0, At, B0); PG8_MMA(1, 1, At, B1); PG8_BAR; PG8_SCHED;
.Lfiw_p6_1:
	s_waitcnt lgkmcnt(0)
	s_barrier
	v_mfma_f32_16x16x32_bf16 v[124:127], v[144:147], v[184:187], v[124:127]
	v_mfma_f32_16x16x32_bf16 v[120:123], v[152:155], v[184:187], v[120:123]
	v_mfma_f32_16x16x32_bf16 v[108:111], v[144:147], v[192:195], v[108:111]
	v_mfma_f32_16x16x32_bf16 v[104:107], v[152:155], v[192:195], v[104:107]
	v_mfma_f32_16x16x32_bf16 v[92:95], v[144:147], v[202:205], v[92:95]
	v_mfma_f32_16x16x32_bf16 v[88:91], v[152:155], v[202:205], v[88:91]
	v_mfma_f32_16x16x32_bf16 v[76:79], v[144:147], v[214:217], v[76:79]
	v_mfma_f32_16x16x32_bf16 v[72:75], v[152:155], v[214:217], v[72:75]
	v_mfma_f32_16x16x32_bf16 v[124:127], v[148:151], v[188:191], v[124:127]
	v_mfma_f32_16x16x32_bf16 v[120:123], v[156:159], v[188:191], v[120:123]
	v_mfma_f32_16x16x32_bf16 v[108:111], v[148:151], v[196:199], v[108:111]
	v_mfma_f32_16x16x32_bf16 v[104:107], v[156:159], v[196:199], v[104:107]
	v_mfma_f32_16x16x32_bf16 v[92:95], v[148:151], v[210:213], v[92:95]
	v_mfma_f32_16x16x32_bf16 v[88:91], v[156:159], v[210:213], v[88:91]
	v_mfma_f32_16x16x32_bf16 v[76:79], v[148:151], v[218:221], v[76:79]
	v_mfma_f32_16x16x32_bf16 v[72:75], v[156:159], v[218:221], v[72:75]
	v_mfma_f32_16x16x32_bf16 v[116:119], v[160:163], v[184:187], v[116:119]
	v_mfma_f32_16x16x32_bf16 v[112:115], v[176:179], v[184:187], v[112:115]
	v_mfma_f32_16x16x32_bf16 v[100:103], v[160:163], v[192:195], v[100:103]
	v_mfma_f32_16x16x32_bf16 v[96:99], v[176:179], v[192:195], v[96:99]
	v_mfma_f32_16x16x32_bf16 v[84:87], v[160:163], v[202:205], v[84:87]
	v_mfma_f32_16x16x32_bf16 v[80:83], v[176:179], v[202:205], v[80:83]
	v_mfma_f32_16x16x32_bf16 v[68:71], v[160:163], v[214:217], v[68:71]
	v_mfma_f32_16x16x32_bf16 v[64:67], v[176:179], v[214:217], v[64:67]
	v_mfma_f32_16x16x32_bf16 v[116:119], v[164:167], v[188:191], v[116:119]
	v_mfma_f32_16x16x32_bf16 v[112:115], v[180:183], v[188:191], v[112:115]
	v_mfma_f32_16x16x32_bf16 v[100:103], v[164:167], v[196:199], v[100:103]
	v_mfma_f32_16x16x32_bf16 v[96:99], v[180:183], v[196:199], v[96:99]
	v_mfma_f32_16x16x32_bf16 v[84:87], v[164:167], v[210:213], v[84:87]
	v_mfma_f32_16x16x32_bf16 v[80:83], v[180:183], v[210:213], v[80:83]
	v_mfma_f32_16x16x32_bf16 v[68:71], v[164:167], v[218:221], v[68:71]
	v_mfma_f32_16x16x32_bf16 v[64:67], v[180:183], v[218:221], v[64:67]
	s_barrier
	s_add_i32 s73, s54, s67
	v_lshl_add_u64 v[206:207], s[40:41], 0, v[132:133]
	s_mov_b32 m0, s73
	ds_read_b128 v[184:187], v172 offset:16384
	ds_read_b128 v[188:191], v172 offset:17408
	ds_read_b128 v[192:195], v172 offset:18432
	ds_read_b128 v[196:199], v172 offset:19456
	ds_read_b128 v[202:205], v172 offset:20480
	ds_read_b128 v[210:213], v172 offset:21504
	ds_read_b128 v[214:217], v172 offset:22528
	ds_read_b128 v[218:221], v172 offset:23552
	global_load_lds_dwordx4 v[206:207], off
	s_add_i32 m0, s73, 0x2000
	s_add_u32 s74, s40, 0x10000
	v_lshl_add_u64 v[222:223], s[40:41], 0, v[128:129]
	s_addc_u32 s75, s41, 0
	s_add_i32 s73, s55, s67
	global_load_lds_dwordx4 v[222:223], off
	v_lshl_add_u64 v[224:225], s[74:75], 0, v[132:133]
	s_mov_b32 m0, s73
	v_lshl_add_u64 v[226:227], s[42:43], 0, v[130:131]
	global_load_lds_dwordx4 v[224:225], off
	v_lshl_add_u64 v[224:225], s[74:75], 0, v[128:129]
	s_add_i32 m0, s73, 0x2000
	s_nop 0
	global_load_lds_dwordx4 v[224:225], off
	v_lshl_add_u64 v[224:225], s[42:43], 0, v[134:135]
	s_mov_b32 m0, s37
	s_nop 0
	global_load_lds_dwordx4 v[224:225], off
	s_mov_b32 m0, s46
	s_nop 0
	global_load_lds_dwordx4 v[226:227], off
	s_cmp_lg_u32 s99, 0
	s_cbranch_scc1 .Lfiw_p6_0
	s_waitcnt vmcnt(8)
.Lfiw_p6_0:
	s_waitcnt lgkmcnt(0)
	s_barrier
	v_mfma_f32_16x16x32_bf16 v[60:63], v[144:147], v[184:187], v[60:63]
	v_mfma_f32_16x16x32_bf16 v[56:59], v[152:155], v[184:187], v[56:59]
	v_mfma_f32_16x16x32_bf16 v[44:47], v[144:147], v[192:195], v[44:47]
	v_mfma_f32_16x16x32_bf16 v[40:43], v[152:155], v[192:195], v[40:43]
	v_mfma_f32_16x16x32_bf16 v[28:31], v[144:147], v[202:205], v[28:31]
	v_mfma_f32_16x16x32_bf16 v[24:27], v[152:155], v[202:205], v[24:27]
	v_mfma_f32_16x16x32_bf16 v[12:15], v[144:147], v[214:217], v[12:15]
	v_mfma_f32_16x16x32_bf16 v[8:11], v[152:155], v[214:217], v[8:11]
	v_mfma_f32_16x16x32_bf16 v[60:63], v[148:151], v[188:191], v[60:63]
	v_mfma_f32_16x16x32_bf16 v[56:59], v[156:159], v[188:191], v[56:59]
	v_mfma_f32_16x16x32_bf16 v[44:47], v[148:151], v[196:199], v[44:47]
	v_mfma_f32_16x16x32_bf16 v[40:43], v[156:159], v[196:199], v[40:43]
	v_mfma_f32_16x16x32_bf16 v[28:31], v[148:151], v[210:213], v[28:31]
	v_mfma_f32_16x16x32_bf16 v[24:27], v[156:159], v[210:213], v[24:27]
	v_mfma_f32_16x16x32_bf16 v[12:15], v[148:151], v[218:221], v[12:15]
	v_mfma_f32_16x16x32_bf16 v[8:11], v[156:159], v[218:221], v[8:11]
	v_mfma_f32_16x16x32_bf16 v[52:55], v[160:163], v[184:187], v[52:55]
	v_mfma_f32_16x16x32_bf16 v[48:51], v[176:179], v[184:187], v[48:51]
	v_mfma_f32_16x16x32_bf16 v[36:39], v[160:163], v[192:195], v[36:39]
	v_mfma_f32_16x16x32_bf16 v[32:35], v[176:179], v[192:195], v[32:35]
	v_mfma_f32_16x16x32_bf16 v[20:23], v[160:163], v[202:205], v[20:23]
	v_mfma_f32_16x16x32_bf16 v[16:19], v[176:179], v[202:205], v[16:19]
	v_mfma_f32_16x16x32_bf16 v[4:7], v[160:163], v[214:217], v[4:7]
	v_mfma_f32_16x16x32_bf16 v[0:3], v[176:179], v[214:217], v[0:3]
	v_mfma_f32_16x16x32_bf16 v[52:55], v[164:167], v[188:191], v[52:55]
	v_mfma_f32_16x16x32_bf16 v[48:51], v[180:183], v[188:191], v[48:51]
	v_mfma_f32_16x16x32_bf16 v[36:39], v[164:167], v[196:199], v[36:39]
	v_mfma_f32_16x16x32_bf16 v[32:35], v[180:183], v[196:199], v[32:35]
	v_mfma_f32_16x16x32_bf16 v[20:23], v[164:167], v[210:213], v[20:23]
	v_mfma_f32_16x16x32_bf16 v[16:19], v[180:183], v[210:213], v[16:19]
	v_mfma_f32_16x16x32_bf16 v[4:7], v[164:167], v[218:221], v[4:7]
	v_mfma_f32_16x16x32_bf16 v[0:3], v[180:183], v[218:221], v[0:3]
	s_barrier
; #define PG8_STAGE(bufoff, gbase, voff) do { _Pragma("unroll") for (int _i = 0; _i < 2; ++_i) \
;         __builtin_amdgcn_global_load_lds((const unsigned*)((const char*)(gbase) + (voff)[_i]), (PG8_LAS unsigned*)(lds + (bufoff) + ldsw + _i * 8192), 16, 0, 0); } while (0)
; #define PG8_STAGEA(bufoff, gbase, voff) do { _Pragma("unroll") for (int _i = 0; _i < 2; ++_i) \
;         __builtin_amdgcn_global_load_lds((const unsigned*)((const char*)(gbase) + (voff)[_i]), (PG8_LAS unsigned*)(lds + (bufoff) + ldsw + _i * 8192), 16, 0, AUXA); } while (0)
; #define PG8_LDA(dst, b, h) do { _Pragma("unroll") for (int m = 0; m < 4; ++m) _Pragma("unroll") for (int k = 0; k < 2; ++k) dst[m][k] = *(const PG8_LAS bf16x8*)(lds + PG8_SA(b, h) + aoff + m * 2048 + k * 1024); } while (0)
; #define PG8_LDB(dst, b, h) do { _Pragma("unroll") for (int n = 0; n < 2; ++n) _Pragma("unroll") for (int k = 0; k < 2; ++k) dst[n][k] = *(const PG8_LAS bf16x8*)(lds + PG8_SB(b, h) + boff + n * 2048 + k * 1024); } while (0)
; #define PG8_WAIT_V(n) asm volatile("s_waitcnt vmcnt(" #n ")" ::: "memory")
; #define PG8_WAIT_L(n) asm volatile("s_waitcnt lgkmcnt(" #n ")" ::: "memory")
; #define PG8_BAR __builtin_amdgcn_s_barrier()
; #define PG8_SCHED __builtin_amdgcn_sched_barrier(0)
;     ...
;             if constexpr (SP2) {
;             PG8_LDB(B0, 0, 0); PG8_LDB(B1, 0, 1); PG8_SCHED; PG8_LDA(At, 0, 0); PG8_STAGEA(PG8_SA(1, 1), a1 + hstep, voffA);
;             PG8_WAIT_V(8); PG8_WAIT_L(0); PG8_BAR; PG8_MMA(0, 0, At, B0); PG8_MMA(0, 1, At, B1); PG8_BAR; PG8_SCHED;
;             PG8_LDA(At, 0, 1); PG8_STAGE(PG8_SB(0, 0), b2, voffB); PG8_STAGE(PG8_SB(0, 1), b2 + hstepB, voffB); PG8_STAGEA(PG8_SA(0, 0), a2, voffA);
;             PG8_WAIT_V(8); PG8_WAIT_L(0); PG8_BAR; PG8_MMA(1, 0, At, B0); PG8_MMA(1, 1, At, B1); PG8_BAR; PG8_SCHED;
;             PG8_LDB(B0, 1, 0); PG8_LDB(B1, 1, 1); PG8_SCHED; PG8_LDA(At, 1, 0); PG8_STAGEA(PG8_SA(0, 1), a2 + hstep, voffA);
;             PG8_WAIT_V(8); PG8_WAIT_L(0); PG8_BAR; PG8_MMA(0, 0, At, B0); PG8_MMA(0, 1, At, B1); PG8_BAR; PG8_SCHED;
;             PG8_LDA(At, 1, 1); PG8_STAGE(PG8_SB(1, 0), b3, voffB); PG8_STAGE(PG8_SB(1, 1), b3 + hstepB, voffB); PG8_STAGEA(PG8_SA(1, 0), a3, voffA);
;             PG8_WAIT_V(8); PG8_WAIT_L(0); PG8_BAR; PG8_MMA(1, 0, At, B0); PG8_MMA(1, 1, At, B1); PG8_BAR; PG8_SCHED;
	s_add_i32 s73, 0, 0x18000
	s_add_i32 s74, 0, 0x1c000
	v_add_u32_e32 v156, s73, v169
	v_add_u32_e32 v173, s74, v169
	ds_read_b128 v[144:147], v156
	ds_read_b128 v[148:151], v156 offset:1024
	ds_read_b128 v[152:155], v156 offset:2048
	ds_read_b128 v[156:159], v156 offset:3072
	ds_read_b128 v[160:163], v173
	ds_read_b128 v[164:167], v173 offset:1024
	ds_read_b128 v[176:179], v173 offset:2048
	ds_read_b128 v[180:183], v173 offset:3072
	s_add_u32 s42, s42, 0x40000
	s_addc_u32 s43, s43, 0
	s_mov_b32 m0, s47
	v_lshl_add_u64 v[228:229], s[42:43], 0, v[134:135]
	ds_read_b128 v[184:187], v172 offset:32768
	ds_read_b128 v[188:191], v172 offset:33792
	ds_read_b128 v[192:195], v172 offset:34816
	ds_read_b128 v[196:199], v172 offset:35840
	ds_read_b128 v[202:205], v172 offset:36864
	ds_read_b128 v[210:213], v172 offset:37888
	ds_read_b128 v[214:217], v172 offset:38912
	ds_read_b128 v[218:221], v172 offset:39936
	global_load_lds_dwordx4 v[228:229], off
	v_lshl_add_u64 v[228:229], s[42:43], 0, v[130:131]
	s_mov_b32 m0, s50
	s_nop 0
	global_load_lds_dwordx4 v[228:229], off
	s_mov_b32 s99, 0
	s_waitcnt vmcnt(8)
	s_waitcnt lgkmcnt(0)
	s_barrier
	v_mfma_f32_16x16x32_bf16 v[124:127], v[144:147], v[184:187], v[124:127]
	v_mfma_f32_16x16x32_bf16 v[120:123], v[152:155], v[184:187], v[120:123]
	v_mfma_f32_16x16x32_bf16 v[108:111], v[144:147], v[192:195], v[108:111]
	v_mfma_f32_16x16x32_bf16 v[104:107], v[152:155], v[192:195], v[104:107]
	v_mfma_f32_16x16x32_bf16 v[92:95], v[144:147], v[202:205], v[92:95]
	v_mfma_f32_16x16x32_bf16 v[88:91], v[152:155], v[202:205], v[88:91]
	v_mfma_f32_16x16x32_bf16 v[76:79], v[144:147], v[214:217], v[76:79]
	v_mfma_f32_16x16x32_bf16 v[72:75], v[152:155], v[214:217], v[72:75]
	v_mfma_f32_16x16x32_bf16 v[124:127], v[148:151], v[188:191], v[124:127]
	v_mfma_f32_16x16x32_bf16 v[120:123], v[156:159], v[188:191], v[120:123]
	v_mfma_f32_16x16x32_bf16 v[108:111], v[148:151], v[196:199], v[108:111]
	v_mfma_f32_16x16x32_bf16 v[104:107], v[156:159], v[196:199], v[104:107]
	v_mfma_f32_16x16x32_bf16 v[92:95], v[148:151], v[210:213], v[92:95]
	v_mfma_f32_16x16x32_bf16 v[88:91], v[156:159], v[210:213], v[88:91]
	v_mfma_f32_16x16x32_bf16 v[76:79], v[148:151], v[218:221], v[76:79]
	v_mfma_f32_16x16x32_bf16 v[72:75], v[156:159], v[218:221], v[72:75]
	v_mfma_f32_16x16x32_bf16 v[116:119], v[160:163], v[184:187], v[116:119]
	v_mfma_f32_16x16x32_bf16 v[112:115], v[176:179], v[184:187], v[112:115]
	v_mfma_f32_16x16x32_bf16 v[100:103], v[160:163], v[192:195], v[100:103]
	v_mfma_f32_16x16x32_bf16 v[96:99], v[176:179], v[192:195], v[96:99]
	v_mfma_f32_16x16x32_bf16 v[84:87], v[160:163], v[202:205], v[84:87]
	v_mfma_f32_16x16x32_bf16 v[80:83], v[176:179], v[202:205], v[80:83]
	v_mfma_f32_16x16x32_bf16 v[68:71], v[160:163], v[214:217], v[68:71]
	v_mfma_f32_16x16x32_bf16 v[64:67], v[176:179], v[214:217], v[64:67]
	v_mfma_f32_16x16x32_bf16 v[116:119], v[164:167], v[188:191], v[116:119]
	v_mfma_f32_16x16x32_bf16 v[112:115], v[180:183], v[188:191], v[112:115]
	v_mfma_f32_16x16x32_bf16 v[100:103], v[164:167], v[196:199], v[100:103]
	v_mfma_f32_16x16x32_bf16 v[96:99], v[180:183], v[196:199], v[96:99]
	v_mfma_f32_16x16x32_bf16 v[84:87], v[164:167], v[210:213], v[84:87]
	v_mfma_f32_16x16x32_bf16 v[80:83], v[180:183], v[210:213], v[80:83]
	v_mfma_f32_16x16x32_bf16 v[68:71], v[164:167], v[218:221], v[68:71]
	v_mfma_f32_16x16x32_bf16 v[64:67], v[180:183], v[218:221], v[64:67]
	s_barrier
; #define PG8_STAGE(bufoff, gbase, voff) do { _Pragma("unroll") for (int _i = 0; _i < 2; ++_i) \
;         __builtin_amdgcn_global_load_lds((const unsigned*)((const char*)(gbase) + (voff)[_i]), (PG8_LAS unsigned*)(lds + (bufoff) + ldsw + _i * 8192), 16, 0, 0); } while (0)
; #define PG8_STAGEA(bufoff, gbase, voff) do { _Pragma("unroll") for (int _i = 0; _i < 2; ++_i) \
;         __builtin_amdgcn_global_load_lds((const unsigned*)((const char*)(gbase) + (voff)[_i]), (PG8_LAS unsigned*)(lds + (bufoff) + ldsw + _i * 8192), 16, 0, AUXA); } while (0)
; #define PG8_LDA(dst, b, h) do { _Pragma("unroll") for (int m = 0; m < 4; ++m) _Pragma("unroll") for (int k = 0; k < 2; ++k) dst[m][k] = *(const PG8_LAS bf16x8*)(lds + PG8_SA(b, h) + aoff + m * 2048 + k * 1024); } while (0)
; #define PG8_LDB(dst, b, h) do { _Pragma("unroll") for (int n = 0; n < 2; ++n) _Pragma("unroll") for (int k = 0; k < 2; ++k) dst[n][k] = *(const PG8_LAS bf16x8*)(lds + PG8_SB(b, h) + boff + n * 2048 + k * 1024); } while (0)
; #define PG8_WAIT_V(n) asm volatile("s_waitcnt vmcnt(" #n ")" ::: "memory")
; #define PG8_WAIT_L(n) asm volatile("s_waitcnt lgkmcnt(" #n ")" ::: "memory")
; #define PG8_BAR __builtin_amdgcn_s_barrier()
; #define PG8_SCHED __builtin_amdgcn_sched_barrier(0)
;     ...
;             if constexpr (SP2) {
;             PG8_LDB(B0, 0, 0); PG8_LDB(B1, 0, 1); PG8_SCHED; PG8_LDA(At, 0, 0); PG8_STAGEA(PG8_SA(1, 1), a1 + hstep, voffA);
;             PG8_WAIT_V(8); PG8_WAIT_L(0); PG8_BAR; PG8_MMA(0, 0, At, B0); PG8_MMA(0, 1, At, B1); PG8_BAR; PG8_SCHED;
;             PG8_LDA(At, 0, 1); PG8_STAGE(PG8_SB(0, 0), b2, voffB); PG8_STAGE(PG8_SB(0, 1), b2 + hstepB, voffB); PG8_STAGEA(PG8_SA(0, 0), a2, voffA);
;             PG8_WAIT_V(8); PG8_WAIT_L(0); PG8_BAR; PG8_MMA(1, 0, At, B0); PG8_MMA(1, 1, At, B1); PG8_BAR; PG8_SCHED;
;             PG8_LDB(B0, 1, 0); PG8_LDB(B1, 1, 1); PG8_SCHED; PG8_LDA(At, 1, 0); PG8_STAGEA(PG8_SA(0, 1), a2 + hstep, voffA);
;             PG8_WAIT_V(8); PG8_WAIT_L(0); PG8_BAR; PG8_MMA(0, 0, At, B0); PG8_MMA(0, 1, At, B1); PG8_BAR; PG8_SCHED;
;             PG8_LDA(At, 1, 1); PG8_STAGE(PG8_SB(1, 0), b3, voffB); PG8_STAGE(PG8_SB(1, 1), b3 + hstepB, voffB); PG8_STAGEA(PG8_SA(1, 0), a3, voffA);
;             PG8_WAIT_V(8); PG8_WAIT_L(0); PG8_BAR; PG8_MMA(1, 0, At, B0); PG8_MMA(1, 1, At, B1); PG8_BAR; PG8_SCHED;
;     ...
;         if constexpr (ALIGN_EPI) { if (wr == 0) PG8_BAR; }
	s_add_i32 s42, s73, s67
	v_lshl_add_u64 v[206:207], v[206:207], 0, s[16:17]
	s_mov_b32 m0, s42
	ds_read_b128 v[184:187], v172 offset:49152
	ds_read_b128 v[188:191], v172 offset:50176
	ds_read_b128 v[192:195], v172 offset:51200
	ds_read_b128 v[196:199], v172 offset:52224
	ds_read_b128 v[202:205], v172 offset:53248
	ds_read_b128 v[210:213], v172 offset:54272
	ds_read_b128 v[214:217], v172 offset:55296
	ds_read_b128 v[218:221], v172 offset:56320
	global_load_lds_dwordx4 v[206:207], off
	s_add_i32 m0, s42, 0x2000
	s_add_u32 s40, s40, 0x10080
	v_lshl_add_u64 v[206:207], v[222:223], 0, s[16:17]
	s_addc_u32 s41, s41, 0
	s_add_i32 s42, s74, s67
	global_load_lds_dwordx4 v[206:207], off
	v_lshl_add_u64 v[206:207], s[40:41], 0, v[132:133]
	s_mov_b32 m0, s42
	s_nop 0
	global_load_lds_dwordx4 v[206:207], off
	v_lshl_add_u64 v[206:207], s[40:41], 0, v[128:129]
	s_add_i32 m0, s42, 0x2000
	s_nop 0
	global_load_lds_dwordx4 v[206:207], off
	v_lshl_add_u64 v[206:207], v[224:225], 0, s[16:17]
	s_mov_b32 m0, s51
	s_nop 0
	global_load_lds_dwordx4 v[206:207], off
	v_lshl_add_u64 v[206:207], v[226:227], 0, s[16:17]
	s_mov_b32 m0, s52
	s_nop 0
	global_load_lds_dwordx4 v[206:207], off
	s_waitcnt vmcnt(8)
	s_waitcnt lgkmcnt(0)
	s_barrier
	v_mfma_f32_16x16x32_bf16 v[60:63], v[144:147], v[184:187], v[60:63]
	v_mfma_f32_16x16x32_bf16 v[56:59], v[152:155], v[184:187], v[56:59]
	v_mfma_f32_16x16x32_bf16 v[44:47], v[144:147], v[192:195], v[44:47]
	v_mfma_f32_16x16x32_bf16 v[40:43], v[152:155], v[192:195], v[40:43]
	v_mfma_f32_16x16x32_bf16 v[28:31], v[144:147], v[202:205], v[28:31]
	v_mfma_f32_16x16x32_bf16 v[24:27], v[152:155], v[202:205], v[24:27]
	v_mfma_f32_16x16x32_bf16 v[12:15], v[144:147], v[214:217], v[12:15]
	v_mfma_f32_16x16x32_bf16 v[8:11], v[152:155], v[214:217], v[8:11]
	v_mfma_f32_16x16x32_bf16 v[60:63], v[148:151], v[188:191], v[60:63]
	v_mfma_f32_16x16x32_bf16 v[56:59], v[156:159], v[188:191], v[56:59]
	v_mfma_f32_16x16x32_bf16 v[44:47], v[148:151], v[196:199], v[44:47]
	v_mfma_f32_16x16x32_bf16 v[40:43], v[156:159], v[196:199], v[40:43]
	v_mfma_f32_16x16x32_bf16 v[28:31], v[148:151], v[210:213], v[28:31]
	v_mfma_f32_16x16x32_bf16 v[24:27], v[156:159], v[210:213], v[24:27]
	v_mfma_f32_16x16x32_bf16 v[12:15], v[148:151], v[218:221], v[12:15]
	v_mfma_f32_16x16x32_bf16 v[8:11], v[156:159], v[218:221], v[8:11]
	v_mfma_f32_16x16x32_bf16 v[52:55], v[160:163], v[184:187], v[52:55]
	v_mfma_f32_16x16x32_bf16 v[48:51], v[176:179], v[184:187], v[48:51]
	v_mfma_f32_16x16x32_bf16 v[36:39], v[160:163], v[192:195], v[36:39]
	v_mfma_f32_16x16x32_bf16 v[32:35], v[176:179], v[192:195], v[32:35]
	v_mfma_f32_16x16x32_bf16 v[20:23], v[160:163], v[202:205], v[20:23]
	v_mfma_f32_16x16x32_bf16 v[16:19], v[176:179], v[202:205], v[16:19]
	v_mfma_f32_16x16x32_bf16 v[4:7], v[160:163], v[214:217], v[4:7]
	v_mfma_f32_16x16x32_bf16 v[0:3], v[176:179], v[214:217], v[0:3]
	v_mfma_f32_16x16x32_bf16 v[52:55], v[164:167], v[188:191], v[52:55]
	v_mfma_f32_16x16x32_bf16 v[48:51], v[180:183], v[188:191], v[48:51]
	v_mfma_f32_16x16x32_bf16 v[36:39], v[164:167], v[196:199], v[36:39]
	v_mfma_f32_16x16x32_bf16 v[32:35], v[180:183], v[196:199], v[32:35]
	v_mfma_f32_16x16x32_bf16 v[20:23], v[164:167], v[210:213], v[20:23]
	v_mfma_f32_16x16x32_bf16 v[16:19], v[180:183], v[210:213], v[16:19]
	v_mfma_f32_16x16x32_bf16 v[4:7], v[164:167], v[218:221], v[4:7]
	v_mfma_f32_16x16x32_bf16 v[0:3], v[180:183], v[218:221], v[0:3]
	s_barrier
	s_add_i32 s71, s71, 2
	s_add_u32 s38, s38, 0x100
	s_addc_u32 s39, s39, 0
	s_add_u32 s59, s59, 0x100
	s_addc_u32 s70, s70, 0
	s_cmp_gt_u32 s71, 13
	s_cbranch_scc0 .LBB0_977
	s_setprio 0
	s_and_b64 vcc, exec, s[18:19]
	s_cbranch_vccz .LBB0_980
	s_barrier

; #define PG8_STAGE(bufoff, gbase, voff) do { _Pragma("unroll") for (int _i = 0; _i < 2; ++_i) \
;         __builtin_amdgcn_global_load_lds((const unsigned*)((const char*)(gbase) + (voff)[_i]), (PG8_LAS unsigned*)(lds + (bufoff) + ldsw + _i * 8192), 16, 0, 0); } while (0)
; #define PG8_STAGEA(bufoff, gbase, voff) do { _Pragma("unroll") for (int _i = 0; _i < 2; ++_i) \
;         __builtin_amdgcn_global_load_lds((const unsigned*)((const char*)(gbase) + (voff)[_i]), (PG8_LAS unsigned*)(lds + (bufoff) + ldsw + _i * 8192), 16, 0, AUXA); } while (0)
; #define PG8_LDA(dst, b, h) do { _Pragma("unroll") for (int m = 0; m < 4; ++m) _Pragma("unroll") for (int k = 0; k < 2; ++k) dst[m][k] = *(const PG8_LAS bf16x8*)(lds + PG8_SA(b, h) + aoff + m * 2048 + k * 1024); } while (0)
; #define PG8_LDB(dst, b, h) do { _Pragma("unroll") for (int n = 0; n < 2; ++n) _Pragma("unroll") for (int k = 0; k < 2; ++k) dst[n][k] = *(const PG8_LAS bf16x8*)(lds + PG8_SB(b, h) + boff + n * 2048 + k * 1024); } while (0)
; #define PG8_WAIT_V(n) asm volatile("s_waitcnt vmcnt(" #n ")" ::: "memory")
; #define PG8_WAIT_L(n) asm volatile("s_waitcnt lgkmcnt(" #n ")" ::: "memory")
; #define PG8_BAR __builtin_amdgcn_s_barrier()
; #define PG8_SCHED __builtin_amdgcn_sched_barrier(0)
;     ...
;             if constexpr (SP2) {
;             PG8_LDB(B0, 0, 0); PG8_LDB(B1, 0, 1); PG8_SCHED; PG8_LDA(At, 0, 0); PG8_STAGEA(PG8_SA(1, 1), a1 + hstep, voffA);
;             PG8_WAIT_V(8); PG8_WAIT_L(0); PG8_BAR; PG8_MMA(0, 0, At, B0); PG8_MMA(0, 1, At, B1); PG8_BAR; PG8_SCHED;
;             PG8_LDA(At, 0, 1); PG8_STAGE(PG8_SB(0, 0), b2, voffB); PG8_STAGE(PG8_SB(0, 1), b2 + hstepB, voffB); PG8_STAGEA(PG8_SA(0, 0), a2, voffA);
;             PG8_WAIT_V(8); PG8_WAIT_L(0); PG8_BAR; PG8_MMA(1, 0, At, B0); PG8_MMA(1, 1, At, B1); PG8_BAR; PG8_SCHED;
;             PG8_LDB(B0, 1, 0); PG8_LDB(B1, 1, 1); PG8_SCHED; PG8_LDA(At, 1, 0); PG8_STAGEA(PG8_SA(0, 1), a2 + hstep, voffA);
;             PG8_WAIT_V(8); PG8_WAIT_L(0); PG8_BAR; PG8_MMA(0, 0, At, B0); PG8_MMA(0, 1, At, B1); PG8_BAR; PG8_SCHED;
;             PG8_LDA(At, 1, 1); PG8_STAGE(PG8_SB(1, 0), b3, voffB); PG8_STAGE(PG8_SB(1, 1), b3 + hstepB, voffB); PG8_STAGEA(PG8_SA(1, 0), a3, voffA);
;             PG8_WAIT_V(8); PG8_WAIT_L(0); PG8_BAR; PG8_MMA(1, 0, At, B0); PG8_MMA(1, 1, At, B1); PG8_BAR; PG8_SCHED;
.Lsp7_back:
	v_lshl_add_u64 v[206:207], s[38:39], 0, v[150:151]
	s_add_i32 m0, s49, 0xc000
	ds_read_b128 v[202:205], v164
	ds_read_b128 v[210:213], v164 offset:1024
	ds_read_b128 v[214:217], v164 offset:2048
	ds_read_b128 v[218:221], v164 offset:3072
	ds_read_b128 v[222:225], v164 offset:4096
	ds_read_b128 v[226:229], v164 offset:5120
	ds_read_b128 v[230:233], v164 offset:6144
	ds_read_b128 v[234:237], v164 offset:7168
	global_load_lds_dwordx4 v[206:207], off
	v_lshl_add_u64 v[206:207], s[38:39], 0, v[130:131]
	s_add_i32 m0, s49, 0xe000
	s_nop 0
	global_load_lds_dwordx4 v[206:207], off
	s_waitcnt vmcnt(8)
	s_waitcnt lgkmcnt(0)
	s_barrier
	v_mfma_f32_16x16x32_bf16 v[124:127], v[166:169], v[202:205], v[124:127]
	v_mfma_f32_16x16x32_bf16 v[120:123], v[176:179], v[202:205], v[120:123]
	v_mfma_f32_16x16x32_bf16 v[108:111], v[166:169], v[214:217], v[108:111]
	v_mfma_f32_16x16x32_bf16 v[104:107], v[176:179], v[214:217], v[104:107]
	v_mfma_f32_16x16x32_bf16 v[92:95], v[166:169], v[222:225], v[92:95]
	v_mfma_f32_16x16x32_bf16 v[88:91], v[176:179], v[222:225], v[88:91]
	v_mfma_f32_16x16x32_bf16 v[76:79], v[166:169], v[230:233], v[76:79]
	v_mfma_f32_16x16x32_bf16 v[72:75], v[176:179], v[230:233], v[72:75]
	v_mfma_f32_16x16x32_bf16 v[124:127], v[170:173], v[210:213], v[124:127]
	v_mfma_f32_16x16x32_bf16 v[120:123], v[180:183], v[210:213], v[120:123]
	v_mfma_f32_16x16x32_bf16 v[108:111], v[170:173], v[218:221], v[108:111]
	v_mfma_f32_16x16x32_bf16 v[104:107], v[180:183], v[218:221], v[104:107]
	v_mfma_f32_16x16x32_bf16 v[92:95], v[170:173], v[226:229], v[92:95]
	v_mfma_f32_16x16x32_bf16 v[88:91], v[180:183], v[226:229], v[88:91]
	v_mfma_f32_16x16x32_bf16 v[76:79], v[170:173], v[234:237], v[76:79]
	v_mfma_f32_16x16x32_bf16 v[72:75], v[180:183], v[234:237], v[72:75]
	v_mfma_f32_16x16x32_bf16 v[116:119], v[184:187], v[202:205], v[116:119]
	v_mfma_f32_16x16x32_bf16 v[112:115], v[192:195], v[202:205], v[112:115]
	v_mfma_f32_16x16x32_bf16 v[100:103], v[184:187], v[214:217], v[100:103]
	v_mfma_f32_16x16x32_bf16 v[96:99], v[192:195], v[214:217], v[96:99]
	v_mfma_f32_16x16x32_bf16 v[84:87], v[184:187], v[222:225], v[84:87]
	v_mfma_f32_16x16x32_bf16 v[80:83], v[192:195], v[222:225], v[80:83]
	v_mfma_f32_16x16x32_bf16 v[68:71], v[184:187], v[230:233], v[68:71]
	v_mfma_f32_16x16x32_bf16 v[64:67], v[192:195], v[230:233], v[64:67]
	v_mfma_f32_16x16x32_bf16 v[116:119], v[188:191], v[210:213], v[116:119]
	v_mfma_f32_16x16x32_bf16 v[112:115], v[196:199], v[210:213], v[112:115]
	v_mfma_f32_16x16x32_bf16 v[100:103], v[188:191], v[218:221], v[100:103]
	v_mfma_f32_16x16x32_bf16 v[96:99], v[196:199], v[218:221], v[96:99]
	v_mfma_f32_16x16x32_bf16 v[84:87], v[188:191], v[226:229], v[84:87]
	v_mfma_f32_16x16x32_bf16 v[80:83], v[196:199], v[226:229], v[80:83]
	v_mfma_f32_16x16x32_bf16 v[68:71], v[188:191], v[234:237], v[68:71]
	v_mfma_f32_16x16x32_bf16 v[64:67], v[196:199], v[234:237], v[64:67]
	s_barrier
	s_add_i32 s74, s59, s67
	v_lshl_add_u64 v[206:207], s[44:45], 0, v[136:137]
	s_mov_b32 m0, s74
	ds_read_b128 v[202:205], v164 offset:16384
	ds_read_b128 v[210:213], v164 offset:17408
	ds_read_b128 v[214:217], v164 offset:18432
	ds_read_b128 v[218:221], v164 offset:19456
	ds_read_b128 v[222:225], v164 offset:20480
	ds_read_b128 v[226:229], v164 offset:21504
	ds_read_b128 v[230:233], v164 offset:22528
	ds_read_b128 v[234:237], v164 offset:23552
	global_load_lds_dwordx4 v[206:207], off
	s_add_i32 m0, s74, 0x2000
	s_add_u32 s74, s44, 0x40000
	v_lshl_add_u64 v[238:239], s[44:45], 0, v[140:141]
	s_addc_u32 s75, s45, 0
	s_add_i32 s76, s70, s67
	global_load_lds_dwordx4 v[238:239], off
	v_lshl_add_u64 v[240:241], s[74:75], 0, v[136:137]
	s_mov_b32 m0, s76
	v_lshl_add_u64 v[242:243], s[50:51], 0, v[138:139]
	global_load_lds_dwordx4 v[240:241], off
	v_lshl_add_u64 v[240:241], s[74:75], 0, v[140:141]
	s_add_i32 m0, s76, 0x2000
	s_nop 0
	global_load_lds_dwordx4 v[240:241], off
	v_lshl_add_u64 v[240:241], s[50:51], 0, v[134:135]
	s_mov_b32 m0, s49
	s_nop 0
	global_load_lds_dwordx4 v[240:241], off
	s_mov_b32 m0, s52
	s_nop 0
	global_load_lds_dwordx4 v[242:243], off
	s_waitcnt vmcnt(8)
	s_waitcnt lgkmcnt(0)
	s_barrier
	v_mfma_f32_16x16x32_bf16 v[60:63], v[166:169], v[202:205], v[60:63]
	v_mfma_f32_16x16x32_bf16 v[56:59], v[176:179], v[202:205], v[56:59]
	v_mfma_f32_16x16x32_bf16 v[44:47], v[166:169], v[214:217], v[44:47]
	v_mfma_f32_16x16x32_bf16 v[40:43], v[176:179], v[214:217], v[40:43]
	v_mfma_f32_16x16x32_bf16 v[28:31], v[166:169], v[222:225], v[28:31]
	v_mfma_f32_16x16x32_bf16 v[24:27], v[176:179], v[222:225], v[24:27]
	v_mfma_f32_16x16x32_bf16 v[12:15], v[166:169], v[230:233], v[12:15]
	v_mfma_f32_16x16x32_bf16 v[8:11], v[176:179], v[230:233], v[8:11]
	v_mfma_f32_16x16x32_bf16 v[60:63], v[170:173], v[210:213], v[60:63]
	v_mfma_f32_16x16x32_bf16 v[56:59], v[180:183], v[210:213], v[56:59]
	v_mfma_f32_16x16x32_bf16 v[44:47], v[170:173], v[218:221], v[44:47]
	v_mfma_f32_16x16x32_bf16 v[40:43], v[180:183], v[218:221], v[40:43]
	v_mfma_f32_16x16x32_bf16 v[28:31], v[170:173], v[226:229], v[28:31]
	v_mfma_f32_16x16x32_bf16 v[24:27], v[180:183], v[226:229], v[24:27]
	v_mfma_f32_16x16x32_bf16 v[12:15], v[170:173], v[234:237], v[12:15]
	v_mfma_f32_16x16x32_bf16 v[8:11], v[180:183], v[234:237], v[8:11]
	v_mfma_f32_16x16x32_bf16 v[52:55], v[184:187], v[202:205], v[52:55]
	v_mfma_f32_16x16x32_bf16 v[48:51], v[192:195], v[202:205], v[48:51]
	v_mfma_f32_16x16x32_bf16 v[36:39], v[184:187], v[214:217], v[36:39]
	v_mfma_f32_16x16x32_bf16 v[32:35], v[192:195], v[214:217], v[32:35]
	v_mfma_f32_16x16x32_bf16 v[20:23], v[184:187], v[222:225], v[20:23]
	v_mfma_f32_16x16x32_bf16 v[16:19], v[192:195], v[222:225], v[16:19]
	v_mfma_f32_16x16x32_bf16 v[4:7], v[184:187], v[230:233], v[4:7]
	v_mfma_f32_16x16x32_bf16 v[0:3], v[192:195], v[230:233], v[0:3]
	v_mfma_f32_16x16x32_bf16 v[52:55], v[188:191], v[210:213], v[52:55]
	v_mfma_f32_16x16x32_bf16 v[48:51], v[196:199], v[210:213], v[48:51]
	v_mfma_f32_16x16x32_bf16 v[36:39], v[188:191], v[218:221], v[36:39]
	v_mfma_f32_16x16x32_bf16 v[32:35], v[196:199], v[218:221], v[32:35]
	v_mfma_f32_16x16x32_bf16 v[20:23], v[188:191], v[226:229], v[20:23]
	v_mfma_f32_16x16x32_bf16 v[16:19], v[196:199], v[226:229], v[16:19]
	v_mfma_f32_16x16x32_bf16 v[4:7], v[188:191], v[234:237], v[4:7]
	v_mfma_f32_16x16x32_bf16 v[0:3], v[196:199], v[234:237], v[0:3]
	s_barrier
; #define PG8_STAGE(bufoff, gbase, voff) do { _Pragma("unroll") for (int _i = 0; _i < 2; ++_i) \
;         __builtin_amdgcn_global_load_lds((const unsigned*)((const char*)(gbase) + (voff)[_i]), (PG8_LAS unsigned*)(lds + (bufoff) + ldsw + _i * 8192), 16, 0, 0); } while (0)
; #define PG8_STAGEA(bufoff, gbase, voff) do { _Pragma("unroll") for (int _i = 0; _i < 2; ++_i) \
;         __builtin_amdgcn_global_load_lds((const unsigned*)((const char*)(gbase) + (voff)[_i]), (PG8_LAS unsigned*)(lds + (bufoff) + ldsw + _i * 8192), 16, 0, AUXA); } while (0)
; #define PG8_LDA(dst, b, h) do { _Pragma("unroll") for (int m = 0; m < 4; ++m) _Pragma("unroll") for (int k = 0; k < 2; ++k) dst[m][k] = *(const PG8_LAS bf16x8*)(lds + PG8_SA(b, h) + aoff + m * 2048 + k * 1024); } while (0)
; #define PG8_LDB(dst, b, h) do { _Pragma("unroll") for (int n = 0; n < 2; ++n) _Pragma("unroll") for (int k = 0; k < 2; ++k) dst[n][k] = *(const PG8_LAS bf16x8*)(lds + PG8_SB(b, h) + boff + n * 2048 + k * 1024); } while (0)
; #define PG8_WAIT_V(n) asm volatile("s_waitcnt vmcnt(" #n ")" ::: "memory")
; #define PG8_WAIT_L(n) asm volatile("s_waitcnt lgkmcnt(" #n ")" ::: "memory")
; #define PG8_BAR __builtin_amdgcn_s_barrier()
; #define PG8_SCHED __builtin_amdgcn_sched_barrier(0)
;     ...
;             if constexpr (SP2) {
;             PG8_LDB(B0, 0, 0); PG8_LDB(B1, 0, 1); PG8_SCHED; PG8_LDA(At, 0, 0); PG8_STAGEA(PG8_SA(1, 1), a1 + hstep, voffA);
;             PG8_WAIT_V(8); PG8_WAIT_L(0); PG8_BAR; PG8_MMA(0, 0, At, B0); PG8_MMA(0, 1, At, B1); PG8_BAR; PG8_SCHED;
;             PG8_LDA(At, 0, 1); PG8_STAGE(PG8_SB(0, 0), b2, voffB); PG8_STAGE(PG8_SB(0, 1), b2 + hstepB, voffB); PG8_STAGEA(PG8_SA(0, 0), a2, voffA);
;             PG8_WAIT_V(8); PG8_WAIT_L(0); PG8_BAR; PG8_MMA(1, 0, At, B0); PG8_MMA(1, 1, At, B1); PG8_BAR; PG8_SCHED;
;             PG8_LDB(B0, 1, 0); PG8_LDB(B1, 1, 1); PG8_SCHED; PG8_LDA(At, 1, 0); PG8_STAGEA(PG8_SA(0, 1), a2 + hstep, voffA);
;             PG8_WAIT_V(8); PG8_WAIT_L(0); PG8_BAR; PG8_MMA(0, 0, At, B0); PG8_MMA(0, 1, At, B1); PG8_BAR; PG8_SCHED;
;             PG8_LDA(At, 1, 1); PG8_STAGE(PG8_SB(1, 0), b3, voffB); PG8_STAGE(PG8_SB(1, 1), b3 + hstepB, voffB); PG8_STAGEA(PG8_SA(1, 0), a3, voffA);
;             PG8_WAIT_V(8); PG8_WAIT_L(0); PG8_BAR; PG8_MMA(1, 0, At, B0); PG8_MMA(1, 1, At, B1); PG8_BAR; PG8_SCHED;
	s_add_i32 s74, 0, 0x18000
	v_add_u32_e32 v128, s74, v163
	s_add_i32 s75, 0, 0x1c000
	ds_read_b128 v[166:169], v128
	ds_read_b128 v[170:173], v128 offset:1024
	ds_read_b128 v[176:179], v128 offset:2048
	ds_read_b128 v[180:183], v128 offset:3072
	v_add_u32_e32 v128, s75, v163
	ds_read_b128 v[184:187], v128
	ds_read_b128 v[188:191], v128 offset:1024
	ds_read_b128 v[192:195], v128 offset:2048
	ds_read_b128 v[196:199], v128 offset:3072
	s_add_u32 s50, s50, 0x100000
	s_addc_u32 s51, s51, 0
	s_mov_b32 m0, s53
	v_lshl_add_u64 v[244:245], s[50:51], 0, v[134:135]
	ds_read_b128 v[202:205], v164 offset:32768
	ds_read_b128 v[210:213], v164 offset:33792
	ds_read_b128 v[214:217], v164 offset:34816
	ds_read_b128 v[218:221], v164 offset:35840
	ds_read_b128 v[222:225], v164 offset:36864
	ds_read_b128 v[226:229], v164 offset:37888
	ds_read_b128 v[230:233], v164 offset:38912
	ds_read_b128 v[234:237], v164 offset:39936
	global_load_lds_dwordx4 v[244:245], off
	v_lshl_add_u64 v[244:245], s[50:51], 0, v[138:139]
	s_mov_b32 m0, s54
	s_nop 0
	global_load_lds_dwordx4 v[244:245], off
	s_waitcnt vmcnt(8)
	s_waitcnt lgkmcnt(0)
	s_barrier
	v_mfma_f32_16x16x32_bf16 v[124:127], v[166:169], v[202:205], v[124:127]
	v_mfma_f32_16x16x32_bf16 v[120:123], v[176:179], v[202:205], v[120:123]
	v_mfma_f32_16x16x32_bf16 v[108:111], v[166:169], v[214:217], v[108:111]
	v_mfma_f32_16x16x32_bf16 v[104:107], v[176:179], v[214:217], v[104:107]
	v_mfma_f32_16x16x32_bf16 v[92:95], v[166:169], v[222:225], v[92:95]
	v_mfma_f32_16x16x32_bf16 v[88:91], v[176:179], v[222:225], v[88:91]
	v_mfma_f32_16x16x32_bf16 v[76:79], v[166:169], v[230:233], v[76:79]
	v_mfma_f32_16x16x32_bf16 v[72:75], v[176:179], v[230:233], v[72:75]
	v_mfma_f32_16x16x32_bf16 v[124:127], v[170:173], v[210:213], v[124:127]
	v_mfma_f32_16x16x32_bf16 v[120:123], v[180:183], v[210:213], v[120:123]
	v_mfma_f32_16x16x32_bf16 v[108:111], v[170:173], v[218:221], v[108:111]
	v_mfma_f32_16x16x32_bf16 v[104:107], v[180:183], v[218:221], v[104:107]
	v_mfma_f32_16x16x32_bf16 v[92:95], v[170:173], v[226:229], v[92:95]
	v_mfma_f32_16x16x32_bf16 v[88:91], v[180:183], v[226:229], v[88:91]
	v_mfma_f32_16x16x32_bf16 v[76:79], v[170:173], v[234:237], v[76:79]
	v_mfma_f32_16x16x32_bf16 v[72:75], v[180:183], v[234:237], v[72:75]
	v_mfma_f32_16x16x32_bf16 v[116:119], v[184:187], v[202:205], v[116:119]
	v_mfma_f32_16x16x32_bf16 v[112:115], v[192:195], v[202:205], v[112:115]
	v_mfma_f32_16x16x32_bf16 v[100:103], v[184:187], v[214:217], v[100:103]
	v_mfma_f32_16x16x32_bf16 v[96:99], v[192:195], v[214:217], v[96:99]
	v_mfma_f32_16x16x32_bf16 v[84:87], v[184:187], v[222:225], v[84:87]
	v_mfma_f32_16x16x32_bf16 v[80:83], v[192:195], v[222:225], v[80:83]
	v_mfma_f32_16x16x32_bf16 v[68:71], v[184:187], v[230:233], v[68:71]
	v_mfma_f32_16x16x32_bf16 v[64:67], v[192:195], v[230:233], v[64:67]
	v_mfma_f32_16x16x32_bf16 v[116:119], v[188:191], v[210:213], v[116:119]
	v_mfma_f32_16x16x32_bf16 v[112:115], v[196:199], v[210:213], v[112:115]
	v_mfma_f32_16x16x32_bf16 v[100:103], v[188:191], v[218:221], v[100:103]
	v_mfma_f32_16x16x32_bf16 v[96:99], v[196:199], v[218:221], v[96:99]
	v_mfma_f32_16x16x32_bf16 v[84:87], v[188:191], v[226:229], v[84:87]
	v_mfma_f32_16x16x32_bf16 v[80:83], v[196:199], v[226:229], v[80:83]
	v_mfma_f32_16x16x32_bf16 v[68:71], v[188:191], v[234:237], v[68:71]
	v_mfma_f32_16x16x32_bf16 v[64:67], v[196:199], v[234:237], v[64:67]
	s_barrier
; #define PG8_STAGE(bufoff, gbase, voff) do { _Pragma("unroll") for (int _i = 0; _i < 2; ++_i) \
;         __builtin_amdgcn_global_load_lds((const unsigned*)((const char*)(gbase) + (voff)[_i]), (PG8_LAS unsigned*)(lds + (bufoff) + ldsw + _i * 8192), 16, 0, 0); } while (0)
; #define PG8_STAGEA(bufoff, gbase, voff) do { _Pragma("unroll") for (int _i = 0; _i < 2; ++_i) \
;         __builtin_amdgcn_global_load_lds((const unsigned*)((const char*)(gbase) + (voff)[_i]), (PG8_LAS unsigned*)(lds + (bufoff) + ldsw + _i * 8192), 16, 0, AUXA); } while (0)
; #define PG8_LDA(dst, b, h) do { _Pragma("unroll") for (int m = 0; m < 4; ++m) _Pragma("unroll") for (int k = 0; k < 2; ++k) dst[m][k] = *(const PG8_LAS bf16x8*)(lds + PG8_SA(b, h) + aoff + m * 2048 + k * 1024); } while (0)
; #define PG8_LDB(dst, b, h) do { _Pragma("unroll") for (int n = 0; n < 2; ++n) _Pragma("unroll") for (int k = 0; k < 2; ++k) dst[n][k] = *(const PG8_LAS bf16x8*)(lds + PG8_SB(b, h) + boff + n * 2048 + k * 1024); } while (0)
; #define PG8_WAIT_V(n) asm volatile("s_waitcnt vmcnt(" #n ")" ::: "memory")
; #define PG8_WAIT_L(n) asm volatile("s_waitcnt lgkmcnt(" #n ")" ::: "memory")
; #define PG8_BAR __builtin_amdgcn_s_barrier()
; #define PG8_SCHED __builtin_amdgcn_sched_barrier(0)
;     ...
;             if constexpr (SP2) {
;             PG8_LDB(B0, 0, 0); PG8_LDB(B1, 0, 1); PG8_SCHED; PG8_LDA(At, 0, 0); PG8_STAGEA(PG8_SA(1, 1), a1 + hstep, voffA);
;             PG8_WAIT_V(8); PG8_WAIT_L(0); PG8_BAR; PG8_MMA(0, 0, At, B0); PG8_MMA(0, 1, At, B1); PG8_BAR; PG8_SCHED;
;             PG8_LDA(At, 0, 1); PG8_STAGE(PG8_SB(0, 0), b2, voffB); PG8_STAGE(PG8_SB(0, 1), b2 + hstepB, voffB); PG8_STAGEA(PG8_SA(0, 0), a2, voffA);
;             PG8_WAIT_V(8); PG8_WAIT_L(0); PG8_BAR; PG8_MMA(1, 0, At, B0); PG8_MMA(1, 1, At, B1); PG8_BAR; PG8_SCHED;
;             PG8_LDB(B0, 1, 0); PG8_LDB(B1, 1, 1); PG8_SCHED; PG8_LDA(At, 1, 0); PG8_STAGEA(PG8_SA(0, 1), a2 + hstep, voffA);
;             PG8_WAIT_V(8); PG8_WAIT_L(0); PG8_BAR; PG8_MMA(0, 0, At, B0); PG8_MMA(0, 1, At, B1); PG8_BAR; PG8_SCHED;
;             PG8_LDA(At, 1, 1); PG8_STAGE(PG8_SB(1, 0), b3, voffB); PG8_STAGE(PG8_SB(1, 1), b3 + hstepB, voffB); PG8_STAGEA(PG8_SA(1, 0), a3, voffA);
;             PG8_WAIT_V(8); PG8_WAIT_L(0); PG8_BAR; PG8_MMA(1, 0, At, B0); PG8_MMA(1, 1, At, B1); PG8_BAR; PG8_SCHED;
;     ...
;         if constexpr (ALIGN_EPI) { if (wr == 0) PG8_BAR; }
	s_add_i32 s50, s74, s67
	v_lshl_add_u64 v[206:207], v[206:207], 0, s[16:17]
	s_mov_b32 m0, s50
	ds_read_b128 v[202:205], v164 offset:49152
	ds_read_b128 v[210:213], v164 offset:50176
	ds_read_b128 v[214:217], v164 offset:51200
	ds_read_b128 v[218:221], v164 offset:52224
	ds_read_b128 v[222:225], v164 offset:53248
	ds_read_b128 v[226:229], v164 offset:54272
	ds_read_b128 v[230:233], v164 offset:55296
	ds_read_b128 v[234:237], v164 offset:56320
	global_load_lds_dwordx4 v[206:207], off
	s_add_i32 m0, s50, 0x2000
	s_add_u32 s44, s44, 0x40080
	v_lshl_add_u64 v[206:207], v[238:239], 0, s[16:17]
	s_addc_u32 s45, s45, 0
	s_add_i32 s50, s75, s67
	global_load_lds_dwordx4 v[206:207], off
	v_lshl_add_u64 v[206:207], s[44:45], 0, v[136:137]
	s_mov_b32 m0, s50
	s_nop 0
	global_load_lds_dwordx4 v[206:207], off
	v_lshl_add_u64 v[206:207], s[44:45], 0, v[140:141]
	s_add_i32 m0, s50, 0x2000
	s_nop 0
	global_load_lds_dwordx4 v[206:207], off
	v_lshl_add_u64 v[206:207], v[240:241], 0, s[16:17]
	s_mov_b32 m0, s55
	s_nop 0
	global_load_lds_dwordx4 v[206:207], off
	v_lshl_add_u64 v[206:207], v[242:243], 0, s[16:17]
	s_mov_b32 m0, s56
	s_nop 0
	global_load_lds_dwordx4 v[206:207], off
	s_waitcnt vmcnt(8)
	s_waitcnt lgkmcnt(0)
	s_barrier
	v_mfma_f32_16x16x32_bf16 v[60:63], v[166:169], v[202:205], v[60:63]
	v_mfma_f32_16x16x32_bf16 v[56:59], v[176:179], v[202:205], v[56:59]
	v_mfma_f32_16x16x32_bf16 v[44:47], v[166:169], v[214:217], v[44:47]
	v_mfma_f32_16x16x32_bf16 v[40:43], v[176:179], v[214:217], v[40:43]
	v_mfma_f32_16x16x32_bf16 v[28:31], v[166:169], v[222:225], v[28:31]
	v_mfma_f32_16x16x32_bf16 v[24:27], v[176:179], v[222:225], v[24:27]
	v_mfma_f32_16x16x32_bf16 v[12:15], v[166:169], v[230:233], v[12:15]
	v_mfma_f32_16x16x32_bf16 v[8:11], v[176:179], v[230:233], v[8:11]
	v_mfma_f32_16x16x32_bf16 v[60:63], v[170:173], v[210:213], v[60:63]
	v_mfma_f32_16x16x32_bf16 v[56:59], v[180:183], v[210:213], v[56:59]
	v_mfma_f32_16x16x32_bf16 v[44:47], v[170:173], v[218:221], v[44:47]
	v_mfma_f32_16x16x32_bf16 v[40:43], v[180:183], v[218:221], v[40:43]
	v_mfma_f32_16x16x32_bf16 v[28:31], v[170:173], v[226:229], v[28:31]
	v_mfma_f32_16x16x32_bf16 v[24:27], v[180:183], v[226:229], v[24:27]
	v_mfma_f32_16x16x32_bf16 v[12:15], v[170:173], v[234:237], v[12:15]
	v_mfma_f32_16x16x32_bf16 v[8:11], v[180:183], v[234:237], v[8:11]
	v_mfma_f32_16x16x32_bf16 v[52:55], v[184:187], v[202:205], v[52:55]
	v_mfma_f32_16x16x32_bf16 v[48:51], v[192:195], v[202:205], v[48:51]
	v_mfma_f32_16x16x32_bf16 v[36:39], v[184:187], v[214:217], v[36:39]
	v_mfma_f32_16x16x32_bf16 v[32:35], v[192:195], v[214:217], v[32:35]
	v_mfma_f32_16x16x32_bf16 v[20:23], v[184:187], v[222:225], v[20:23]
	v_mfma_f32_16x16x32_bf16 v[16:19], v[192:195], v[222:225], v[16:19]
	v_mfma_f32_16x16x32_bf16 v[4:7], v[184:187], v[230:233], v[4:7]
	v_mfma_f32_16x16x32_bf16 v[0:3], v[192:195], v[230:233], v[0:3]
	v_mfma_f32_16x16x32_bf16 v[52:55], v[188:191], v[210:213], v[52:55]
	v_mfma_f32_16x16x32_bf16 v[48:51], v[196:199], v[210:213], v[48:51]
	v_mfma_f32_16x16x32_bf16 v[36:39], v[188:191], v[218:221], v[36:39]
	v_mfma_f32_16x16x32_bf16 v[32:35], v[196:199], v[218:221], v[32:35]
	v_mfma_f32_16x16x32_bf16 v[20:23], v[188:191], v[226:229], v[20:23]
	v_mfma_f32_16x16x32_bf16 v[16:19], v[196:199], v[226:229], v[16:19]
	v_mfma_f32_16x16x32_bf16 v[4:7], v[188:191], v[234:237], v[4:7]
	v_mfma_f32_16x16x32_bf16 v[0:3], v[196:199], v[234:237], v[0:3]
	s_barrier
	s_add_i32 s44, s73, 2
	s_add_u32 s42, s42, 0x100
	s_addc_u32 s43, s43, 0
	v_lshl_add_u64 v[150:151], v[150:151], 0, s[20:21]
	v_lshl_add_u64 v[130:131], v[130:131], 0, s[20:21]
	s_cmp_ge_i32 s73, s57
	s_mov_b32 s73, s44
	s_cbranch_scc0 .LBB0_1054
	s_setprio 0
	s_and_b64 vcc, exec, s[18:19]
	s_cbranch_vccz .LBB0_1057
	s_barrier
